# v26
# speedup vs baseline: 1.0006x; 1.0006x over previous
; #define LDA(dst, b, h)                                                                                               \
;   _Pragma("unroll") for (int m = 0; m < 4; ++m) _Pragma("unroll") for (int k = 0; k < 2; ++k) dst[m][k] =            \
;       *reinterpret_cast<const bf16x8*>(SA(b, h) + lds_byte(wr * 64 + m * 16 + fr, k * 32 + fq * 8))
; #define LDB(dst, b, h)                                                                                               \
;   _Pragma("unroll") for (int n = 0; n < 2; ++n) _Pragma("unroll") for (int k = 0; k < 2; ++k) dst[n][k] =            \
;       *reinterpret_cast<const bf16x8*>(SB(b, h) + lds_byte(wc * 32 + n * 16 + fr, k * 32 + fq * 8))
; #define WAIT_V(n) asm volatile("s_waitcnt vmcnt(" #n ")" ::: "memory")
; #define WAIT_L(n) asm volatile("s_waitcnt lgkmcnt(" #n ")" ::: "memory")
; #define BAR __builtin_amdgcn_s_barrier()
; #define SCHED __builtin_amdgcn_sched_barrier(0)
; template <int EPI>
; __device__ __forceinline__ void gemm_phase(const u16* __restrict__ A, const u16* __restrict__ Bt, const int K,
;                                            const int nN, char* shm, const EpiArgs& ea) {
;     ...
;       LDB(B0, 0, 0); SCHED; LDA(At, 0, 0); STAGE(SA(1, 1), rA, brow + HALF, t + 1);
;       WAIT_V(10); WAIT_L(8); BAR; WAIT_L(0); MMA(0, 0, At, B0); BAR; SCHED;
;       LDB(B1, 0, 1); STAGE(SB(0, 0), rB, bcol, t + 2);
;       WAIT_V(10); BAR; WAIT_L(0); MMA(0, 1, At, B1); BAR;
;       LDA(At, 0, 1); STAGE(SA(0, 0), rA, brow, t + 2);
;       BAR; WAIT_L(0); MMA(1, 0, At, B0); BAR; SCHED;
;       STAGE(SB(0, 1), rB, bcol + HALF, t + 2);
;       WAIT_V(10); BAR; MMA(1, 1, At, B1); BAR;
;       LDB(B0, 1, 0); SCHED; LDA(At, 1, 0); STAGE(SA(0, 1), rA, brow + HALF, t + 2);
.LBB0_172:
	ds_read_b128 v[142:145], v133
	ds_read_b128 v[146:149], v133 offset:1024
	ds_read_b128 v[150:153], v133 offset:2048
	ds_read_b128 v[154:157], v133 offset:3072
	s_add_i32 s73, s67, s72
	s_mov_b32 m0, s57
	s_add_i32 s6, s73, 0x4000
	ds_read_b128 v[162:165], v134
	ds_read_b128 v[166:169], v134 offset:1024
	ds_read_b128 v[170:173], v135
	ds_read_b128 v[176:179], v135 offset:1024
	ds_read_b128 v[180:183], v136
	ds_read_b128 v[184:187], v136 offset:1024
	ds_read_b128 v[188:191], v137
	ds_read_b128 v[192:195], v137 offset:1024
	buffer_load_dwordx4 v130, s[0:3], s6 offen lds
	s_mov_b32 m0, s58
	s_add_i32 s6, s73, 0x6000
	buffer_load_dwordx4 v130, s[0:3], s6 offen lds
	s_waitcnt vmcnt(10)
	s_waitcnt lgkmcnt(8)
	s_barrier
	s_waitcnt lgkmcnt(0)
	v_mfma_f32_16x16x32_bf16 v[124:127], v[142:145], v[162:165], v[124:127]
	v_mfma_f32_16x16x32_bf16 v[120:123], v[150:153], v[162:165], v[120:123]
	v_mfma_f32_16x16x32_bf16 v[116:119], v[142:145], v[170:173], v[116:119]
	v_mfma_f32_16x16x32_bf16 v[112:115], v[150:153], v[170:173], v[112:115]
	v_mfma_f32_16x16x32_bf16 v[108:111], v[142:145], v[180:183], v[108:111]
	v_mfma_f32_16x16x32_bf16 v[104:107], v[150:153], v[180:183], v[104:107]
	v_mfma_f32_16x16x32_bf16 v[100:103], v[142:145], v[188:191], v[100:103]
	v_mfma_f32_16x16x32_bf16 v[96:99], v[150:153], v[188:191], v[96:99]
	v_mfma_f32_16x16x32_bf16 v[124:127], v[146:149], v[166:169], v[124:127]
	v_mfma_f32_16x16x32_bf16 v[120:123], v[154:157], v[166:169], v[120:123]
	v_mfma_f32_16x16x32_bf16 v[116:119], v[146:149], v[176:179], v[116:119]
	v_mfma_f32_16x16x32_bf16 v[112:115], v[154:157], v[176:179], v[112:115]
	v_mfma_f32_16x16x32_bf16 v[108:111], v[146:149], v[184:187], v[108:111]
	v_mfma_f32_16x16x32_bf16 v[104:107], v[154:157], v[184:187], v[104:107]
	v_mfma_f32_16x16x32_bf16 v[100:103], v[146:149], v[192:195], v[100:103]
	v_mfma_f32_16x16x32_bf16 v[96:99], v[154:157], v[192:195], v[96:99]
	s_barrier
	s_add_i32 s74, s70, s72
	s_mov_b32 m0, s34
	s_add_i32 s75, s74, 0x8000
	s_mov_b32 s6, s2
	s_mov_b32 s7, s3
	ds_read_b128 v[196:199], v138
	ds_read_b128 v[200:203], v138 offset:1024
	ds_read_b128 v[204:207], v138 offset:2048
	ds_read_b128 v[208:211], v138 offset:3072
	buffer_load_dwordx4 v130, s[4:7], s75 offen lds
	s_mov_b32 m0, s35
	s_add_i32 s75, s74, 0xa000
	buffer_load_dwordx4 v130, s[4:7], s75 offen lds
	s_waitcnt vmcnt(10)
	s_barrier
	s_waitcnt lgkmcnt(0)
	v_mfma_f32_16x16x32_bf16 v[92:95], v[196:199], v[162:165], v[92:95]
	v_mfma_f32_16x16x32_bf16 v[88:91], v[204:207], v[162:165], v[88:91]
	v_mfma_f32_16x16x32_bf16 v[84:87], v[196:199], v[170:173], v[84:87]
	v_mfma_f32_16x16x32_bf16 v[80:83], v[204:207], v[170:173], v[80:83]
	v_mfma_f32_16x16x32_bf16 v[76:79], v[196:199], v[180:183], v[76:79]
	v_mfma_f32_16x16x32_bf16 v[72:75], v[204:207], v[180:183], v[72:75]
	v_mfma_f32_16x16x32_bf16 v[68:71], v[196:199], v[188:191], v[68:71]
	v_mfma_f32_16x16x32_bf16 v[64:67], v[204:207], v[188:191], v[64:67]
	v_mfma_f32_16x16x32_bf16 v[92:95], v[200:203], v[166:169], v[92:95]
	v_mfma_f32_16x16x32_bf16 v[88:91], v[208:211], v[166:169], v[88:91]
	v_mfma_f32_16x16x32_bf16 v[84:87], v[200:203], v[176:179], v[84:87]
	v_mfma_f32_16x16x32_bf16 v[80:83], v[208:211], v[176:179], v[80:83]
	v_mfma_f32_16x16x32_bf16 v[76:79], v[200:203], v[184:187], v[76:79]
	v_mfma_f32_16x16x32_bf16 v[72:75], v[208:211], v[184:187], v[72:75]
	v_mfma_f32_16x16x32_bf16 v[68:71], v[200:203], v[192:195], v[68:71]
	v_mfma_f32_16x16x32_bf16 v[64:67], v[208:211], v[192:195], v[64:67]
	s_add_i32 s75, s69, s72
	s_mov_b32 m0, s38
	s_add_i32 s78, s75, 0x8000
	s_barrier
	ds_read_b128 v[162:165], v134 offset:16384
	ds_read_b128 v[166:169], v134 offset:17408
	ds_read_b128 v[170:173], v135 offset:16384
	ds_read_b128 v[176:179], v135 offset:17408
	ds_read_b128 v[180:183], v136 offset:16384
	ds_read_b128 v[184:187], v136 offset:17408
	ds_read_b128 v[188:191], v137 offset:16384
	ds_read_b128 v[192:195], v137 offset:17408
	buffer_load_dwordx4 v130, s[0:3], s78 offen lds
	s_mov_b32 m0, s39
	s_add_i32 s78, s75, 0xa000
	buffer_load_dwordx4 v130, s[0:3], s78 offen lds
	s_barrier
	s_waitcnt lgkmcnt(0)
	v_mfma_f32_16x16x32_bf16 v[60:63], v[142:145], v[162:165], v[60:63]
	v_mfma_f32_16x16x32_bf16 v[56:59], v[150:153], v[162:165], v[56:59]
	v_mfma_f32_16x16x32_bf16 v[52:55], v[142:145], v[170:173], v[52:55]
	v_mfma_f32_16x16x32_bf16 v[48:51], v[150:153], v[170:173], v[48:51]
	v_mfma_f32_16x16x32_bf16 v[44:47], v[142:145], v[180:183], v[44:47]
	v_mfma_f32_16x16x32_bf16 v[40:43], v[150:153], v[180:183], v[40:43]
	v_mfma_f32_16x16x32_bf16 v[36:39], v[142:145], v[188:191], v[36:39]
	v_mfma_f32_16x16x32_bf16 v[32:35], v[150:153], v[188:191], v[32:35]
	v_mfma_f32_16x16x32_bf16 v[60:63], v[146:149], v[166:169], v[60:63]
	v_mfma_f32_16x16x32_bf16 v[56:59], v[154:157], v[166:169], v[56:59]
	v_mfma_f32_16x16x32_bf16 v[52:55], v[146:149], v[176:179], v[52:55]
	v_mfma_f32_16x16x32_bf16 v[48:51], v[154:157], v[176:179], v[48:51]
	v_mfma_f32_16x16x32_bf16 v[44:47], v[146:149], v[184:187], v[44:47]
	v_mfma_f32_16x16x32_bf16 v[40:43], v[154:157], v[184:187], v[40:43]
	v_mfma_f32_16x16x32_bf16 v[36:39], v[146:149], v[192:195], v[36:39]
	v_mfma_f32_16x16x32_bf16 v[32:35], v[154:157], v[192:195], v[32:35]
	s_barrier
	s_add_i32 s78, s68, s72
	s_mov_b32 m0, s40
	s_add_i32 s79, s78, 0x8000
	buffer_load_dwordx4 v130, s[4:7], s79 offen lds
	s_mov_b32 m0, s41
	s_add_i32 s79, s78, 0xa000
	buffer_load_dwordx4 v130, s[4:7], s79 offen lds
	s_waitcnt vmcnt(10)
	s_barrier
; #define LDA(dst, b, h)                                                                                               \
;   _Pragma("unroll") for (int m = 0; m < 4; ++m) _Pragma("unroll") for (int k = 0; k < 2; ++k) dst[m][k] =            \
;       *reinterpret_cast<const bf16x8*>(SA(b, h) + lds_byte(wr * 64 + m * 16 + fr, k * 32 + fq * 8))
; #define LDB(dst, b, h)                                                                                               \
;   _Pragma("unroll") for (int n = 0; n < 2; ++n) _Pragma("unroll") for (int k = 0; k < 2; ++k) dst[n][k] =            \
;       *reinterpret_cast<const bf16x8*>(SB(b, h) + lds_byte(wc * 32 + n * 16 + fr, k * 32 + fq * 8))
; #define WAIT_V(n) asm volatile("s_waitcnt vmcnt(" #n ")" ::: "memory")
; #define WAIT_L(n) asm volatile("s_waitcnt lgkmcnt(" #n ")" ::: "memory")
; #define BAR __builtin_amdgcn_s_barrier()
; #define SCHED __builtin_amdgcn_sched_barrier(0)
; template <int EPI>
; __device__ __forceinline__ void gemm_phase(const u16* __restrict__ A, const u16* __restrict__ Bt, const int K,
;                                            const int nN, char* shm, const EpiArgs& ea) {
;     ...
;       LDB(B0, 1, 0); SCHED; LDA(At, 1, 0); STAGE(SA(0, 1), rA, brow + HALF, t + 2);
;       WAIT_V(10); WAIT_L(8); BAR; WAIT_L(0); MMA(0, 0, At, B0); BAR; SCHED;
;       LDB(B1, 1, 1); STAGE(SB(1, 0), rB, bcol, t + 3);
;       WAIT_V(10); BAR; WAIT_L(0); MMA(0, 1, At, B1); BAR;
;       LDA(At, 1, 1); STAGE(SA(1, 0), rA, brow, t + 3);
;       BAR; WAIT_L(0); MMA(1, 0, At, B0); BAR; SCHED;
;       STAGE(SB(1, 1), rB, bcol + HALF, t + 3);
	v_mfma_f32_16x16x32_bf16 v[28:31], v[196:199], v[162:165], v[28:31]
	v_mfma_f32_16x16x32_bf16 v[24:27], v[204:207], v[162:165], v[24:27]
	v_mfma_f32_16x16x32_bf16 v[20:23], v[196:199], v[170:173], v[20:23]
	v_mfma_f32_16x16x32_bf16 v[16:19], v[204:207], v[170:173], v[16:19]
	v_mfma_f32_16x16x32_bf16 v[12:15], v[196:199], v[180:183], v[12:15]
	v_mfma_f32_16x16x32_bf16 v[8:11], v[204:207], v[180:183], v[8:11]
	v_mfma_f32_16x16x32_bf16 v[4:7], v[196:199], v[188:191], v[4:7]
	v_mfma_f32_16x16x32_bf16 v[0:3], v[204:207], v[188:191], v[0:3]
	v_mfma_f32_16x16x32_bf16 v[28:31], v[200:203], v[166:169], v[28:31]
	v_mfma_f32_16x16x32_bf16 v[24:27], v[208:211], v[166:169], v[24:27]
	v_mfma_f32_16x16x32_bf16 v[20:23], v[200:203], v[176:179], v[20:23]
	v_mfma_f32_16x16x32_bf16 v[16:19], v[208:211], v[176:179], v[16:19]
	v_mfma_f32_16x16x32_bf16 v[12:15], v[200:203], v[184:187], v[12:15]
	v_mfma_f32_16x16x32_bf16 v[8:11], v[208:211], v[184:187], v[8:11]
	v_mfma_f32_16x16x32_bf16 v[4:7], v[200:203], v[192:195], v[4:7]
	v_mfma_f32_16x16x32_bf16 v[0:3], v[208:211], v[192:195], v[0:3]
	s_barrier
	ds_read_b128 v[142:145], v139
	ds_read_b128 v[146:149], v139 offset:1024
	ds_read_b128 v[150:153], v139 offset:2048
	ds_read_b128 v[154:157], v139 offset:3072
	s_mov_b32 m0, s42
	s_add_i32 s79, s73, 0x8000
	ds_read_b128 v[162:165], v134 offset:32768
	ds_read_b128 v[166:169], v134 offset:33792
	ds_read_b128 v[170:173], v135 offset:32768
	ds_read_b128 v[176:179], v135 offset:33792
	ds_read_b128 v[180:183], v136 offset:32768
	ds_read_b128 v[184:187], v136 offset:33792
	ds_read_b128 v[188:191], v137 offset:32768
	ds_read_b128 v[192:195], v137 offset:33792
	buffer_load_dwordx4 v130, s[0:3], s79 offen lds
	s_mov_b32 m0, s43
	s_add_i32 s73, s73, 0xa000
	buffer_load_dwordx4 v130, s[0:3], s73 offen lds
	s_waitcnt vmcnt(10)
	s_waitcnt lgkmcnt(8)
	s_barrier
	s_waitcnt lgkmcnt(0)
	v_mfma_f32_16x16x32_bf16 v[124:127], v[142:145], v[162:165], v[124:127]
	v_mfma_f32_16x16x32_bf16 v[120:123], v[150:153], v[162:165], v[120:123]
	v_mfma_f32_16x16x32_bf16 v[116:119], v[142:145], v[170:173], v[116:119]
	v_mfma_f32_16x16x32_bf16 v[112:115], v[150:153], v[170:173], v[112:115]
	v_mfma_f32_16x16x32_bf16 v[108:111], v[142:145], v[180:183], v[108:111]
	v_mfma_f32_16x16x32_bf16 v[104:107], v[150:153], v[180:183], v[104:107]
	v_mfma_f32_16x16x32_bf16 v[100:103], v[142:145], v[188:191], v[100:103]
	v_mfma_f32_16x16x32_bf16 v[96:99], v[150:153], v[188:191], v[96:99]
	v_mfma_f32_16x16x32_bf16 v[124:127], v[146:149], v[166:169], v[124:127]
	v_mfma_f32_16x16x32_bf16 v[120:123], v[154:157], v[166:169], v[120:123]
	v_mfma_f32_16x16x32_bf16 v[116:119], v[146:149], v[176:179], v[116:119]
	v_mfma_f32_16x16x32_bf16 v[112:115], v[154:157], v[176:179], v[112:115]
	v_mfma_f32_16x16x32_bf16 v[108:111], v[146:149], v[184:187], v[108:111]
	v_mfma_f32_16x16x32_bf16 v[104:107], v[154:157], v[184:187], v[104:107]
	v_mfma_f32_16x16x32_bf16 v[100:103], v[146:149], v[192:195], v[100:103]
	v_mfma_f32_16x16x32_bf16 v[96:99], v[154:157], v[192:195], v[96:99]
	s_barrier
	s_mov_b32 m0, s48
	s_add_i32 s73, s74, 0xc000
	ds_read_b128 v[196:199], v140
	ds_read_b128 v[200:203], v140 offset:1024
	ds_read_b128 v[204:207], v140 offset:2048
	ds_read_b128 v[208:211], v140 offset:3072
	buffer_load_dwordx4 v130, s[4:7], s73 offen lds
	s_mov_b32 m0, s49
	s_add_i32 s74, s74, 0xe000
	buffer_load_dwordx4 v130, s[4:7], s74 offen lds
	s_waitcnt vmcnt(10)
	s_barrier
	s_waitcnt lgkmcnt(0)
	v_mfma_f32_16x16x32_bf16 v[92:95], v[196:199], v[162:165], v[92:95]
	v_mfma_f32_16x16x32_bf16 v[88:91], v[204:207], v[162:165], v[88:91]
	v_mfma_f32_16x16x32_bf16 v[84:87], v[196:199], v[170:173], v[84:87]
	v_mfma_f32_16x16x32_bf16 v[80:83], v[204:207], v[170:173], v[80:83]
	v_mfma_f32_16x16x32_bf16 v[76:79], v[196:199], v[180:183], v[76:79]
	v_mfma_f32_16x16x32_bf16 v[72:75], v[204:207], v[180:183], v[72:75]
	v_mfma_f32_16x16x32_bf16 v[68:71], v[196:199], v[188:191], v[68:71]
	v_mfma_f32_16x16x32_bf16 v[64:67], v[204:207], v[188:191], v[64:67]
	v_mfma_f32_16x16x32_bf16 v[92:95], v[200:203], v[166:169], v[92:95]
	v_mfma_f32_16x16x32_bf16 v[88:91], v[208:211], v[166:169], v[88:91]
	v_mfma_f32_16x16x32_bf16 v[84:87], v[200:203], v[176:179], v[84:87]
	v_mfma_f32_16x16x32_bf16 v[80:83], v[208:211], v[176:179], v[80:83]
	v_mfma_f32_16x16x32_bf16 v[76:79], v[200:203], v[184:187], v[76:79]
	v_mfma_f32_16x16x32_bf16 v[72:75], v[208:211], v[184:187], v[72:75]
	v_mfma_f32_16x16x32_bf16 v[68:71], v[200:203], v[192:195], v[68:71]
	v_mfma_f32_16x16x32_bf16 v[64:67], v[208:211], v[192:195], v[64:67]
	s_mov_b32 m0, s52
	s_add_i32 s73, s75, 0xc000
	s_barrier
	ds_read_b128 v[162:165], v134 offset:49152
	ds_read_b128 v[166:169], v134 offset:50176
	ds_read_b128 v[170:173], v135 offset:49152
	ds_read_b128 v[176:179], v135 offset:50176
	ds_read_b128 v[180:183], v136 offset:49152
	ds_read_b128 v[184:187], v136 offset:50176
	ds_read_b128 v[188:191], v137 offset:49152
	ds_read_b128 v[192:195], v137 offset:50176
	buffer_load_dwordx4 v130, s[0:3], s73 offen lds
	s_mov_b32 m0, s53
	s_add_i32 s75, s75, 0xe000
	buffer_load_dwordx4 v130, s[0:3], s75 offen lds
	s_barrier
; #define LDA(dst, b, h)                                                                                               \
;   _Pragma("unroll") for (int m = 0; m < 4; ++m) _Pragma("unroll") for (int k = 0; k < 2; ++k) dst[m][k] =            \
;       *reinterpret_cast<const bf16x8*>(SA(b, h) + lds_byte(wr * 64 + m * 16 + fr, k * 32 + fq * 8))
; #define LDB(dst, b, h)                                                                                               \
;   _Pragma("unroll") for (int n = 0; n < 2; ++n) _Pragma("unroll") for (int k = 0; k < 2; ++k) dst[n][k] =            \
;       *reinterpret_cast<const bf16x8*>(SB(b, h) + lds_byte(wc * 32 + n * 16 + fr, k * 32 + fq * 8))
; #define WAIT_V(n) asm volatile("s_waitcnt vmcnt(" #n ")" ::: "memory")
; #define WAIT_L(n) asm volatile("s_waitcnt lgkmcnt(" #n ")" ::: "memory")
; #define BAR __builtin_amdgcn_s_barrier()
; #define SCHED __builtin_amdgcn_sched_barrier(0)
; template <int EPI>
; __device__ __forceinline__ void gemm_phase(const u16* __restrict__ A, const u16* __restrict__ Bt, const int K,
;                                            const int nN, char* shm, const EpiArgs& ea) {
;     ...
;       BAR; WAIT_L(0); MMA(1, 0, At, B0); BAR; SCHED;
;       STAGE(SB(1, 1), rB, bcol + HALF, t + 3);
;       WAIT_V(10); BAR; MMA(1, 1, At, B1); BAR;
;     }
;     float eC = 0.f, eB = 0.f;
;     float2 eS = make_float2(0.f, 0.f);
;     if (EPI == EPI_IN || EPI == EPI_SWIGLU_LN) {
;       if (wr == 0) {
;         eC = ea.c1[bcol + tid];
;         eS = *(const float2*)(ea.st_in + (size_t)(brow + tid) * 2);
;       } else {
;         eC = ea.c2[bcol + tid - 256];
;         if (EPI == EPI_IN) eB = ea.bias[bcol + tid - 256];
;       }
;     }
;     {
;       LDB(B0, 0, 0); LDA(At, 0, 0); STAGE(SA(1, 1), rA, brow + HALF, nt - 1);
;       WAIT_V(10); BAR; WAIT_L(0); MMA(0, 0, At, B0); BAR;
;       LDB(B1, 0, 1); WAIT_V(8); BAR; WAIT_L(0); MMA(0, 1, At, B1); BAR;
;       LDA(At, 0, 1); WAIT_V(4); BAR; WAIT_L(0); MMA(1, 0, At, B0); MMA(1, 1, At, B1); BAR;
;     }
;     {
;       LDB(B0, 1, 0); LDA(At, 1, 0); WAIT_V(2); BAR; WAIT_L(0); MMA(0, 0, At, B0); BAR;
	s_waitcnt lgkmcnt(0)
	v_mfma_f32_16x16x32_bf16 v[60:63], v[142:145], v[162:165], v[60:63]
	v_mfma_f32_16x16x32_bf16 v[56:59], v[150:153], v[162:165], v[56:59]
	v_mfma_f32_16x16x32_bf16 v[52:55], v[142:145], v[170:173], v[52:55]
	v_mfma_f32_16x16x32_bf16 v[48:51], v[150:153], v[170:173], v[48:51]
	v_mfma_f32_16x16x32_bf16 v[44:47], v[142:145], v[180:183], v[44:47]
	v_mfma_f32_16x16x32_bf16 v[40:43], v[150:153], v[180:183], v[40:43]
	v_mfma_f32_16x16x32_bf16 v[36:39], v[142:145], v[188:191], v[36:39]
	v_mfma_f32_16x16x32_bf16 v[32:35], v[150:153], v[188:191], v[32:35]
	v_mfma_f32_16x16x32_bf16 v[60:63], v[146:149], v[166:169], v[60:63]
	v_mfma_f32_16x16x32_bf16 v[56:59], v[154:157], v[166:169], v[56:59]
	v_mfma_f32_16x16x32_bf16 v[52:55], v[146:149], v[176:179], v[52:55]
	v_mfma_f32_16x16x32_bf16 v[48:51], v[154:157], v[176:179], v[48:51]
	v_mfma_f32_16x16x32_bf16 v[44:47], v[146:149], v[184:187], v[44:47]
	v_mfma_f32_16x16x32_bf16 v[40:43], v[154:157], v[184:187], v[40:43]
	v_mfma_f32_16x16x32_bf16 v[36:39], v[146:149], v[192:195], v[36:39]
	v_mfma_f32_16x16x32_bf16 v[32:35], v[154:157], v[192:195], v[32:35]
	s_barrier
	s_mov_b32 m0, s54
	s_add_i32 s73, s78, 0xc000
	buffer_load_dwordx4 v130, s[4:7], s73 offen lds
	s_mov_b32 m0, s55
	s_add_i32 s78, s78, 0xe000
	buffer_load_dwordx4 v130, s[4:7], s78 offen lds
	s_waitcnt vmcnt(10)
	s_barrier
	v_mfma_f32_16x16x32_bf16 v[28:31], v[196:199], v[162:165], v[28:31]
	v_mfma_f32_16x16x32_bf16 v[24:27], v[204:207], v[162:165], v[24:27]
	v_mfma_f32_16x16x32_bf16 v[20:23], v[196:199], v[170:173], v[20:23]
	v_mfma_f32_16x16x32_bf16 v[16:19], v[204:207], v[170:173], v[16:19]
	v_mfma_f32_16x16x32_bf16 v[12:15], v[196:199], v[180:183], v[12:15]
	v_mfma_f32_16x16x32_bf16 v[8:11], v[204:207], v[180:183], v[8:11]
	v_mfma_f32_16x16x32_bf16 v[4:7], v[196:199], v[188:191], v[4:7]
	v_mfma_f32_16x16x32_bf16 v[0:3], v[204:207], v[188:191], v[0:3]
	v_mfma_f32_16x16x32_bf16 v[28:31], v[200:203], v[166:169], v[28:31]
	v_mfma_f32_16x16x32_bf16 v[24:27], v[208:211], v[166:169], v[24:27]
	v_mfma_f32_16x16x32_bf16 v[20:23], v[200:203], v[176:179], v[20:23]
	v_mfma_f32_16x16x32_bf16 v[16:19], v[208:211], v[176:179], v[16:19]
	v_mfma_f32_16x16x32_bf16 v[12:15], v[200:203], v[184:187], v[12:15]
	v_mfma_f32_16x16x32_bf16 v[8:11], v[208:211], v[184:187], v[8:11]
	v_mfma_f32_16x16x32_bf16 v[4:7], v[200:203], v[192:195], v[4:7]
	v_mfma_f32_16x16x32_bf16 v[0:3], v[208:211], v[192:195], v[0:3]
	s_add_i32 s71, s71, 2
	s_add_i32 s72, s72, 0x8000
	s_cmp_lt_u32 s71, 28
	s_barrier
	s_cbranch_scc1 .LBB0_172
	s_mov_b32 m0, s57
	s_add_i32 s6, s67, 0x7c000
	ds_read_b128 v[142:145], v133
	ds_read_b128 v[146:149], v133 offset:1024
	ds_read_b128 v[150:153], v133 offset:2048
	ds_read_b128 v[154:157], v133 offset:3072
	ds_read_b128 v[162:165], v134
	ds_read_b128 v[166:169], v134 offset:1024
	ds_read_b128 v[170:173], v135
	ds_read_b128 v[176:179], v135 offset:1024
	ds_read_b128 v[180:183], v136
	ds_read_b128 v[184:187], v136 offset:1024
	ds_read_b128 v[188:191], v137
	ds_read_b128 v[192:195], v137 offset:1024
	buffer_load_dwordx4 v130, s[0:3], s6 offen lds
	s_mov_b32 m0, s58
	s_add_i32 s67, s67, 0x7e000
	buffer_load_dwordx4 v130, s[0:3], s67 offen lds
	s_waitcnt vmcnt(10)
	s_barrier
	s_waitcnt lgkmcnt(0)
	v_mfma_f32_16x16x32_bf16 v[124:127], v[142:145], v[162:165], v[124:127]
	v_mfma_f32_16x16x32_bf16 v[120:123], v[150:153], v[162:165], v[120:123]
	v_mfma_f32_16x16x32_bf16 v[116:119], v[142:145], v[170:173], v[116:119]
	v_mfma_f32_16x16x32_bf16 v[112:115], v[150:153], v[170:173], v[112:115]
	v_mfma_f32_16x16x32_bf16 v[108:111], v[142:145], v[180:183], v[108:111]
	v_mfma_f32_16x16x32_bf16 v[104:107], v[150:153], v[180:183], v[104:107]
	v_mfma_f32_16x16x32_bf16 v[100:103], v[142:145], v[188:191], v[100:103]
	v_mfma_f32_16x16x32_bf16 v[96:99], v[150:153], v[188:191], v[96:99]
	v_mfma_f32_16x16x32_bf16 v[124:127], v[146:149], v[166:169], v[124:127]
	v_mfma_f32_16x16x32_bf16 v[120:123], v[154:157], v[166:169], v[120:123]
	v_mfma_f32_16x16x32_bf16 v[116:119], v[146:149], v[176:179], v[116:119]
	v_mfma_f32_16x16x32_bf16 v[112:115], v[154:157], v[176:179], v[112:115]
	v_mfma_f32_16x16x32_bf16 v[108:111], v[146:149], v[184:187], v[108:111]
	v_mfma_f32_16x16x32_bf16 v[104:107], v[154:157], v[184:187], v[104:107]
	v_mfma_f32_16x16x32_bf16 v[100:103], v[146:149], v[192:195], v[100:103]
	v_mfma_f32_16x16x32_bf16 v[96:99], v[154:157], v[192:195], v[96:99]
	s_barrier
	ds_read_b128 v[196:199], v138
	ds_read_b128 v[200:203], v138 offset:1024
	ds_read_b128 v[204:207], v138 offset:2048
	ds_read_b128 v[208:211], v138 offset:3072
	s_waitcnt vmcnt(8)
	s_barrier
	s_waitcnt lgkmcnt(0)
	v_mfma_f32_16x16x32_bf16 v[76:79], v[196:199], v[180:183], v[76:79]
	v_mfma_f32_16x16x32_bf16 v[72:75], v[204:207], v[180:183], v[72:75]
	v_mfma_f32_16x16x32_bf16 v[68:71], v[196:199], v[188:191], v[68:71]
	v_mfma_f32_16x16x32_bf16 v[64:67], v[204:207], v[188:191], v[64:67]
	v_mfma_f32_16x16x32_bf16 v[92:95], v[196:199], v[162:165], v[92:95]
	v_mfma_f32_16x16x32_bf16 v[88:91], v[204:207], v[162:165], v[88:91]
	v_mfma_f32_16x16x32_bf16 v[84:87], v[196:199], v[170:173], v[84:87]
	v_mfma_f32_16x16x32_bf16 v[80:83], v[204:207], v[170:173], v[80:83]
	v_mfma_f32_16x16x32_bf16 v[76:79], v[200:203], v[184:187], v[76:79]
	v_mfma_f32_16x16x32_bf16 v[72:75], v[208:211], v[184:187], v[72:75]
	v_mfma_f32_16x16x32_bf16 v[68:71], v[200:203], v[192:195], v[68:71]
	v_mfma_f32_16x16x32_bf16 v[64:67], v[208:211], v[192:195], v[64:67]
	v_mfma_f32_16x16x32_bf16 v[212:215], v[200:203], v[166:169], v[92:95]
	v_mfma_f32_16x16x32_bf16 v[162:165], v[208:211], v[166:169], v[88:91]
	v_mfma_f32_16x16x32_bf16 v[166:169], v[200:203], v[176:179], v[84:87]
	v_mfma_f32_16x16x32_bf16 v[170:173], v[208:211], v[176:179], v[80:83]
	s_barrier
; #define LDA(dst, b, h)                                                                                               \
;   _Pragma("unroll") for (int m = 0; m < 4; ++m) _Pragma("unroll") for (int k = 0; k < 2; ++k) dst[m][k] =            \
;       *reinterpret_cast<const bf16x8*>(SA(b, h) + lds_byte(wr * 64 + m * 16 + fr, k * 32 + fq * 8))
; #define LDB(dst, b, h)                                                                                               \
;   _Pragma("unroll") for (int n = 0; n < 2; ++n) _Pragma("unroll") for (int k = 0; k < 2; ++k) dst[n][k] =            \
;       *reinterpret_cast<const bf16x8*>(SB(b, h) + lds_byte(wc * 32 + n * 16 + fr, k * 32 + fq * 8))
; #define WAIT_V(n) asm volatile("s_waitcnt vmcnt(" #n ")" ::: "memory")
; #define WAIT_L(n) asm volatile("s_waitcnt lgkmcnt(" #n ")" ::: "memory")
; #define BAR __builtin_amdgcn_s_barrier()
; template <int EPI>
; __device__ __forceinline__ void gemm_phase(const u16* __restrict__ A, const u16* __restrict__ Bt, const int K,
;                                            const int nN, char* shm, const EpiArgs& ea) {
;     ...
;       LDA(At, 0, 1); WAIT_V(4); BAR; WAIT_L(0); MMA(1, 0, At, B0); MMA(1, 1, At, B1); BAR;
;     }
;     {
;       LDB(B0, 1, 0); LDA(At, 1, 0); WAIT_V(2); BAR; WAIT_L(0); MMA(0, 0, At, B0); BAR;
;       LDB(B1, 1, 1); WAIT_V(0); BAR; WAIT_L(0); MMA(0, 1, At, B1); BAR;
;       LDA(At, 1, 1); BAR; WAIT_L(0); MMA(1, 0, At, B0); MMA(1, 1, At, B1); BAR;
	s_nop 0
	ds_read_b128 v[80:83], v134 offset:16384
	ds_read_b128 v[84:87], v134 offset:17408
	ds_read_b128 v[88:91], v135 offset:16384
	ds_read_b128 v[92:95], v135 offset:17408
	ds_read_b128 v[176:179], v136 offset:16384
	ds_read_b128 v[180:183], v136 offset:17408
	ds_read_b128 v[184:187], v137 offset:16384
	ds_read_b128 v[188:191], v137 offset:17408
	s_waitcnt vmcnt(4)
	s_barrier
	s_waitcnt lgkmcnt(0)
	v_mfma_f32_16x16x32_bf16 v[60:63], v[142:145], v[80:83], v[60:63]
	v_mfma_f32_16x16x32_bf16 v[56:59], v[150:153], v[80:83], v[56:59]
	v_mfma_f32_16x16x32_bf16 v[52:55], v[142:145], v[88:91], v[52:55]
	v_mfma_f32_16x16x32_bf16 v[48:51], v[150:153], v[88:91], v[48:51]
	v_mfma_f32_16x16x32_bf16 v[44:47], v[142:145], v[176:179], v[44:47]
	v_mfma_f32_16x16x32_bf16 v[40:43], v[150:153], v[176:179], v[40:43]
	v_mfma_f32_16x16x32_bf16 v[36:39], v[142:145], v[184:187], v[36:39]
	v_mfma_f32_16x16x32_bf16 v[32:35], v[150:153], v[184:187], v[32:35]
	v_mfma_f32_16x16x32_bf16 v[60:63], v[146:149], v[84:87], v[60:63]
	v_mfma_f32_16x16x32_bf16 v[56:59], v[154:157], v[84:87], v[56:59]
	v_mfma_f32_16x16x32_bf16 v[52:55], v[146:149], v[92:95], v[52:55]
	v_mfma_f32_16x16x32_bf16 v[48:51], v[154:157], v[92:95], v[48:51]
	v_mfma_f32_16x16x32_bf16 v[44:47], v[146:149], v[180:183], v[44:47]
	v_mfma_f32_16x16x32_bf16 v[40:43], v[154:157], v[180:183], v[40:43]
	v_mfma_f32_16x16x32_bf16 v[36:39], v[146:149], v[188:191], v[36:39]
	v_mfma_f32_16x16x32_bf16 v[32:35], v[154:157], v[188:191], v[32:35]
	v_mfma_f32_16x16x32_bf16 v[12:15], v[196:199], v[176:179], v[12:15]
	v_mfma_f32_16x16x32_bf16 v[8:11], v[204:207], v[176:179], v[8:11]
	v_mfma_f32_16x16x32_bf16 v[4:7], v[196:199], v[184:187], v[4:7]
	v_mfma_f32_16x16x32_bf16 v[0:3], v[204:207], v[184:187], v[0:3]
	v_mfma_f32_16x16x32_bf16 v[28:31], v[196:199], v[80:83], v[28:31]
	v_mfma_f32_16x16x32_bf16 v[24:27], v[204:207], v[80:83], v[24:27]
	v_mfma_f32_16x16x32_bf16 v[20:23], v[196:199], v[88:91], v[20:23]
	v_mfma_f32_16x16x32_bf16 v[16:19], v[204:207], v[88:91], v[16:19]
	v_mfma_f32_16x16x32_bf16 v[12:15], v[200:203], v[180:183], v[12:15]
	v_mfma_f32_16x16x32_bf16 v[8:11], v[208:211], v[180:183], v[8:11]
	v_mfma_f32_16x16x32_bf16 v[4:7], v[200:203], v[188:191], v[4:7]
	v_mfma_f32_16x16x32_bf16 v[0:3], v[208:211], v[188:191], v[0:3]
	v_mfma_f32_16x16x32_bf16 v[142:145], v[200:203], v[84:87], v[28:31]
	v_mfma_f32_16x16x32_bf16 v[146:149], v[208:211], v[84:87], v[24:27]
	v_mfma_f32_16x16x32_bf16 v[150:153], v[200:203], v[92:95], v[20:23]
	v_mfma_f32_16x16x32_bf16 v[154:157], v[208:211], v[92:95], v[16:19]
	s_barrier
	s_nop 0
	ds_read_b128 v[16:19], v139
	ds_read_b128 v[20:23], v139 offset:1024
	ds_read_b128 v[176:179], v139 offset:2048
	ds_read_b128 v[180:183], v139 offset:3072
	ds_read_b128 v[24:27], v134 offset:32768
	ds_read_b128 v[28:31], v134 offset:33792
	ds_read_b128 v[184:187], v135 offset:32768
	ds_read_b128 v[188:191], v135 offset:33792
	ds_read_b128 v[192:195], v136 offset:32768
	ds_read_b128 v[196:199], v136 offset:33792
	ds_read_b128 v[200:203], v137 offset:32768
	ds_read_b128 v[204:207], v137 offset:33792
	s_waitcnt vmcnt(2)
	s_barrier
	s_waitcnt lgkmcnt(0)
	v_mfma_f32_16x16x32_bf16 v[80:83], v[16:19], v[24:27], v[124:127]
	v_mfma_f32_16x16x32_bf16 v[124:127], v[20:23], v[28:31], v[80:83]
	v_mfma_f32_16x16x32_bf16 v[80:83], v[176:179], v[24:27], v[120:123]
	v_mfma_f32_16x16x32_bf16 v[120:123], v[180:183], v[28:31], v[80:83]
	v_mfma_f32_16x16x32_bf16 v[80:83], v[16:19], v[184:187], v[116:119]
	v_mfma_f32_16x16x32_bf16 v[116:119], v[20:23], v[188:191], v[80:83]
	v_mfma_f32_16x16x32_bf16 v[80:83], v[176:179], v[184:187], v[112:115]
	v_mfma_f32_16x16x32_bf16 v[112:115], v[180:183], v[188:191], v[80:83]
	v_mfma_f32_16x16x32_bf16 v[80:83], v[16:19], v[192:195], v[108:111]
	v_mfma_f32_16x16x32_bf16 v[92:95], v[20:23], v[196:199], v[80:83]
	v_mfma_f32_16x16x32_bf16 v[80:83], v[176:179], v[192:195], v[104:107]
	v_mfma_f32_16x16x32_bf16 v[88:91], v[180:183], v[196:199], v[80:83]
	v_mfma_f32_16x16x32_bf16 v[80:83], v[16:19], v[200:203], v[100:103]
	v_mfma_f32_16x16x32_bf16 v[84:87], v[20:23], v[204:207], v[80:83]
	v_mfma_f32_16x16x32_bf16 v[80:83], v[176:179], v[200:203], v[96:99]
	v_mfma_f32_16x16x32_bf16 v[80:83], v[180:183], v[204:207], v[80:83]
	s_barrier
	ds_read_b128 v[208:211], v140
	ds_read_b128 v[216:219], v140 offset:1024
	ds_read_b128 v[220:223], v140 offset:2048
	ds_read_b128 v[224:227], v140 offset:3072
	s_waitcnt vmcnt(0)
	s_barrier
; #define LDA(dst, b, h)                                                                                               \
;   _Pragma("unroll") for (int m = 0; m < 4; ++m) _Pragma("unroll") for (int k = 0; k < 2; ++k) dst[m][k] =            \
;       *reinterpret_cast<const bf16x8*>(SA(b, h) + lds_byte(wr * 64 + m * 16 + fr, k * 32 + fq * 8))
; #define LDB(dst, b, h)                                                                                               \
;   _Pragma("unroll") for (int n = 0; n < 2; ++n) _Pragma("unroll") for (int k = 0; k < 2; ++k) dst[n][k] =            \
;       *reinterpret_cast<const bf16x8*>(SB(b, h) + lds_byte(wc * 32 + n * 16 + fr, k * 32 + fq * 8))
; #define WAIT_V(n) asm volatile("s_waitcnt vmcnt(" #n ")" ::: "memory")
; #define WAIT_L(n) asm volatile("s_waitcnt lgkmcnt(" #n ")" ::: "memory")
; #define BAR __builtin_amdgcn_s_barrier()
; template <int EPI>
; __device__ __forceinline__ void gemm_phase(const u16* __restrict__ A, const u16* __restrict__ Bt, const int K,
;                                            const int nN, char* shm, const EpiArgs& ea) {
;     ...
;       LDB(B0, 1, 0); LDA(At, 1, 0); WAIT_V(2); BAR; WAIT_L(0); MMA(0, 0, At, B0); BAR;
;       LDB(B1, 1, 1); WAIT_V(0); BAR; WAIT_L(0); MMA(0, 1, At, B1); BAR;
;       LDA(At, 1, 1); BAR; WAIT_L(0); MMA(1, 0, At, B0); MMA(1, 1, At, B1); BAR;
;     }
;     if (wr == 0) BAR;
;     if (has_next) STAGE7(brow2, bcol2);
	s_waitcnt lgkmcnt(0)
	v_mfma_f32_16x16x32_bf16 v[96:99], v[208:211], v[24:27], v[212:215]
	v_mfma_f32_16x16x32_bf16 v[24:27], v[220:223], v[24:27], v[162:165]
	v_mfma_f32_16x16x32_bf16 v[104:107], v[224:227], v[28:31], v[24:27]
	v_mfma_f32_16x16x32_bf16 v[24:27], v[208:211], v[184:187], v[166:169]
	v_mfma_f32_16x16x32_bf16 v[100:103], v[216:219], v[188:191], v[24:27]
	v_mfma_f32_16x16x32_bf16 v[24:27], v[220:223], v[184:187], v[170:173]
	v_mfma_f32_16x16x32_bf16 v[108:111], v[216:219], v[28:31], v[96:99]
	v_mfma_f32_16x16x32_bf16 v[96:99], v[224:227], v[188:191], v[24:27]
	v_mfma_f32_16x16x32_bf16 v[24:27], v[208:211], v[192:195], v[76:79]
	v_mfma_f32_16x16x32_bf16 v[76:79], v[216:219], v[196:199], v[24:27]
	v_mfma_f32_16x16x32_bf16 v[24:27], v[220:223], v[192:195], v[72:75]
	v_mfma_f32_16x16x32_bf16 v[72:75], v[224:227], v[196:199], v[24:27]
	v_mfma_f32_16x16x32_bf16 v[24:27], v[208:211], v[200:203], v[68:71]
	v_mfma_f32_16x16x32_bf16 v[68:71], v[216:219], v[204:207], v[24:27]
	v_mfma_f32_16x16x32_bf16 v[24:27], v[220:223], v[200:203], v[64:67]
	v_mfma_f32_16x16x32_bf16 v[64:67], v[224:227], v[204:207], v[24:27]
	s_barrier
	ds_read_b128 v[162:165], v134 offset:49152
	ds_read_b128 v[166:169], v134 offset:50176
	ds_read_b128 v[170:173], v135 offset:49152
	ds_read_b128 v[184:187], v135 offset:50176
	ds_read_b128 v[188:191], v136 offset:49152
	ds_read_b128 v[192:195], v136 offset:50176
	ds_read_b128 v[196:199], v137 offset:49152
	ds_read_b128 v[200:203], v137 offset:50176
	s_barrier
	s_waitcnt lgkmcnt(0)
	v_mfma_f32_16x16x32_bf16 v[24:27], v[16:19], v[162:165], v[60:63]
	v_mfma_f32_16x16x32_bf16 v[60:63], v[20:23], v[166:169], v[24:27]
	v_mfma_f32_16x16x32_bf16 v[24:27], v[176:179], v[162:165], v[56:59]
	v_mfma_f32_16x16x32_bf16 v[56:59], v[180:183], v[166:169], v[24:27]
	v_mfma_f32_16x16x32_bf16 v[24:27], v[16:19], v[170:173], v[52:55]
	v_mfma_f32_16x16x32_bf16 v[52:55], v[20:23], v[184:187], v[24:27]
	v_mfma_f32_16x16x32_bf16 v[24:27], v[176:179], v[170:173], v[48:51]
	v_mfma_f32_16x16x32_bf16 v[48:51], v[180:183], v[184:187], v[24:27]
	v_mfma_f32_16x16x32_bf16 v[24:27], v[16:19], v[188:191], v[44:47]
	v_mfma_f32_16x16x32_bf16 v[16:19], v[16:19], v[196:199], v[36:39]
	v_mfma_f32_16x16x32_bf16 v[28:31], v[20:23], v[192:195], v[24:27]
	v_mfma_f32_16x16x32_bf16 v[24:27], v[176:179], v[188:191], v[40:43]
	v_mfma_f32_16x16x32_bf16 v[20:23], v[20:23], v[200:203], v[16:19]
	v_mfma_f32_16x16x32_bf16 v[16:19], v[176:179], v[196:199], v[32:35]
	v_mfma_f32_16x16x32_bf16 v[24:27], v[180:183], v[192:195], v[24:27]
	v_mfma_f32_16x16x32_bf16 v[16:19], v[180:183], v[200:203], v[16:19]
	v_mfma_f32_16x16x32_bf16 v[32:35], v[208:211], v[162:165], v[142:145]
	v_mfma_f32_16x16x32_bf16 v[44:47], v[216:219], v[166:169], v[32:35]
	v_mfma_f32_16x16x32_bf16 v[32:35], v[220:223], v[162:165], v[146:149]
	v_mfma_f32_16x16x32_bf16 v[40:43], v[224:227], v[166:169], v[32:35]
	v_mfma_f32_16x16x32_bf16 v[32:35], v[208:211], v[170:173], v[150:153]
	v_mfma_f32_16x16x32_bf16 v[36:39], v[216:219], v[184:187], v[32:35]
	v_mfma_f32_16x16x32_bf16 v[32:35], v[220:223], v[170:173], v[154:157]
	v_mfma_f32_16x16x32_bf16 v[12:15], v[208:211], v[188:191], v[12:15]
	v_mfma_f32_16x16x32_bf16 v[8:11], v[220:223], v[188:191], v[8:11]
	v_mfma_f32_16x16x32_bf16 v[4:7], v[208:211], v[196:199], v[4:7]
	v_mfma_f32_16x16x32_bf16 v[0:3], v[220:223], v[196:199], v[0:3]
	v_mfma_f32_16x16x32_bf16 v[32:35], v[224:227], v[184:187], v[32:35]
	v_mfma_f32_16x16x32_bf16 v[12:15], v[216:219], v[192:195], v[12:15]
	v_mfma_f32_16x16x32_bf16 v[8:11], v[224:227], v[192:195], v[8:11]
	v_mfma_f32_16x16x32_bf16 v[4:7], v[216:219], v[200:203], v[4:7]
	v_mfma_f32_16x16x32_bf16 v[0:3], v[224:227], v[200:203], v[0:3]
	s_andn2_b64 vcc, exec, s[26:27]
	s_barrier
	s_cbranch_vccnz .LBB0_175
	s_barrier
.LBB0_175:
	s_andn2_b64 vcc, exec, s[30:31]
	s_cbranch_vccnz .LBB0_166
	s_lshr_b32 s6, s63, 7
	s_mov_b32 m0, s34
	s_mul_i32 s30, s6, 0x84000
	s_mov_b32 s6, s2
	s_mov_b32 s7, s3
	buffer_load_dwordx4 v130, s[4:7], s30 offen lds
	s_mov_b32 m0, s35
	s_or_b32 s31, s30, 0x2000
	buffer_load_dwordx4 v130, s[4:7], s31 offen lds
	s_lshr_b32 s31, s64, 7
	s_mul_i32 s31, s31, 0x84000
	s_mov_b32 m0, s38
	s_or_b32 s67, s31, 0x2000
	buffer_load_dwordx4 v130, s[0:3], s31 offen lds
	s_mov_b32 m0, s39
	s_nop 0
	buffer_load_dwordx4 v130, s[0:3], s67 offen lds
	s_mov_b32 m0, s40
	s_add_i32 s67, s30, 0x84000
	buffer_load_dwordx4 v130, s[4:7], s67 offen lds
	s_mov_b32 m0, s41
	s_add_i32 s67, s30, 0x86000
	buffer_load_dwordx4 v130, s[4:7], s67 offen lds
	s_mov_b32 m0, s42
	s_add_i32 s67, s31, 0x84000
	buffer_load_dwordx4 v130, s[0:3], s67 offen lds
	s_mov_b32 m0, s43
	s_add_i32 s67, s31, 0x86000
	buffer_load_dwordx4 v130, s[0:3], s67 offen lds
	s_mov_b32 m0, s48
	s_or_b32 s67, s30, 0x4000
	buffer_load_dwordx4 v130, s[4:7], s67 offen lds
	s_mov_b32 m0, s49
	s_or_b32 s67, s30, 0x6000
	buffer_load_dwordx4 v130, s[4:7], s67 offen lds
	s_or_b32 s67, s31, 0x4000
	s_mov_b32 m0, s52
	s_or_b32 s31, s31, 0x6000
	buffer_load_dwordx4 v130, s[0:3], s67 offen lds
	s_mov_b32 m0, s53
	s_nop 0
	buffer_load_dwordx4 v130, s[0:3], s31 offen lds
	s_add_i32 s31, s30, 0x88000
	s_mov_b32 m0, s54
	s_add_i32 s30, s30, 0x8a000
	buffer_load_dwordx4 v130, s[4:7], s31 offen lds
	s_mov_b32 m0, s55
	s_nop 0
	buffer_load_dwordx4 v130, s[4:7], s30 offen lds
	s_branch .LBB0_166

; #define LDA(dst, b, h)                                                                                               \
;   _Pragma("unroll") for (int m = 0; m < 4; ++m) _Pragma("unroll") for (int k = 0; k < 2; ++k) dst[m][k] =            \
;       *reinterpret_cast<const bf16x8*>(SA(b, h) + lds_byte(wr * 64 + m * 16 + fr, k * 32 + fq * 8))
; #define LDB(dst, b, h)                                                                                               \
;   _Pragma("unroll") for (int n = 0; n < 2; ++n) _Pragma("unroll") for (int k = 0; k < 2; ++k) dst[n][k] =            \
;       *reinterpret_cast<const bf16x8*>(SB(b, h) + lds_byte(wc * 32 + n * 16 + fr, k * 32 + fq * 8))
; #define WAIT_V(n) asm volatile("s_waitcnt vmcnt(" #n ")" ::: "memory")
; #define WAIT_L(n) asm volatile("s_waitcnt lgkmcnt(" #n ")" ::: "memory")
; #define BAR __builtin_amdgcn_s_barrier()
; #define SCHED __builtin_amdgcn_sched_barrier(0)
; template <int EPI>
; __device__ __forceinline__ void gemm_phase(const u16* __restrict__ A, const u16* __restrict__ Bt, const int K,
;                                            const int nN, char* shm, const EpiArgs& ea) {
;     ...
;       LDB(B0, 0, 0); SCHED; LDA(At, 0, 0); STAGE(SA(1, 1), rA, brow + HALF, t + 1);
;       WAIT_V(10); WAIT_L(8); BAR; WAIT_L(0); MMA(0, 0, At, B0); BAR; SCHED;
;       LDB(B1, 0, 1); STAGE(SB(0, 0), rB, bcol, t + 2);
;       WAIT_V(10); BAR; WAIT_L(0); MMA(0, 1, At, B1); BAR;
;       LDA(At, 0, 1); STAGE(SA(0, 0), rA, brow, t + 2);
;       BAR; WAIT_L(0); MMA(1, 0, At, B0); BAR; SCHED;
;       STAGE(SB(0, 1), rB, bcol + HALF, t + 2);
;       WAIT_V(10); BAR; MMA(1, 1, At, B1); BAR;
;       LDB(B0, 1, 0); SCHED; LDA(At, 1, 0); STAGE(SA(0, 1), rA, brow + HALF, t + 2);
.LBB0_231:
	ds_read_b128 v[130:133], v138
	ds_read_b128 v[146:149], v138 offset:1024
	ds_read_b128 v[150:153], v138 offset:2048
	ds_read_b128 v[154:157], v138 offset:3072
	s_add_i32 s78, s70, s75
	s_mov_b32 m0, s48
	s_add_i32 s26, s78, 0x4000
	ds_read_b128 v[162:165], v139
	ds_read_b128 v[166:169], v139 offset:1024
	ds_read_b128 v[170:173], v140
	ds_read_b128 v[176:179], v140 offset:1024
	ds_read_b128 v[180:183], v141
	ds_read_b128 v[184:187], v141 offset:1024
	ds_read_b128 v[188:191], v142
	ds_read_b128 v[192:195], v142 offset:1024
	buffer_load_dwordx4 v134, s[0:3], s26 offen lds
	s_mov_b32 m0, s49
	s_add_i32 s26, s78, 0x6000
	buffer_load_dwordx4 v134, s[0:3], s26 offen lds
	s_waitcnt vmcnt(10)
	s_waitcnt lgkmcnt(8)
	s_barrier
	s_waitcnt lgkmcnt(0)
	v_mfma_f32_16x16x32_bf16 v[124:127], v[130:133], v[162:165], v[124:127]
	v_mfma_f32_16x16x32_bf16 v[120:123], v[150:153], v[162:165], v[120:123]
	v_mfma_f32_16x16x32_bf16 v[116:119], v[130:133], v[170:173], v[116:119]
	v_mfma_f32_16x16x32_bf16 v[112:115], v[150:153], v[170:173], v[112:115]
	v_mfma_f32_16x16x32_bf16 v[108:111], v[130:133], v[180:183], v[108:111]
	v_mfma_f32_16x16x32_bf16 v[104:107], v[150:153], v[180:183], v[104:107]
	v_mfma_f32_16x16x32_bf16 v[100:103], v[130:133], v[188:191], v[100:103]
	v_mfma_f32_16x16x32_bf16 v[96:99], v[150:153], v[188:191], v[96:99]
	v_mfma_f32_16x16x32_bf16 v[124:127], v[146:149], v[166:169], v[124:127]
	v_mfma_f32_16x16x32_bf16 v[120:123], v[154:157], v[166:169], v[120:123]
	v_mfma_f32_16x16x32_bf16 v[116:119], v[146:149], v[176:179], v[116:119]
	v_mfma_f32_16x16x32_bf16 v[112:115], v[154:157], v[176:179], v[112:115]
	v_mfma_f32_16x16x32_bf16 v[108:111], v[146:149], v[184:187], v[108:111]
	v_mfma_f32_16x16x32_bf16 v[104:107], v[154:157], v[184:187], v[104:107]
	v_mfma_f32_16x16x32_bf16 v[100:103], v[146:149], v[192:195], v[100:103]
	v_mfma_f32_16x16x32_bf16 v[96:99], v[154:157], v[192:195], v[96:99]
	s_barrier
	s_add_i32 s79, s73, s75
	s_mov_b32 m0, s52
	s_add_i32 s80, s79, 0x8000
	s_mov_b32 s26, s2
	s_mov_b32 s27, s3
	ds_read_b128 v[196:199], v143
	ds_read_b128 v[200:203], v143 offset:1024
	ds_read_b128 v[204:207], v143 offset:2048
	ds_read_b128 v[208:211], v143 offset:3072
	buffer_load_dwordx4 v134, s[24:27], s80 offen lds
	s_mov_b32 m0, s53
	s_add_i32 s80, s79, 0xa000
	buffer_load_dwordx4 v134, s[24:27], s80 offen lds
	s_waitcnt vmcnt(10)
	s_barrier
	s_waitcnt lgkmcnt(0)
	v_mfma_f32_16x16x32_bf16 v[92:95], v[196:199], v[162:165], v[92:95]
	v_mfma_f32_16x16x32_bf16 v[88:91], v[204:207], v[162:165], v[88:91]
	v_mfma_f32_16x16x32_bf16 v[84:87], v[196:199], v[170:173], v[84:87]
	v_mfma_f32_16x16x32_bf16 v[80:83], v[204:207], v[170:173], v[80:83]
	v_mfma_f32_16x16x32_bf16 v[76:79], v[196:199], v[180:183], v[76:79]
	v_mfma_f32_16x16x32_bf16 v[72:75], v[204:207], v[180:183], v[72:75]
	v_mfma_f32_16x16x32_bf16 v[68:71], v[196:199], v[188:191], v[68:71]
	v_mfma_f32_16x16x32_bf16 v[64:67], v[204:207], v[188:191], v[64:67]
	v_mfma_f32_16x16x32_bf16 v[92:95], v[200:203], v[166:169], v[92:95]
	v_mfma_f32_16x16x32_bf16 v[88:91], v[208:211], v[166:169], v[88:91]
	v_mfma_f32_16x16x32_bf16 v[84:87], v[200:203], v[176:179], v[84:87]
	v_mfma_f32_16x16x32_bf16 v[80:83], v[208:211], v[176:179], v[80:83]
	v_mfma_f32_16x16x32_bf16 v[76:79], v[200:203], v[184:187], v[76:79]
	v_mfma_f32_16x16x32_bf16 v[72:75], v[208:211], v[184:187], v[72:75]
	v_mfma_f32_16x16x32_bf16 v[68:71], v[200:203], v[192:195], v[68:71]
	v_mfma_f32_16x16x32_bf16 v[64:67], v[208:211], v[192:195], v[64:67]
	s_add_i32 s80, s72, s75
	s_mov_b32 m0, s43
	s_add_i32 s81, s80, 0x8000
	s_barrier
	ds_read_b128 v[162:165], v139 offset:16384
	ds_read_b128 v[166:169], v139 offset:17408
	ds_read_b128 v[170:173], v140 offset:16384
	ds_read_b128 v[176:179], v140 offset:17408
	ds_read_b128 v[180:183], v141 offset:16384
	ds_read_b128 v[184:187], v141 offset:17408
	ds_read_b128 v[188:191], v142 offset:16384
	ds_read_b128 v[192:195], v142 offset:17408
	buffer_load_dwordx4 v134, s[0:3], s81 offen lds
	s_mov_b32 m0, s54
	s_add_i32 s81, s80, 0xa000
	buffer_load_dwordx4 v134, s[0:3], s81 offen lds
	s_barrier
	s_waitcnt lgkmcnt(0)
	v_mfma_f32_16x16x32_bf16 v[60:63], v[130:133], v[162:165], v[60:63]
	v_mfma_f32_16x16x32_bf16 v[56:59], v[150:153], v[162:165], v[56:59]
	v_mfma_f32_16x16x32_bf16 v[52:55], v[130:133], v[170:173], v[52:55]
	v_mfma_f32_16x16x32_bf16 v[48:51], v[150:153], v[170:173], v[48:51]
	v_mfma_f32_16x16x32_bf16 v[44:47], v[130:133], v[180:183], v[44:47]
	v_mfma_f32_16x16x32_bf16 v[40:43], v[150:153], v[180:183], v[40:43]
	v_mfma_f32_16x16x32_bf16 v[36:39], v[130:133], v[188:191], v[36:39]
	v_mfma_f32_16x16x32_bf16 v[32:35], v[150:153], v[188:191], v[32:35]
	v_mfma_f32_16x16x32_bf16 v[60:63], v[146:149], v[166:169], v[60:63]
	v_mfma_f32_16x16x32_bf16 v[56:59], v[154:157], v[166:169], v[56:59]
	v_mfma_f32_16x16x32_bf16 v[52:55], v[146:149], v[176:179], v[52:55]
	v_mfma_f32_16x16x32_bf16 v[48:51], v[154:157], v[176:179], v[48:51]
	v_mfma_f32_16x16x32_bf16 v[44:47], v[146:149], v[184:187], v[44:47]
	v_mfma_f32_16x16x32_bf16 v[40:43], v[154:157], v[184:187], v[40:43]
	v_mfma_f32_16x16x32_bf16 v[36:39], v[146:149], v[192:195], v[36:39]
	v_mfma_f32_16x16x32_bf16 v[32:35], v[154:157], v[192:195], v[32:35]
	s_barrier
	s_add_i32 s81, s71, s75
	s_mov_b32 m0, s55
	s_add_i32 s82, s81, 0x8000
	buffer_load_dwordx4 v134, s[24:27], s82 offen lds
	s_mov_b32 m0, s56
	s_add_i32 s82, s81, 0xa000
	buffer_load_dwordx4 v134, s[24:27], s82 offen lds
	s_waitcnt vmcnt(10)
	s_barrier
; #define LDA(dst, b, h)                                                                                               \
;   _Pragma("unroll") for (int m = 0; m < 4; ++m) _Pragma("unroll") for (int k = 0; k < 2; ++k) dst[m][k] =            \
;       *reinterpret_cast<const bf16x8*>(SA(b, h) + lds_byte(wr * 64 + m * 16 + fr, k * 32 + fq * 8))
; #define LDB(dst, b, h)                                                                                               \
;   _Pragma("unroll") for (int n = 0; n < 2; ++n) _Pragma("unroll") for (int k = 0; k < 2; ++k) dst[n][k] =            \
;       *reinterpret_cast<const bf16x8*>(SB(b, h) + lds_byte(wc * 32 + n * 16 + fr, k * 32 + fq * 8))
; #define WAIT_V(n) asm volatile("s_waitcnt vmcnt(" #n ")" ::: "memory")
; #define WAIT_L(n) asm volatile("s_waitcnt lgkmcnt(" #n ")" ::: "memory")
; #define BAR __builtin_amdgcn_s_barrier()
; #define SCHED __builtin_amdgcn_sched_barrier(0)
; template <int EPI>
; __device__ __forceinline__ void gemm_phase(const u16* __restrict__ A, const u16* __restrict__ Bt, const int K,
;                                            const int nN, char* shm, const EpiArgs& ea) {
;     ...
;       LDB(B0, 1, 0); SCHED; LDA(At, 1, 0); STAGE(SA(0, 1), rA, brow + HALF, t + 2);
;       WAIT_V(10); WAIT_L(8); BAR; WAIT_L(0); MMA(0, 0, At, B0); BAR; SCHED;
;       LDB(B1, 1, 1); STAGE(SB(1, 0), rB, bcol, t + 3);
;       WAIT_V(10); BAR; WAIT_L(0); MMA(0, 1, At, B1); BAR;
;       LDA(At, 1, 1); STAGE(SA(1, 0), rA, brow, t + 3);
;       BAR; WAIT_L(0); MMA(1, 0, At, B0); BAR; SCHED;
;       STAGE(SB(1, 1), rB, bcol + HALF, t + 3);
	v_mfma_f32_16x16x32_bf16 v[28:31], v[196:199], v[162:165], v[28:31]
	v_mfma_f32_16x16x32_bf16 v[24:27], v[204:207], v[162:165], v[24:27]
	v_mfma_f32_16x16x32_bf16 v[20:23], v[196:199], v[170:173], v[20:23]
	v_mfma_f32_16x16x32_bf16 v[16:19], v[204:207], v[170:173], v[16:19]
	v_mfma_f32_16x16x32_bf16 v[12:15], v[196:199], v[180:183], v[12:15]
	v_mfma_f32_16x16x32_bf16 v[8:11], v[204:207], v[180:183], v[8:11]
	v_mfma_f32_16x16x32_bf16 v[4:7], v[196:199], v[188:191], v[4:7]
	v_mfma_f32_16x16x32_bf16 v[0:3], v[204:207], v[188:191], v[0:3]
	v_mfma_f32_16x16x32_bf16 v[28:31], v[200:203], v[166:169], v[28:31]
	v_mfma_f32_16x16x32_bf16 v[24:27], v[208:211], v[166:169], v[24:27]
	v_mfma_f32_16x16x32_bf16 v[20:23], v[200:203], v[176:179], v[20:23]
	v_mfma_f32_16x16x32_bf16 v[16:19], v[208:211], v[176:179], v[16:19]
	v_mfma_f32_16x16x32_bf16 v[12:15], v[200:203], v[184:187], v[12:15]
	v_mfma_f32_16x16x32_bf16 v[8:11], v[208:211], v[184:187], v[8:11]
	v_mfma_f32_16x16x32_bf16 v[4:7], v[200:203], v[192:195], v[4:7]
	v_mfma_f32_16x16x32_bf16 v[0:3], v[208:211], v[192:195], v[0:3]
	s_barrier
	ds_read_b128 v[130:133], v144
	ds_read_b128 v[146:149], v144 offset:1024
	ds_read_b128 v[150:153], v144 offset:2048
	ds_read_b128 v[154:157], v144 offset:3072
	s_mov_b32 m0, s57
	s_add_i32 s82, s78, 0x8000
	ds_read_b128 v[162:165], v139 offset:32768
	ds_read_b128 v[166:169], v139 offset:33792
	ds_read_b128 v[170:173], v140 offset:32768
	ds_read_b128 v[176:179], v140 offset:33792
	ds_read_b128 v[180:183], v141 offset:32768
	ds_read_b128 v[184:187], v141 offset:33792
	ds_read_b128 v[188:191], v142 offset:32768
	ds_read_b128 v[192:195], v142 offset:33792
	buffer_load_dwordx4 v134, s[0:3], s82 offen lds
	s_mov_b32 m0, s58
	s_add_i32 s78, s78, 0xa000
	buffer_load_dwordx4 v134, s[0:3], s78 offen lds
	s_waitcnt vmcnt(10)
	s_waitcnt lgkmcnt(8)
	s_barrier
	s_waitcnt lgkmcnt(0)
	v_mfma_f32_16x16x32_bf16 v[124:127], v[130:133], v[162:165], v[124:127]
	v_mfma_f32_16x16x32_bf16 v[120:123], v[150:153], v[162:165], v[120:123]
	v_mfma_f32_16x16x32_bf16 v[116:119], v[130:133], v[170:173], v[116:119]
	v_mfma_f32_16x16x32_bf16 v[112:115], v[150:153], v[170:173], v[112:115]
	v_mfma_f32_16x16x32_bf16 v[108:111], v[130:133], v[180:183], v[108:111]
	v_mfma_f32_16x16x32_bf16 v[104:107], v[150:153], v[180:183], v[104:107]
	v_mfma_f32_16x16x32_bf16 v[100:103], v[130:133], v[188:191], v[100:103]
	v_mfma_f32_16x16x32_bf16 v[96:99], v[150:153], v[188:191], v[96:99]
	v_mfma_f32_16x16x32_bf16 v[124:127], v[146:149], v[166:169], v[124:127]
	v_mfma_f32_16x16x32_bf16 v[120:123], v[154:157], v[166:169], v[120:123]
	v_mfma_f32_16x16x32_bf16 v[116:119], v[146:149], v[176:179], v[116:119]
	v_mfma_f32_16x16x32_bf16 v[112:115], v[154:157], v[176:179], v[112:115]
	v_mfma_f32_16x16x32_bf16 v[108:111], v[146:149], v[184:187], v[108:111]
	v_mfma_f32_16x16x32_bf16 v[104:107], v[154:157], v[184:187], v[104:107]
	v_mfma_f32_16x16x32_bf16 v[100:103], v[146:149], v[192:195], v[100:103]
	v_mfma_f32_16x16x32_bf16 v[96:99], v[154:157], v[192:195], v[96:99]
	s_barrier
	s_mov_b32 m0, s59
	s_add_i32 s78, s79, 0xc000
	ds_read_b128 v[196:199], v145
	ds_read_b128 v[200:203], v145 offset:1024
	ds_read_b128 v[204:207], v145 offset:2048
	ds_read_b128 v[208:211], v145 offset:3072
	buffer_load_dwordx4 v134, s[24:27], s78 offen lds
	s_mov_b32 m0, s60
	s_add_i32 s79, s79, 0xe000
	buffer_load_dwordx4 v134, s[24:27], s79 offen lds
	s_waitcnt vmcnt(10)
	s_barrier
	s_waitcnt lgkmcnt(0)
	v_mfma_f32_16x16x32_bf16 v[92:95], v[196:199], v[162:165], v[92:95]
	v_mfma_f32_16x16x32_bf16 v[88:91], v[204:207], v[162:165], v[88:91]
	v_mfma_f32_16x16x32_bf16 v[84:87], v[196:199], v[170:173], v[84:87]
	v_mfma_f32_16x16x32_bf16 v[80:83], v[204:207], v[170:173], v[80:83]
	v_mfma_f32_16x16x32_bf16 v[76:79], v[196:199], v[180:183], v[76:79]
	v_mfma_f32_16x16x32_bf16 v[72:75], v[204:207], v[180:183], v[72:75]
	v_mfma_f32_16x16x32_bf16 v[68:71], v[196:199], v[188:191], v[68:71]
	v_mfma_f32_16x16x32_bf16 v[64:67], v[204:207], v[188:191], v[64:67]
	v_mfma_f32_16x16x32_bf16 v[92:95], v[200:203], v[166:169], v[92:95]
	v_mfma_f32_16x16x32_bf16 v[88:91], v[208:211], v[166:169], v[88:91]
	v_mfma_f32_16x16x32_bf16 v[84:87], v[200:203], v[176:179], v[84:87]
	v_mfma_f32_16x16x32_bf16 v[80:83], v[208:211], v[176:179], v[80:83]
	v_mfma_f32_16x16x32_bf16 v[76:79], v[200:203], v[184:187], v[76:79]
	v_mfma_f32_16x16x32_bf16 v[72:75], v[208:211], v[184:187], v[72:75]
	v_mfma_f32_16x16x32_bf16 v[68:71], v[200:203], v[192:195], v[68:71]
	v_mfma_f32_16x16x32_bf16 v[64:67], v[208:211], v[192:195], v[64:67]
	s_mov_b32 m0, s61
	s_add_i32 s78, s80, 0xc000
	s_barrier
	ds_read_b128 v[162:165], v139 offset:49152
	ds_read_b128 v[166:169], v139 offset:50176
	ds_read_b128 v[170:173], v140 offset:49152
	ds_read_b128 v[176:179], v140 offset:50176
	ds_read_b128 v[180:183], v141 offset:49152
	ds_read_b128 v[184:187], v141 offset:50176
	ds_read_b128 v[188:191], v142 offset:49152
	ds_read_b128 v[192:195], v142 offset:50176
	buffer_load_dwordx4 v134, s[0:3], s78 offen lds
	s_mov_b32 m0, s62
	s_add_i32 s80, s80, 0xe000
	buffer_load_dwordx4 v134, s[0:3], s80 offen lds
	s_barrier
; #define LDA(dst, b, h)                                                                                               \
;   _Pragma("unroll") for (int m = 0; m < 4; ++m) _Pragma("unroll") for (int k = 0; k < 2; ++k) dst[m][k] =            \
;       *reinterpret_cast<const bf16x8*>(SA(b, h) + lds_byte(wr * 64 + m * 16 + fr, k * 32 + fq * 8))
; #define LDB(dst, b, h)                                                                                               \
;   _Pragma("unroll") for (int n = 0; n < 2; ++n) _Pragma("unroll") for (int k = 0; k < 2; ++k) dst[n][k] =            \
;       *reinterpret_cast<const bf16x8*>(SB(b, h) + lds_byte(wc * 32 + n * 16 + fr, k * 32 + fq * 8))
; #define WAIT_V(n) asm volatile("s_waitcnt vmcnt(" #n ")" ::: "memory")
; #define WAIT_L(n) asm volatile("s_waitcnt lgkmcnt(" #n ")" ::: "memory")
; #define BAR __builtin_amdgcn_s_barrier()
; #define SCHED __builtin_amdgcn_sched_barrier(0)
; template <int EPI>
; __device__ __forceinline__ void gemm_phase(const u16* __restrict__ A, const u16* __restrict__ Bt, const int K,
;                                            const int nN, char* shm, const EpiArgs& ea) {
;     ...
;       BAR; WAIT_L(0); MMA(1, 0, At, B0); BAR; SCHED;
;       STAGE(SB(1, 1), rB, bcol + HALF, t + 3);
;       WAIT_V(10); BAR; MMA(1, 1, At, B1); BAR;
;     }
;     float eC = 0.f, eB = 0.f;
;     float2 eS = make_float2(0.f, 0.f);
;     if (EPI == EPI_IN || EPI == EPI_SWIGLU_LN) {
;       if (wr == 0) {
;         eC = ea.c1[bcol + tid];
;         eS = *(const float2*)(ea.st_in + (size_t)(brow + tid) * 2);
;       } else {
;         eC = ea.c2[bcol + tid - 256];
;         if (EPI == EPI_IN) eB = ea.bias[bcol + tid - 256];
;       }
;     }
;     {
;       LDB(B0, 0, 0); LDA(At, 0, 0); STAGE(SA(1, 1), rA, brow + HALF, nt - 1);
;       WAIT_V(10); BAR; WAIT_L(0); MMA(0, 0, At, B0); BAR;
;       LDB(B1, 0, 1); WAIT_V(8); BAR; WAIT_L(0); MMA(0, 1, At, B1); BAR;
;       LDA(At, 0, 1); WAIT_V(4); BAR; WAIT_L(0); MMA(1, 0, At, B0); MMA(1, 1, At, B1); BAR;
;     }
;     {
;       LDB(B0, 1, 0); LDA(At, 1, 0); WAIT_V(2); BAR; WAIT_L(0); MMA(0, 0, At, B0); BAR;
	s_waitcnt lgkmcnt(0)
	v_mfma_f32_16x16x32_bf16 v[60:63], v[130:133], v[162:165], v[60:63]
	v_mfma_f32_16x16x32_bf16 v[56:59], v[150:153], v[162:165], v[56:59]
	v_mfma_f32_16x16x32_bf16 v[52:55], v[130:133], v[170:173], v[52:55]
	v_mfma_f32_16x16x32_bf16 v[48:51], v[150:153], v[170:173], v[48:51]
	v_mfma_f32_16x16x32_bf16 v[44:47], v[130:133], v[180:183], v[44:47]
	v_mfma_f32_16x16x32_bf16 v[40:43], v[150:153], v[180:183], v[40:43]
	v_mfma_f32_16x16x32_bf16 v[36:39], v[130:133], v[188:191], v[36:39]
	v_mfma_f32_16x16x32_bf16 v[32:35], v[150:153], v[188:191], v[32:35]
	v_mfma_f32_16x16x32_bf16 v[60:63], v[146:149], v[166:169], v[60:63]
	v_mfma_f32_16x16x32_bf16 v[56:59], v[154:157], v[166:169], v[56:59]
	v_mfma_f32_16x16x32_bf16 v[52:55], v[146:149], v[176:179], v[52:55]
	v_mfma_f32_16x16x32_bf16 v[48:51], v[154:157], v[176:179], v[48:51]
	v_mfma_f32_16x16x32_bf16 v[44:47], v[146:149], v[184:187], v[44:47]
	v_mfma_f32_16x16x32_bf16 v[40:43], v[154:157], v[184:187], v[40:43]
	v_mfma_f32_16x16x32_bf16 v[36:39], v[146:149], v[192:195], v[36:39]
	v_mfma_f32_16x16x32_bf16 v[32:35], v[154:157], v[192:195], v[32:35]
	s_barrier
	s_mov_b32 m0, s63
	s_add_i32 s78, s81, 0xc000
	buffer_load_dwordx4 v134, s[24:27], s78 offen lds
	s_mov_b32 m0, s64
	s_add_i32 s81, s81, 0xe000
	buffer_load_dwordx4 v134, s[24:27], s81 offen lds
	s_waitcnt vmcnt(10)
	s_barrier
	v_mfma_f32_16x16x32_bf16 v[28:31], v[196:199], v[162:165], v[28:31]
	v_mfma_f32_16x16x32_bf16 v[24:27], v[204:207], v[162:165], v[24:27]
	v_mfma_f32_16x16x32_bf16 v[20:23], v[196:199], v[170:173], v[20:23]
	v_mfma_f32_16x16x32_bf16 v[16:19], v[204:207], v[170:173], v[16:19]
	v_mfma_f32_16x16x32_bf16 v[12:15], v[196:199], v[180:183], v[12:15]
	v_mfma_f32_16x16x32_bf16 v[8:11], v[204:207], v[180:183], v[8:11]
	v_mfma_f32_16x16x32_bf16 v[4:7], v[196:199], v[188:191], v[4:7]
	v_mfma_f32_16x16x32_bf16 v[0:3], v[204:207], v[188:191], v[0:3]
	v_mfma_f32_16x16x32_bf16 v[28:31], v[200:203], v[166:169], v[28:31]
	v_mfma_f32_16x16x32_bf16 v[24:27], v[208:211], v[166:169], v[24:27]
	v_mfma_f32_16x16x32_bf16 v[20:23], v[200:203], v[176:179], v[20:23]
	v_mfma_f32_16x16x32_bf16 v[16:19], v[208:211], v[176:179], v[16:19]
	v_mfma_f32_16x16x32_bf16 v[12:15], v[200:203], v[184:187], v[12:15]
	v_mfma_f32_16x16x32_bf16 v[8:11], v[208:211], v[184:187], v[8:11]
	v_mfma_f32_16x16x32_bf16 v[4:7], v[200:203], v[192:195], v[4:7]
	v_mfma_f32_16x16x32_bf16 v[0:3], v[208:211], v[192:195], v[0:3]
	s_add_i32 s74, s74, 2
	s_add_i32 s75, s75, 0x8000
	s_cmpk_lt_u32 s74, 0x54
	s_barrier
	s_cbranch_scc1 .LBB0_231
	s_mov_b32 m0, s48
	s_add_i32 s26, s70, 0x15c000
	ds_read_b128 v[130:133], v138
	ds_read_b128 v[146:149], v138 offset:1024
	ds_read_b128 v[150:153], v138 offset:2048
	ds_read_b128 v[154:157], v138 offset:3072
	ds_read_b128 v[162:165], v139
	ds_read_b128 v[166:169], v139 offset:1024
	ds_read_b128 v[170:173], v140
	ds_read_b128 v[176:179], v140 offset:1024
	ds_read_b128 v[180:183], v141
	ds_read_b128 v[184:187], v141 offset:1024
	ds_read_b128 v[188:191], v142
	ds_read_b128 v[192:195], v142 offset:1024
	buffer_load_dwordx4 v134, s[0:3], s26 offen lds
	s_mov_b32 m0, s49
	s_add_i32 s70, s70, 0x15e000
	buffer_load_dwordx4 v134, s[0:3], s70 offen lds
	s_waitcnt vmcnt(10)
	s_barrier
	s_waitcnt lgkmcnt(0)
	v_mfma_f32_16x16x32_bf16 v[124:127], v[130:133], v[162:165], v[124:127]
	v_mfma_f32_16x16x32_bf16 v[116:119], v[130:133], v[170:173], v[116:119]
	v_mfma_f32_16x16x32_bf16 v[112:115], v[150:153], v[170:173], v[112:115]
	v_mfma_f32_16x16x32_bf16 v[100:103], v[130:133], v[188:191], v[100:103]
	v_mfma_f32_16x16x32_bf16 v[96:99], v[150:153], v[188:191], v[96:99]
	v_mfma_f32_16x16x32_bf16 v[124:127], v[146:149], v[166:169], v[124:127]
	v_mfma_f32_16x16x32_bf16 v[120:123], v[150:153], v[162:165], v[120:123]
	v_mfma_f32_16x16x32_bf16 v[116:119], v[146:149], v[176:179], v[116:119]
	v_mfma_f32_16x16x32_bf16 v[112:115], v[154:157], v[176:179], v[112:115]
	v_mfma_f32_16x16x32_bf16 v[108:111], v[130:133], v[180:183], v[108:111]
	v_mfma_f32_16x16x32_bf16 v[104:107], v[150:153], v[180:183], v[104:107]
	v_mfma_f32_16x16x32_bf16 v[100:103], v[146:149], v[192:195], v[100:103]
	v_mfma_f32_16x16x32_bf16 v[96:99], v[154:157], v[192:195], v[96:99]
	v_mfma_f32_16x16x32_bf16 v[196:199], v[154:157], v[166:169], v[120:123]
	v_mfma_f32_16x16x32_bf16 v[200:203], v[146:149], v[184:187], v[108:111]
	v_mfma_f32_16x16x32_bf16 v[204:207], v[154:157], v[184:187], v[104:107]
	s_barrier
	s_nop 0
	ds_read_b128 v[104:107], v143
	ds_read_b128 v[108:111], v143 offset:1024
	ds_read_b128 v[120:123], v143 offset:2048
	ds_read_b128 v[208:211], v143 offset:3072
	s_waitcnt vmcnt(8)
	s_barrier
	s_waitcnt lgkmcnt(0)
	v_mfma_f32_16x16x32_bf16 v[84:87], v[104:107], v[170:173], v[84:87]
	v_mfma_f32_16x16x32_bf16 v[80:83], v[120:123], v[170:173], v[80:83]
	v_mfma_f32_16x16x32_bf16 v[68:71], v[104:107], v[188:191], v[68:71]
	v_mfma_f32_16x16x32_bf16 v[92:95], v[104:107], v[162:165], v[92:95]
	v_mfma_f32_16x16x32_bf16 v[88:91], v[120:123], v[162:165], v[88:91]
	v_mfma_f32_16x16x32_bf16 v[84:87], v[108:111], v[176:179], v[84:87]
	v_mfma_f32_16x16x32_bf16 v[80:83], v[208:211], v[176:179], v[80:83]
	v_mfma_f32_16x16x32_bf16 v[76:79], v[104:107], v[180:183], v[76:79]
	v_mfma_f32_16x16x32_bf16 v[72:75], v[120:123], v[180:183], v[72:75]
	v_mfma_f32_16x16x32_bf16 v[68:71], v[108:111], v[192:195], v[68:71]
	v_mfma_f32_16x16x32_bf16 v[64:67], v[120:123], v[188:191], v[64:67]
	v_mfma_f32_16x16x32_bf16 v[212:215], v[108:111], v[166:169], v[92:95]
	v_mfma_f32_16x16x32_bf16 v[162:165], v[208:211], v[166:169], v[88:91]
	v_mfma_f32_16x16x32_bf16 v[166:169], v[108:111], v[184:187], v[76:79]
	v_mfma_f32_16x16x32_bf16 v[170:173], v[208:211], v[184:187], v[72:75]
	v_mfma_f32_16x16x32_bf16 v[176:179], v[208:211], v[192:195], v[64:67]
	s_barrier
; #define LDA(dst, b, h)                                                                                               \
;   _Pragma("unroll") for (int m = 0; m < 4; ++m) _Pragma("unroll") for (int k = 0; k < 2; ++k) dst[m][k] =            \
;       *reinterpret_cast<const bf16x8*>(SA(b, h) + lds_byte(wr * 64 + m * 16 + fr, k * 32 + fq * 8))
; #define LDB(dst, b, h)                                                                                               \
;   _Pragma("unroll") for (int n = 0; n < 2; ++n) _Pragma("unroll") for (int k = 0; k < 2; ++k) dst[n][k] =            \
;       *reinterpret_cast<const bf16x8*>(SB(b, h) + lds_byte(wc * 32 + n * 16 + fr, k * 32 + fq * 8))
; #define WAIT_V(n) asm volatile("s_waitcnt vmcnt(" #n ")" ::: "memory")
; #define WAIT_L(n) asm volatile("s_waitcnt lgkmcnt(" #n ")" ::: "memory")
; #define BAR __builtin_amdgcn_s_barrier()
; template <int EPI>
; __device__ __forceinline__ void gemm_phase(const u16* __restrict__ A, const u16* __restrict__ Bt, const int K,
;                                            const int nN, char* shm, const EpiArgs& ea) {
;     ...
;       LDA(At, 0, 1); WAIT_V(4); BAR; WAIT_L(0); MMA(1, 0, At, B0); MMA(1, 1, At, B1); BAR;
;     }
;     {
;       LDB(B0, 1, 0); LDA(At, 1, 0); WAIT_V(2); BAR; WAIT_L(0); MMA(0, 0, At, B0); BAR;
;       LDB(B1, 1, 1); WAIT_V(0); BAR; WAIT_L(0); MMA(0, 1, At, B1); BAR;
;       LDA(At, 1, 1); BAR; WAIT_L(0); MMA(1, 0, At, B0); MMA(1, 1, At, B1); BAR;
	s_nop 0
	ds_read_b128 v[64:67], v139 offset:16384
	ds_read_b128 v[72:75], v139 offset:17408
	ds_read_b128 v[76:79], v140 offset:16384
	ds_read_b128 v[88:91], v140 offset:17408
	ds_read_b128 v[92:95], v141 offset:16384
	ds_read_b128 v[180:183], v141 offset:17408
	ds_read_b128 v[184:187], v142 offset:16384
	ds_read_b128 v[188:191], v142 offset:17408
	s_waitcnt vmcnt(4)
	s_barrier
	s_waitcnt lgkmcnt(0)
	v_mfma_f32_16x16x32_bf16 v[60:63], v[130:133], v[64:67], v[60:63]
	v_mfma_f32_16x16x32_bf16 v[52:55], v[130:133], v[76:79], v[52:55]
	v_mfma_f32_16x16x32_bf16 v[48:51], v[150:153], v[76:79], v[48:51]
	v_mfma_f32_16x16x32_bf16 v[36:39], v[130:133], v[184:187], v[36:39]
	v_mfma_f32_16x16x32_bf16 v[32:35], v[150:153], v[184:187], v[32:35]
	v_mfma_f32_16x16x32_bf16 v[60:63], v[146:149], v[72:75], v[60:63]
	v_mfma_f32_16x16x32_bf16 v[56:59], v[150:153], v[64:67], v[56:59]
	v_mfma_f32_16x16x32_bf16 v[52:55], v[146:149], v[88:91], v[52:55]
	v_mfma_f32_16x16x32_bf16 v[48:51], v[154:157], v[88:91], v[48:51]
	v_mfma_f32_16x16x32_bf16 v[44:47], v[130:133], v[92:95], v[44:47]
	v_mfma_f32_16x16x32_bf16 v[40:43], v[150:153], v[92:95], v[40:43]
	v_mfma_f32_16x16x32_bf16 v[36:39], v[146:149], v[188:191], v[36:39]
	v_mfma_f32_16x16x32_bf16 v[32:35], v[154:157], v[188:191], v[32:35]
	v_mfma_f32_16x16x32_bf16 v[192:195], v[154:157], v[72:75], v[56:59]
	v_mfma_f32_16x16x32_bf16 v[216:219], v[146:149], v[180:183], v[44:47]
	v_mfma_f32_16x16x32_bf16 v[220:223], v[154:157], v[180:183], v[40:43]
	v_mfma_f32_16x16x32_bf16 v[20:23], v[104:107], v[76:79], v[20:23]
	v_mfma_f32_16x16x32_bf16 v[16:19], v[120:123], v[76:79], v[16:19]
	v_mfma_f32_16x16x32_bf16 v[4:7], v[104:107], v[184:187], v[4:7]
	v_mfma_f32_16x16x32_bf16 v[28:31], v[104:107], v[64:67], v[28:31]
	v_mfma_f32_16x16x32_bf16 v[24:27], v[120:123], v[64:67], v[24:27]
	v_mfma_f32_16x16x32_bf16 v[20:23], v[108:111], v[88:91], v[20:23]
	v_mfma_f32_16x16x32_bf16 v[16:19], v[208:211], v[88:91], v[16:19]
	v_mfma_f32_16x16x32_bf16 v[12:15], v[104:107], v[92:95], v[12:15]
	v_mfma_f32_16x16x32_bf16 v[8:11], v[120:123], v[92:95], v[8:11]
	v_mfma_f32_16x16x32_bf16 v[4:7], v[108:111], v[188:191], v[4:7]
	v_mfma_f32_16x16x32_bf16 v[0:3], v[120:123], v[184:187], v[0:3]
	v_mfma_f32_16x16x32_bf16 v[130:133], v[108:111], v[72:75], v[28:31]
	v_mfma_f32_16x16x32_bf16 v[146:149], v[208:211], v[72:75], v[24:27]
	v_mfma_f32_16x16x32_bf16 v[150:153], v[108:111], v[180:183], v[12:15]
	v_mfma_f32_16x16x32_bf16 v[154:157], v[208:211], v[180:183], v[8:11]
	v_mfma_f32_16x16x32_bf16 v[180:183], v[208:211], v[188:191], v[0:3]
	s_barrier
	s_nop 0
	ds_read_b128 v[0:3], v144
	ds_read_b128 v[8:11], v144 offset:1024
	ds_read_b128 v[12:15], v144 offset:2048
	ds_read_b128 v[184:187], v144 offset:3072
	ds_read_b128 v[24:27], v139 offset:32768
	ds_read_b128 v[28:31], v139 offset:33792
	ds_read_b128 v[40:43], v140 offset:32768
	ds_read_b128 v[44:47], v140 offset:33792
	ds_read_b128 v[56:59], v141 offset:32768
	ds_read_b128 v[64:67], v141 offset:33792
	ds_read_b128 v[188:191], v142 offset:32768
	ds_read_b128 v[208:211], v142 offset:33792
	s_waitcnt vmcnt(2)
	s_barrier
	s_waitcnt lgkmcnt(0)
	v_mfma_f32_16x16x32_bf16 v[72:75], v[0:3], v[24:27], v[124:127]
	v_mfma_f32_16x16x32_bf16 v[120:123], v[8:11], v[28:31], v[72:75]
	v_mfma_f32_16x16x32_bf16 v[72:75], v[12:15], v[24:27], v[196:199]
	v_mfma_f32_16x16x32_bf16 v[124:127], v[184:187], v[28:31], v[72:75]
	v_mfma_f32_16x16x32_bf16 v[72:75], v[0:3], v[40:43], v[116:119]
	v_mfma_f32_16x16x32_bf16 v[104:107], v[8:11], v[44:47], v[72:75]
	v_mfma_f32_16x16x32_bf16 v[72:75], v[12:15], v[40:43], v[112:115]
	v_mfma_f32_16x16x32_bf16 v[108:111], v[184:187], v[44:47], v[72:75]
	v_mfma_f32_16x16x32_bf16 v[72:75], v[0:3], v[56:59], v[200:203]
	v_mfma_f32_16x16x32_bf16 v[88:91], v[8:11], v[64:67], v[72:75]
	v_mfma_f32_16x16x32_bf16 v[72:75], v[12:15], v[56:59], v[204:207]
	v_mfma_f32_16x16x32_bf16 v[92:95], v[184:187], v[64:67], v[72:75]
	v_mfma_f32_16x16x32_bf16 v[72:75], v[0:3], v[188:191], v[100:103]
	v_mfma_f32_16x16x32_bf16 v[76:79], v[12:15], v[188:191], v[96:99]
	v_mfma_f32_16x16x32_bf16 v[72:75], v[8:11], v[208:211], v[72:75]
	v_mfma_f32_16x16x32_bf16 v[76:79], v[184:187], v[208:211], v[76:79]
	s_barrier
	ds_read_b128 v[196:199], v145
	ds_read_b128 v[200:203], v145 offset:1024
	ds_read_b128 v[204:207], v145 offset:2048
	ds_read_b128 v[224:227], v145 offset:3072
	s_waitcnt vmcnt(0)
	s_barrier
; #define LDA(dst, b, h)                                                                                               \
;   _Pragma("unroll") for (int m = 0; m < 4; ++m) _Pragma("unroll") for (int k = 0; k < 2; ++k) dst[m][k] =            \
;       *reinterpret_cast<const bf16x8*>(SA(b, h) + lds_byte(wr * 64 + m * 16 + fr, k * 32 + fq * 8))
; #define LDB(dst, b, h)                                                                                               \
;   _Pragma("unroll") for (int n = 0; n < 2; ++n) _Pragma("unroll") for (int k = 0; k < 2; ++k) dst[n][k] =            \
;       *reinterpret_cast<const bf16x8*>(SB(b, h) + lds_byte(wc * 32 + n * 16 + fr, k * 32 + fq * 8))
; #define WAIT_V(n) asm volatile("s_waitcnt vmcnt(" #n ")" ::: "memory")
; #define WAIT_L(n) asm volatile("s_waitcnt lgkmcnt(" #n ")" ::: "memory")
; #define BAR __builtin_amdgcn_s_barrier()
; template <int EPI>
; __device__ __forceinline__ void gemm_phase(const u16* __restrict__ A, const u16* __restrict__ Bt, const int K,
;                                            const int nN, char* shm, const EpiArgs& ea) {
;     ...
;       LDB(B0, 1, 0); LDA(At, 1, 0); WAIT_V(2); BAR; WAIT_L(0); MMA(0, 0, At, B0); BAR;
;       LDB(B1, 1, 1); WAIT_V(0); BAR; WAIT_L(0); MMA(0, 1, At, B1); BAR;
;       LDA(At, 1, 1); BAR; WAIT_L(0); MMA(1, 0, At, B0); MMA(1, 1, At, B1); BAR;
;     }
;     if (wr == 0) BAR;
;     if (has_next) STAGE7(brow2, bcol2);
	s_waitcnt lgkmcnt(0)
	v_mfma_f32_16x16x32_bf16 v[96:99], v[196:199], v[24:27], v[212:215]
	v_mfma_f32_16x16x32_bf16 v[24:27], v[204:207], v[24:27], v[162:165]
	v_mfma_f32_16x16x32_bf16 v[116:119], v[224:227], v[28:31], v[24:27]
	v_mfma_f32_16x16x32_bf16 v[24:27], v[196:199], v[40:43], v[84:87]
	v_mfma_f32_16x16x32_bf16 v[112:115], v[200:203], v[28:31], v[96:99]
	v_mfma_f32_16x16x32_bf16 v[96:99], v[200:203], v[44:47], v[24:27]
	v_mfma_f32_16x16x32_bf16 v[24:27], v[204:207], v[40:43], v[80:83]
	v_mfma_f32_16x16x32_bf16 v[100:103], v[224:227], v[44:47], v[24:27]
	v_mfma_f32_16x16x32_bf16 v[24:27], v[196:199], v[56:59], v[166:169]
	v_mfma_f32_16x16x32_bf16 v[80:83], v[200:203], v[64:67], v[24:27]
	v_mfma_f32_16x16x32_bf16 v[24:27], v[204:207], v[56:59], v[170:173]
	v_mfma_f32_16x16x32_bf16 v[84:87], v[224:227], v[64:67], v[24:27]
	v_mfma_f32_16x16x32_bf16 v[24:27], v[196:199], v[188:191], v[68:71]
	v_mfma_f32_16x16x32_bf16 v[64:67], v[200:203], v[208:211], v[24:27]
	v_mfma_f32_16x16x32_bf16 v[24:27], v[204:207], v[188:191], v[176:179]
	v_mfma_f32_16x16x32_bf16 v[68:71], v[224:227], v[208:211], v[24:27]
	s_barrier
	ds_read_b128 v[162:165], v139 offset:49152
	ds_read_b128 v[166:169], v139 offset:50176
	ds_read_b128 v[170:173], v140 offset:49152
	ds_read_b128 v[176:179], v140 offset:50176
	ds_read_b128 v[188:191], v141 offset:49152
	ds_read_b128 v[208:211], v141 offset:50176
	ds_read_b128 v[212:215], v142 offset:49152
	ds_read_b128 v[228:231], v142 offset:50176
	s_barrier
	s_waitcnt lgkmcnt(0)
	v_mfma_f32_16x16x32_bf16 v[24:27], v[0:3], v[162:165], v[60:63]
	v_mfma_f32_16x16x32_bf16 v[56:59], v[8:11], v[166:169], v[24:27]
	v_mfma_f32_16x16x32_bf16 v[24:27], v[12:15], v[162:165], v[192:195]
	v_mfma_f32_16x16x32_bf16 v[60:63], v[184:187], v[166:169], v[24:27]
	v_mfma_f32_16x16x32_bf16 v[24:27], v[0:3], v[170:173], v[52:55]
	v_mfma_f32_16x16x32_bf16 v[40:43], v[8:11], v[176:179], v[24:27]
	v_mfma_f32_16x16x32_bf16 v[24:27], v[12:15], v[170:173], v[48:51]
	v_mfma_f32_16x16x32_bf16 v[44:47], v[184:187], v[176:179], v[24:27]
	v_mfma_f32_16x16x32_bf16 v[24:27], v[0:3], v[188:191], v[216:219]
	v_mfma_f32_16x16x32_bf16 v[0:3], v[0:3], v[212:215], v[36:39]
	v_mfma_f32_16x16x32_bf16 v[24:27], v[8:11], v[208:211], v[24:27]
	v_mfma_f32_16x16x32_bf16 v[28:31], v[12:15], v[188:191], v[220:223]
	v_mfma_f32_16x16x32_bf16 v[8:11], v[8:11], v[228:231], v[0:3]
	v_mfma_f32_16x16x32_bf16 v[0:3], v[12:15], v[212:215], v[32:35]
	v_mfma_f32_16x16x32_bf16 v[28:31], v[184:187], v[208:211], v[28:31]
	v_mfma_f32_16x16x32_bf16 v[12:15], v[184:187], v[228:231], v[0:3]
	v_mfma_f32_16x16x32_bf16 v[0:3], v[196:199], v[162:165], v[130:133]
	v_mfma_f32_16x16x32_bf16 v[48:51], v[200:203], v[166:169], v[0:3]
	v_mfma_f32_16x16x32_bf16 v[0:3], v[204:207], v[162:165], v[146:149]
	v_mfma_f32_16x16x32_bf16 v[52:55], v[224:227], v[166:169], v[0:3]
	v_mfma_f32_16x16x32_bf16 v[0:3], v[196:199], v[170:173], v[20:23]
	v_mfma_f32_16x16x32_bf16 v[32:35], v[200:203], v[176:179], v[0:3]
	v_mfma_f32_16x16x32_bf16 v[0:3], v[204:207], v[170:173], v[16:19]
	v_mfma_f32_16x16x32_bf16 v[36:39], v[224:227], v[176:179], v[0:3]
	v_mfma_f32_16x16x32_bf16 v[0:3], v[196:199], v[188:191], v[150:153]
	v_mfma_f32_16x16x32_bf16 v[16:19], v[200:203], v[208:211], v[0:3]
	v_mfma_f32_16x16x32_bf16 v[0:3], v[204:207], v[188:191], v[154:157]
	v_mfma_f32_16x16x32_bf16 v[20:23], v[224:227], v[208:211], v[0:3]
	v_mfma_f32_16x16x32_bf16 v[0:3], v[196:199], v[212:215], v[4:7]
	v_mfma_f32_16x16x32_bf16 v[4:7], v[204:207], v[212:215], v[180:183]
	v_mfma_f32_16x16x32_bf16 v[0:3], v[200:203], v[228:231], v[0:3]
	v_mfma_f32_16x16x32_bf16 v[4:7], v[224:227], v[228:231], v[4:7]
	s_andn2_b64 vcc, exec, s[30:31]
	s_barrier
	s_cbranch_vccnz .LBB0_234
	s_barrier
.LBB0_234:
	s_andn2_b64 vcc, exec, s[40:41]
	s_cbranch_vccnz .LBB0_236
	s_lshr_b32 s26, s67, 7
	s_mov_b32 m0, s52
	s_mul_i32 s40, s26, 0x164000
	s_mov_b32 s26, s2
	s_mov_b32 s27, s3
	buffer_load_dwordx4 v134, s[24:27], s40 offen lds
	s_mov_b32 m0, s53
	s_or_b32 s41, s40, 0x2000
	buffer_load_dwordx4 v134, s[24:27], s41 offen lds
	s_lshr_b32 s41, s68, 7
	s_mul_i32 s41, s41, 0x164000
	s_mov_b32 m0, s43
	s_or_b32 s70, s41, 0x2000
	buffer_load_dwordx4 v134, s[0:3], s41 offen lds
	s_mov_b32 m0, s54
	s_nop 0
	buffer_load_dwordx4 v134, s[0:3], s70 offen lds
	s_mov_b32 m0, s55
	s_add_i32 s70, s40, 0x164000
	buffer_load_dwordx4 v134, s[24:27], s70 offen lds
	s_mov_b32 m0, s56
	s_add_i32 s70, s40, 0x166000
	buffer_load_dwordx4 v134, s[24:27], s70 offen lds
	s_mov_b32 m0, s57
	s_add_i32 s70, s41, 0x164000
	buffer_load_dwordx4 v134, s[0:3], s70 offen lds
	s_mov_b32 m0, s58
	s_add_i32 s70, s41, 0x166000
	buffer_load_dwordx4 v134, s[0:3], s70 offen lds
	s_mov_b32 m0, s59
	s_or_b32 s70, s40, 0x4000
	buffer_load_dwordx4 v134, s[24:27], s70 offen lds
	s_mov_b32 m0, s60
	s_or_b32 s70, s40, 0x6000
	buffer_load_dwordx4 v134, s[24:27], s70 offen lds
	s_or_b32 s70, s41, 0x4000
	s_mov_b32 m0, s61
	s_or_b32 s41, s41, 0x6000
	buffer_load_dwordx4 v134, s[0:3], s70 offen lds
	s_mov_b32 m0, s62
	s_nop 0
	buffer_load_dwordx4 v134, s[0:3], s41 offen lds
	s_add_i32 s41, s40, 0x168000
	s_mov_b32 m0, s63
	s_add_i32 s40, s40, 0x16a000
	buffer_load_dwordx4 v134, s[24:27], s41 offen lds
	s_mov_b32 m0, s64
	s_nop 0
	buffer_load_dwordx4 v134, s[24:27], s40 offen lds

; #define LDA(dst, b, h)                                                                                               \
;   _Pragma("unroll") for (int m = 0; m < 4; ++m) _Pragma("unroll") for (int k = 0; k < 2; ++k) dst[m][k] =            \
;       *reinterpret_cast<const bf16x8*>(SA(b, h) + lds_byte(wr * 64 + m * 16 + fr, k * 32 + fq * 8))
; #define LDB(dst, b, h)                                                                                               \
;   _Pragma("unroll") for (int n = 0; n < 2; ++n) _Pragma("unroll") for (int k = 0; k < 2; ++k) dst[n][k] =            \
;       *reinterpret_cast<const bf16x8*>(SB(b, h) + lds_byte(wc * 32 + n * 16 + fr, k * 32 + fq * 8))
; #define WAIT_V(n) asm volatile("s_waitcnt vmcnt(" #n ")" ::: "memory")
; #define WAIT_L(n) asm volatile("s_waitcnt lgkmcnt(" #n ")" ::: "memory")
; #define BAR __builtin_amdgcn_s_barrier()
; #define SCHED __builtin_amdgcn_sched_barrier(0)
; template <int EPI>
; __device__ __forceinline__ void gemm_phase(const u16* __restrict__ A, const u16* __restrict__ Bt, const int K,
;                                            const int nN, char* shm, const EpiArgs& ea) {
;     ...
;       LDB(B0, 0, 0); SCHED; LDA(At, 0, 0); STAGE(SA(1, 1), rA, brow + HALF, t + 1);
;       WAIT_V(10); WAIT_L(8); BAR; WAIT_L(0); MMA(0, 0, At, B0); BAR; SCHED;
;       LDB(B1, 0, 1); STAGE(SB(0, 0), rB, bcol, t + 2);
;       WAIT_V(10); BAR; WAIT_L(0); MMA(0, 1, At, B1); BAR;
;       LDA(At, 0, 1); STAGE(SA(0, 0), rA, brow, t + 2);
;       BAR; WAIT_L(0); MMA(1, 0, At, B0); BAR; SCHED;
;       STAGE(SB(0, 1), rB, bcol + HALF, t + 2);
;       WAIT_V(10); BAR; MMA(1, 1, At, B1); BAR;
;       LDB(B0, 1, 0); SCHED; LDA(At, 1, 0); STAGE(SA(0, 1), rA, brow + HALF, t + 2);
.LBB0_306:
	ds_read_b128 v[128:131], v168
	ds_read_b128 v[132:135], v168 offset:1024
	ds_read_b128 v[136:139], v168 offset:2048
	ds_read_b128 v[140:143], v168 offset:3072
	s_add_i32 s79, s72, s78
	s_mov_b32 m0, s52
	s_add_i32 s26, s79, 0x4000
	ds_read_b128 v[144:147], v169
	ds_read_b128 v[148:151], v169 offset:1024
	ds_read_b128 v[152:155], v170
	ds_read_b128 v[156:159], v170 offset:1024
	ds_read_b128 v[180:183], v171
	ds_read_b128 v[184:187], v171 offset:1024
	ds_read_b128 v[188:191], v172
	ds_read_b128 v[192:195], v172 offset:1024
	buffer_load_dwordx4 v161, s[0:3], s26 offen lds
	s_mov_b32 m0, s53
	s_add_i32 s26, s79, 0x6000
	buffer_load_dwordx4 v161, s[0:3], s26 offen lds
	s_waitcnt vmcnt(10)
	s_waitcnt lgkmcnt(8)
	s_barrier
	s_waitcnt lgkmcnt(0)
	v_mfma_f32_16x16x32_bf16 v[124:127], v[128:131], v[144:147], v[124:127]
	v_mfma_f32_16x16x32_bf16 v[120:123], v[136:139], v[144:147], v[120:123]
	v_mfma_f32_16x16x32_bf16 v[116:119], v[128:131], v[152:155], v[116:119]
	v_mfma_f32_16x16x32_bf16 v[112:115], v[136:139], v[152:155], v[112:115]
	v_mfma_f32_16x16x32_bf16 v[108:111], v[128:131], v[180:183], v[108:111]
	v_mfma_f32_16x16x32_bf16 v[104:107], v[136:139], v[180:183], v[104:107]
	v_mfma_f32_16x16x32_bf16 v[100:103], v[128:131], v[188:191], v[100:103]
	v_mfma_f32_16x16x32_bf16 v[96:99], v[136:139], v[188:191], v[96:99]
	v_mfma_f32_16x16x32_bf16 v[124:127], v[132:135], v[148:151], v[124:127]
	v_mfma_f32_16x16x32_bf16 v[120:123], v[140:143], v[148:151], v[120:123]
	v_mfma_f32_16x16x32_bf16 v[116:119], v[132:135], v[156:159], v[116:119]
	v_mfma_f32_16x16x32_bf16 v[112:115], v[140:143], v[156:159], v[112:115]
	v_mfma_f32_16x16x32_bf16 v[108:111], v[132:135], v[184:187], v[108:111]
	v_mfma_f32_16x16x32_bf16 v[104:107], v[140:143], v[184:187], v[104:107]
	v_mfma_f32_16x16x32_bf16 v[100:103], v[132:135], v[192:195], v[100:103]
	v_mfma_f32_16x16x32_bf16 v[96:99], v[140:143], v[192:195], v[96:99]
	s_barrier
	s_add_i32 s80, s74, s78
	s_mov_b32 m0, s54
	s_add_i32 s81, s80, 0x8000
	s_mov_b32 s26, s2
	s_mov_b32 s27, s3
	ds_read_b128 v[196:199], v173
	ds_read_b128 v[200:203], v173 offset:1024
	ds_read_b128 v[204:207], v173 offset:2048
	ds_read_b128 v[208:211], v173 offset:3072
	buffer_load_dwordx4 v161, s[24:27], s81 offen lds
	s_mov_b32 m0, s55
	s_add_i32 s81, s80, 0xa000
	buffer_load_dwordx4 v161, s[24:27], s81 offen lds
	s_waitcnt vmcnt(10)
	s_barrier
	s_waitcnt lgkmcnt(0)
	v_mfma_f32_16x16x32_bf16 v[92:95], v[196:199], v[144:147], v[92:95]
	v_mfma_f32_16x16x32_bf16 v[88:91], v[204:207], v[144:147], v[88:91]
	v_mfma_f32_16x16x32_bf16 v[84:87], v[196:199], v[152:155], v[84:87]
	v_mfma_f32_16x16x32_bf16 v[80:83], v[204:207], v[152:155], v[80:83]
	v_mfma_f32_16x16x32_bf16 v[76:79], v[196:199], v[180:183], v[76:79]
	v_mfma_f32_16x16x32_bf16 v[72:75], v[204:207], v[180:183], v[72:75]
	v_mfma_f32_16x16x32_bf16 v[68:71], v[196:199], v[188:191], v[68:71]
	v_mfma_f32_16x16x32_bf16 v[64:67], v[204:207], v[188:191], v[64:67]
	v_mfma_f32_16x16x32_bf16 v[92:95], v[200:203], v[148:151], v[92:95]
	v_mfma_f32_16x16x32_bf16 v[88:91], v[208:211], v[148:151], v[88:91]
	v_mfma_f32_16x16x32_bf16 v[84:87], v[200:203], v[156:159], v[84:87]
	v_mfma_f32_16x16x32_bf16 v[80:83], v[208:211], v[156:159], v[80:83]
	v_mfma_f32_16x16x32_bf16 v[76:79], v[200:203], v[184:187], v[76:79]
	v_mfma_f32_16x16x32_bf16 v[72:75], v[208:211], v[184:187], v[72:75]
	v_mfma_f32_16x16x32_bf16 v[68:71], v[200:203], v[192:195], v[68:71]
	v_mfma_f32_16x16x32_bf16 v[64:67], v[208:211], v[192:195], v[64:67]
	s_add_i32 s81, s73, s78
	s_mov_b32 m0, s49
	s_add_i32 s82, s81, 0x8000
	s_barrier
	ds_read_b128 v[144:147], v169 offset:16384
	ds_read_b128 v[148:151], v169 offset:17408
	ds_read_b128 v[152:155], v170 offset:16384
	ds_read_b128 v[156:159], v170 offset:17408
	ds_read_b128 v[180:183], v171 offset:16384
	ds_read_b128 v[184:187], v171 offset:17408
	ds_read_b128 v[188:191], v172 offset:16384
	ds_read_b128 v[192:195], v172 offset:17408
	buffer_load_dwordx4 v161, s[0:3], s82 offen lds
	s_mov_b32 m0, s56
	s_add_i32 s82, s81, 0xa000
	buffer_load_dwordx4 v161, s[0:3], s82 offen lds
	s_barrier
	s_waitcnt lgkmcnt(0)
	v_mfma_f32_16x16x32_bf16 v[60:63], v[128:131], v[144:147], v[60:63]
	v_mfma_f32_16x16x32_bf16 v[56:59], v[136:139], v[144:147], v[56:59]
	v_mfma_f32_16x16x32_bf16 v[52:55], v[128:131], v[152:155], v[52:55]
	v_mfma_f32_16x16x32_bf16 v[48:51], v[136:139], v[152:155], v[48:51]
	v_mfma_f32_16x16x32_bf16 v[44:47], v[128:131], v[180:183], v[44:47]
	v_mfma_f32_16x16x32_bf16 v[40:43], v[136:139], v[180:183], v[40:43]
	v_mfma_f32_16x16x32_bf16 v[36:39], v[128:131], v[188:191], v[36:39]
	v_mfma_f32_16x16x32_bf16 v[32:35], v[136:139], v[188:191], v[32:35]
	v_mfma_f32_16x16x32_bf16 v[60:63], v[132:135], v[148:151], v[60:63]
	v_mfma_f32_16x16x32_bf16 v[56:59], v[140:143], v[148:151], v[56:59]
	v_mfma_f32_16x16x32_bf16 v[52:55], v[132:135], v[156:159], v[52:55]
	v_mfma_f32_16x16x32_bf16 v[48:51], v[140:143], v[156:159], v[48:51]
	v_mfma_f32_16x16x32_bf16 v[44:47], v[132:135], v[184:187], v[44:47]
	v_mfma_f32_16x16x32_bf16 v[40:43], v[140:143], v[184:187], v[40:43]
	v_mfma_f32_16x16x32_bf16 v[36:39], v[132:135], v[192:195], v[36:39]
	v_mfma_f32_16x16x32_bf16 v[32:35], v[140:143], v[192:195], v[32:35]
	s_barrier
	s_add_i32 s82, s43, s78
	s_mov_b32 m0, s57
	s_add_i32 s83, s82, 0x8000
	buffer_load_dwordx4 v161, s[24:27], s83 offen lds
	s_mov_b32 m0, s58
	s_add_i32 s83, s82, 0xa000
	buffer_load_dwordx4 v161, s[24:27], s83 offen lds
	s_waitcnt vmcnt(10)
	s_barrier
; #define LDA(dst, b, h)                                                                                               \
;   _Pragma("unroll") for (int m = 0; m < 4; ++m) _Pragma("unroll") for (int k = 0; k < 2; ++k) dst[m][k] =            \
;       *reinterpret_cast<const bf16x8*>(SA(b, h) + lds_byte(wr * 64 + m * 16 + fr, k * 32 + fq * 8))
; #define LDB(dst, b, h)                                                                                               \
;   _Pragma("unroll") for (int n = 0; n < 2; ++n) _Pragma("unroll") for (int k = 0; k < 2; ++k) dst[n][k] =            \
;       *reinterpret_cast<const bf16x8*>(SB(b, h) + lds_byte(wc * 32 + n * 16 + fr, k * 32 + fq * 8))
; #define WAIT_V(n) asm volatile("s_waitcnt vmcnt(" #n ")" ::: "memory")
; #define WAIT_L(n) asm volatile("s_waitcnt lgkmcnt(" #n ")" ::: "memory")
; #define BAR __builtin_amdgcn_s_barrier()
; #define SCHED __builtin_amdgcn_sched_barrier(0)
; template <int EPI>
; __device__ __forceinline__ void gemm_phase(const u16* __restrict__ A, const u16* __restrict__ Bt, const int K,
;                                            const int nN, char* shm, const EpiArgs& ea) {
;     ...
;       LDB(B0, 1, 0); SCHED; LDA(At, 1, 0); STAGE(SA(0, 1), rA, brow + HALF, t + 2);
;       WAIT_V(10); WAIT_L(8); BAR; WAIT_L(0); MMA(0, 0, At, B0); BAR; SCHED;
;       LDB(B1, 1, 1); STAGE(SB(1, 0), rB, bcol, t + 3);
;       WAIT_V(10); BAR; WAIT_L(0); MMA(0, 1, At, B1); BAR;
;       LDA(At, 1, 1); STAGE(SA(1, 0), rA, brow, t + 3);
;       BAR; WAIT_L(0); MMA(1, 0, At, B0); BAR; SCHED;
;       STAGE(SB(1, 1), rB, bcol + HALF, t + 3);
	v_mfma_f32_16x16x32_bf16 v[28:31], v[196:199], v[144:147], v[28:31]
	v_mfma_f32_16x16x32_bf16 v[24:27], v[204:207], v[144:147], v[24:27]
	v_mfma_f32_16x16x32_bf16 v[20:23], v[196:199], v[152:155], v[20:23]
	v_mfma_f32_16x16x32_bf16 v[16:19], v[204:207], v[152:155], v[16:19]
	v_mfma_f32_16x16x32_bf16 v[12:15], v[196:199], v[180:183], v[12:15]
	v_mfma_f32_16x16x32_bf16 v[8:11], v[204:207], v[180:183], v[8:11]
	v_mfma_f32_16x16x32_bf16 v[4:7], v[196:199], v[188:191], v[4:7]
	v_mfma_f32_16x16x32_bf16 v[0:3], v[204:207], v[188:191], v[0:3]
	v_mfma_f32_16x16x32_bf16 v[28:31], v[200:203], v[148:151], v[28:31]
	v_mfma_f32_16x16x32_bf16 v[24:27], v[208:211], v[148:151], v[24:27]
	v_mfma_f32_16x16x32_bf16 v[20:23], v[200:203], v[156:159], v[20:23]
	v_mfma_f32_16x16x32_bf16 v[16:19], v[208:211], v[156:159], v[16:19]
	v_mfma_f32_16x16x32_bf16 v[12:15], v[200:203], v[184:187], v[12:15]
	v_mfma_f32_16x16x32_bf16 v[8:11], v[208:211], v[184:187], v[8:11]
	v_mfma_f32_16x16x32_bf16 v[4:7], v[200:203], v[192:195], v[4:7]
	v_mfma_f32_16x16x32_bf16 v[0:3], v[208:211], v[192:195], v[0:3]
	s_barrier
	ds_read_b128 v[128:131], v176
	ds_read_b128 v[132:135], v176 offset:1024
	ds_read_b128 v[136:139], v176 offset:2048
	ds_read_b128 v[140:143], v176 offset:3072
	s_mov_b32 m0, s59
	s_add_i32 s83, s79, 0x8000
	ds_read_b128 v[144:147], v169 offset:32768
	ds_read_b128 v[148:151], v169 offset:33792
	ds_read_b128 v[152:155], v170 offset:32768
	ds_read_b128 v[156:159], v170 offset:33792
	ds_read_b128 v[180:183], v171 offset:32768
	ds_read_b128 v[184:187], v171 offset:33792
	ds_read_b128 v[188:191], v172 offset:32768
	ds_read_b128 v[192:195], v172 offset:33792
	buffer_load_dwordx4 v161, s[0:3], s83 offen lds
	s_mov_b32 m0, s60
	s_add_i32 s79, s79, 0xa000
	buffer_load_dwordx4 v161, s[0:3], s79 offen lds
	s_waitcnt vmcnt(10)
	s_waitcnt lgkmcnt(8)
	s_barrier
	s_waitcnt lgkmcnt(0)
	v_mfma_f32_16x16x32_bf16 v[124:127], v[128:131], v[144:147], v[124:127]
	v_mfma_f32_16x16x32_bf16 v[120:123], v[136:139], v[144:147], v[120:123]
	v_mfma_f32_16x16x32_bf16 v[116:119], v[128:131], v[152:155], v[116:119]
	v_mfma_f32_16x16x32_bf16 v[112:115], v[136:139], v[152:155], v[112:115]
	v_mfma_f32_16x16x32_bf16 v[108:111], v[128:131], v[180:183], v[108:111]
	v_mfma_f32_16x16x32_bf16 v[104:107], v[136:139], v[180:183], v[104:107]
	v_mfma_f32_16x16x32_bf16 v[100:103], v[128:131], v[188:191], v[100:103]
	v_mfma_f32_16x16x32_bf16 v[96:99], v[136:139], v[188:191], v[96:99]
	v_mfma_f32_16x16x32_bf16 v[124:127], v[132:135], v[148:151], v[124:127]
	v_mfma_f32_16x16x32_bf16 v[120:123], v[140:143], v[148:151], v[120:123]
	v_mfma_f32_16x16x32_bf16 v[116:119], v[132:135], v[156:159], v[116:119]
	v_mfma_f32_16x16x32_bf16 v[112:115], v[140:143], v[156:159], v[112:115]
	v_mfma_f32_16x16x32_bf16 v[108:111], v[132:135], v[184:187], v[108:111]
	v_mfma_f32_16x16x32_bf16 v[104:107], v[140:143], v[184:187], v[104:107]
	v_mfma_f32_16x16x32_bf16 v[100:103], v[132:135], v[192:195], v[100:103]
	v_mfma_f32_16x16x32_bf16 v[96:99], v[140:143], v[192:195], v[96:99]
	s_barrier
	s_mov_b32 m0, s61
	s_add_i32 s79, s80, 0xc000
	ds_read_b128 v[196:199], v177
	ds_read_b128 v[200:203], v177 offset:1024
	ds_read_b128 v[204:207], v177 offset:2048
	ds_read_b128 v[208:211], v177 offset:3072
	buffer_load_dwordx4 v161, s[24:27], s79 offen lds
	s_mov_b32 m0, s62
	s_add_i32 s80, s80, 0xe000
	buffer_load_dwordx4 v161, s[24:27], s80 offen lds
	s_waitcnt vmcnt(10)
	s_barrier
	s_waitcnt lgkmcnt(0)
	v_mfma_f32_16x16x32_bf16 v[92:95], v[196:199], v[144:147], v[92:95]
	v_mfma_f32_16x16x32_bf16 v[88:91], v[204:207], v[144:147], v[88:91]
	v_mfma_f32_16x16x32_bf16 v[84:87], v[196:199], v[152:155], v[84:87]
	v_mfma_f32_16x16x32_bf16 v[80:83], v[204:207], v[152:155], v[80:83]
	v_mfma_f32_16x16x32_bf16 v[76:79], v[196:199], v[180:183], v[76:79]
	v_mfma_f32_16x16x32_bf16 v[72:75], v[204:207], v[180:183], v[72:75]
	v_mfma_f32_16x16x32_bf16 v[68:71], v[196:199], v[188:191], v[68:71]
	v_mfma_f32_16x16x32_bf16 v[64:67], v[204:207], v[188:191], v[64:67]
	v_mfma_f32_16x16x32_bf16 v[92:95], v[200:203], v[148:151], v[92:95]
	v_mfma_f32_16x16x32_bf16 v[88:91], v[208:211], v[148:151], v[88:91]
	v_mfma_f32_16x16x32_bf16 v[84:87], v[200:203], v[156:159], v[84:87]
	v_mfma_f32_16x16x32_bf16 v[80:83], v[208:211], v[156:159], v[80:83]
	v_mfma_f32_16x16x32_bf16 v[76:79], v[200:203], v[184:187], v[76:79]
	v_mfma_f32_16x16x32_bf16 v[72:75], v[208:211], v[184:187], v[72:75]
	v_mfma_f32_16x16x32_bf16 v[68:71], v[200:203], v[192:195], v[68:71]
	v_mfma_f32_16x16x32_bf16 v[64:67], v[208:211], v[192:195], v[64:67]
	s_mov_b32 m0, s63
	s_add_i32 s79, s81, 0xc000
	s_barrier
; #define LDA(dst, b, h)                                                                                               \
;   _Pragma("unroll") for (int m = 0; m < 4; ++m) _Pragma("unroll") for (int k = 0; k < 2; ++k) dst[m][k] =            \
;       *reinterpret_cast<const bf16x8*>(SA(b, h) + lds_byte(wr * 64 + m * 16 + fr, k * 32 + fq * 8))
; #define WAIT_V(n) asm volatile("s_waitcnt vmcnt(" #n ")" ::: "memory")
; #define WAIT_L(n) asm volatile("s_waitcnt lgkmcnt(" #n ")" ::: "memory")
; #define BAR __builtin_amdgcn_s_barrier()
; #define SCHED __builtin_amdgcn_sched_barrier(0)
; template <int EPI>
; __device__ __forceinline__ void gemm_phase(const u16* __restrict__ A, const u16* __restrict__ Bt, const int K,
;                                            const int nN, char* shm, const EpiArgs& ea) {
;     ...
;       LDA(At, 1, 1); STAGE(SA(1, 0), rA, brow, t + 3);
;       BAR; WAIT_L(0); MMA(1, 0, At, B0); BAR; SCHED;
;       STAGE(SB(1, 1), rB, bcol + HALF, t + 3);
;       WAIT_V(10); BAR; MMA(1, 1, At, B1); BAR;
;     }
;     float eC = 0.f, eB = 0.f;
;     float2 eS = make_float2(0.f, 0.f);
;     if (EPI == EPI_IN || EPI == EPI_SWIGLU_LN) {
;       if (wr == 0) {
;         eC = ea.c1[bcol + tid];
;         eS = *(const float2*)(ea.st_in + (size_t)(brow + tid) * 2);
;       } else {
;         eC = ea.c2[bcol + tid - 256];
;         if (EPI == EPI_IN) eB = ea.bias[bcol + tid - 256];
	ds_read_b128 v[144:147], v169 offset:49152
	ds_read_b128 v[148:151], v169 offset:50176
	ds_read_b128 v[152:155], v170 offset:49152
	ds_read_b128 v[156:159], v170 offset:50176
	ds_read_b128 v[180:183], v171 offset:49152
	ds_read_b128 v[184:187], v171 offset:50176
	ds_read_b128 v[188:191], v172 offset:49152
	ds_read_b128 v[192:195], v172 offset:50176
	buffer_load_dwordx4 v161, s[0:3], s79 offen lds
	s_mov_b32 m0, s64
	s_add_i32 s81, s81, 0xe000
	buffer_load_dwordx4 v161, s[0:3], s81 offen lds
	s_barrier
	s_waitcnt lgkmcnt(0)
	v_mfma_f32_16x16x32_bf16 v[60:63], v[128:131], v[144:147], v[60:63]
	v_mfma_f32_16x16x32_bf16 v[56:59], v[136:139], v[144:147], v[56:59]
	v_mfma_f32_16x16x32_bf16 v[52:55], v[128:131], v[152:155], v[52:55]
	v_mfma_f32_16x16x32_bf16 v[48:51], v[136:139], v[152:155], v[48:51]
	v_mfma_f32_16x16x32_bf16 v[44:47], v[128:131], v[180:183], v[44:47]
	v_mfma_f32_16x16x32_bf16 v[40:43], v[136:139], v[180:183], v[40:43]
	v_mfma_f32_16x16x32_bf16 v[36:39], v[128:131], v[188:191], v[36:39]
	v_mfma_f32_16x16x32_bf16 v[32:35], v[136:139], v[188:191], v[32:35]
	v_mfma_f32_16x16x32_bf16 v[60:63], v[132:135], v[148:151], v[60:63]
	v_mfma_f32_16x16x32_bf16 v[56:59], v[140:143], v[148:151], v[56:59]
	v_mfma_f32_16x16x32_bf16 v[52:55], v[132:135], v[156:159], v[52:55]
	v_mfma_f32_16x16x32_bf16 v[48:51], v[140:143], v[156:159], v[48:51]
	v_mfma_f32_16x16x32_bf16 v[44:47], v[132:135], v[184:187], v[44:47]
	v_mfma_f32_16x16x32_bf16 v[40:43], v[140:143], v[184:187], v[40:43]
	v_mfma_f32_16x16x32_bf16 v[36:39], v[132:135], v[192:195], v[36:39]
	v_mfma_f32_16x16x32_bf16 v[32:35], v[140:143], v[192:195], v[32:35]
	s_barrier
	s_mov_b32 m0, s65
	s_add_i32 s79, s82, 0xc000
	buffer_load_dwordx4 v161, s[24:27], s79 offen lds
	s_mov_b32 m0, s66
	s_add_i32 s82, s82, 0xe000
	buffer_load_dwordx4 v161, s[24:27], s82 offen lds
	s_waitcnt vmcnt(10)
	s_barrier
	v_mfma_f32_16x16x32_bf16 v[28:31], v[196:199], v[144:147], v[28:31]
	v_mfma_f32_16x16x32_bf16 v[24:27], v[204:207], v[144:147], v[24:27]
	v_mfma_f32_16x16x32_bf16 v[20:23], v[196:199], v[152:155], v[20:23]
	v_mfma_f32_16x16x32_bf16 v[16:19], v[204:207], v[152:155], v[16:19]
	v_mfma_f32_16x16x32_bf16 v[12:15], v[196:199], v[180:183], v[12:15]
	v_mfma_f32_16x16x32_bf16 v[8:11], v[204:207], v[180:183], v[8:11]
	v_mfma_f32_16x16x32_bf16 v[4:7], v[196:199], v[188:191], v[4:7]
	v_mfma_f32_16x16x32_bf16 v[0:3], v[204:207], v[188:191], v[0:3]
	v_mfma_f32_16x16x32_bf16 v[28:31], v[200:203], v[148:151], v[28:31]
	v_mfma_f32_16x16x32_bf16 v[24:27], v[208:211], v[148:151], v[24:27]
	v_mfma_f32_16x16x32_bf16 v[20:23], v[200:203], v[156:159], v[20:23]
	v_mfma_f32_16x16x32_bf16 v[16:19], v[208:211], v[156:159], v[16:19]
	v_mfma_f32_16x16x32_bf16 v[12:15], v[200:203], v[184:187], v[12:15]
	v_mfma_f32_16x16x32_bf16 v[8:11], v[208:211], v[184:187], v[8:11]
	v_mfma_f32_16x16x32_bf16 v[4:7], v[200:203], v[192:195], v[4:7]
	v_mfma_f32_16x16x32_bf16 v[0:3], v[208:211], v[192:195], v[0:3]
	s_add_i32 s75, s75, 2
	s_add_i32 s78, s78, 0x8000
	s_cmp_lt_u32 s75, 28
	s_barrier
	s_cbranch_scc1 .LBB0_306
	s_mov_b64 s[26:27], -1
	s_and_b64 vcc, exec, s[38:39]
	s_cbranch_vccz .LBB0_309
	s_ashr_i32 s43, s42, 31
	v_lshl_add_u64 v[128:129], v[174:175], 0, s[42:43]
	v_lshl_add_u64 v[128:129], v[128:129], 2, s[50:51]
	global_load_dword v150, v[128:129], off offset:-1024
	v_add_u32_e32 v128, s42, v163
	v_ashrrev_i32_e32 v129, 31, v128
	v_lshl_add_u64 v[128:129], v[128:129], 2, s[18:19]
	s_mov_b64 s[26:27], 0

; #define LDA(dst, b, h)                                                                                               \
;   _Pragma("unroll") for (int m = 0; m < 4; ++m) _Pragma("unroll") for (int k = 0; k < 2; ++k) dst[m][k] =            \
;       *reinterpret_cast<const bf16x8*>(SA(b, h) + lds_byte(wr * 64 + m * 16 + fr, k * 32 + fq * 8))
; #define LDB(dst, b, h)                                                                                               \
;   _Pragma("unroll") for (int n = 0; n < 2; ++n) _Pragma("unroll") for (int k = 0; k < 2; ++k) dst[n][k] =            \
;       *reinterpret_cast<const bf16x8*>(SB(b, h) + lds_byte(wc * 32 + n * 16 + fr, k * 32 + fq * 8))
; #define WAIT_V(n) asm volatile("s_waitcnt vmcnt(" #n ")" ::: "memory")
; #define WAIT_L(n) asm volatile("s_waitcnt lgkmcnt(" #n ")" ::: "memory")
; #define BAR __builtin_amdgcn_s_barrier()
; template <int EPI>
; __device__ __forceinline__ void gemm_phase(const u16* __restrict__ A, const u16* __restrict__ Bt, const int K,
;                                            const int nN, char* shm, const EpiArgs& ea) {
;     ...
;         if (EPI == EPI_IN) eB = ea.bias[bcol + tid - 256];
;       }
;     }
;     {
;       LDB(B0, 0, 0); LDA(At, 0, 0); STAGE(SA(1, 1), rA, brow + HALF, nt - 1);
;       WAIT_V(10); BAR; WAIT_L(0); MMA(0, 0, At, B0); BAR;
;       LDB(B1, 0, 1); WAIT_V(8); BAR; WAIT_L(0); MMA(0, 1, At, B1); BAR;
;       LDA(At, 0, 1); WAIT_V(4); BAR; WAIT_L(0); MMA(1, 0, At, B0); MMA(1, 1, At, B1); BAR;
;     }
;     {
;       LDB(B0, 1, 0); LDA(At, 1, 0); WAIT_V(2); BAR; WAIT_L(0); MMA(0, 0, At, B0); BAR;
.LBB0_311:
	s_mov_b32 m0, s52
	s_add_i32 s26, s72, 0x7c000
	global_load_dword v151, v[128:129], off
	ds_read_b128 v[128:131], v168
	ds_read_b128 v[132:135], v168 offset:1024
	ds_read_b128 v[136:139], v168 offset:2048
	ds_read_b128 v[140:143], v168 offset:3072
	ds_read_b128 v[144:147], v169
	ds_read_b128 v[152:155], v169 offset:1024
	ds_read_b128 v[156:159], v170
	ds_read_b128 v[180:183], v170 offset:1024
	ds_read_b128 v[184:187], v171
	ds_read_b128 v[188:191], v171 offset:1024
	ds_read_b128 v[192:195], v172
	ds_read_b128 v[196:199], v172 offset:1024
	buffer_load_dwordx4 v161, s[0:3], s26 offen lds
	s_mov_b32 m0, s53
	s_add_i32 s72, s72, 0x7e000
	buffer_load_dwordx4 v161, s[0:3], s72 offen lds
	s_waitcnt vmcnt(10)
	s_barrier
	s_waitcnt lgkmcnt(0)
	v_mfma_f32_16x16x32_bf16 v[124:127], v[128:131], v[144:147], v[124:127]
	v_mfma_f32_16x16x32_bf16 v[120:123], v[136:139], v[144:147], v[120:123]
	v_mfma_f32_16x16x32_bf16 v[116:119], v[128:131], v[156:159], v[116:119]
	v_mfma_f32_16x16x32_bf16 v[112:115], v[136:139], v[156:159], v[112:115]
	v_mfma_f32_16x16x32_bf16 v[108:111], v[128:131], v[184:187], v[108:111]
	v_mfma_f32_16x16x32_bf16 v[104:107], v[136:139], v[184:187], v[104:107]
	v_mfma_f32_16x16x32_bf16 v[100:103], v[128:131], v[192:195], v[100:103]
	v_mfma_f32_16x16x32_bf16 v[96:99], v[136:139], v[192:195], v[96:99]
	v_mfma_f32_16x16x32_bf16 v[124:127], v[132:135], v[152:155], v[124:127]
	v_mfma_f32_16x16x32_bf16 v[120:123], v[140:143], v[152:155], v[120:123]
	v_mfma_f32_16x16x32_bf16 v[116:119], v[132:135], v[180:183], v[116:119]
	v_mfma_f32_16x16x32_bf16 v[112:115], v[140:143], v[180:183], v[112:115]
	v_mfma_f32_16x16x32_bf16 v[108:111], v[132:135], v[188:191], v[108:111]
	v_mfma_f32_16x16x32_bf16 v[104:107], v[140:143], v[188:191], v[104:107]
	v_mfma_f32_16x16x32_bf16 v[100:103], v[132:135], v[196:199], v[100:103]
	v_mfma_f32_16x16x32_bf16 v[96:99], v[140:143], v[196:199], v[96:99]
	s_barrier
	ds_read_b128 v[200:203], v173
	ds_read_b128 v[204:207], v173 offset:1024
	ds_read_b128 v[208:211], v173 offset:2048
	ds_read_b128 v[212:215], v173 offset:3072
	s_waitcnt vmcnt(8)
	s_barrier
	s_waitcnt lgkmcnt(0)
	v_mfma_f32_16x16x32_bf16 v[92:95], v[200:203], v[144:147], v[92:95]
	v_mfma_f32_16x16x32_bf16 v[88:91], v[208:211], v[144:147], v[88:91]
	v_mfma_f32_16x16x32_bf16 v[84:87], v[200:203], v[156:159], v[84:87]
	v_mfma_f32_16x16x32_bf16 v[80:83], v[208:211], v[156:159], v[80:83]
	v_mfma_f32_16x16x32_bf16 v[76:79], v[200:203], v[184:187], v[76:79]
	v_mfma_f32_16x16x32_bf16 v[72:75], v[208:211], v[184:187], v[72:75]
	v_mfma_f32_16x16x32_bf16 v[68:71], v[200:203], v[192:195], v[68:71]
	v_mfma_f32_16x16x32_bf16 v[64:67], v[208:211], v[192:195], v[64:67]
	v_mfma_f32_16x16x32_bf16 v[92:95], v[204:207], v[152:155], v[92:95]
	v_mfma_f32_16x16x32_bf16 v[88:91], v[212:215], v[152:155], v[88:91]
	v_mfma_f32_16x16x32_bf16 v[84:87], v[204:207], v[180:183], v[84:87]
	v_mfma_f32_16x16x32_bf16 v[80:83], v[212:215], v[180:183], v[80:83]
	v_mfma_f32_16x16x32_bf16 v[76:79], v[204:207], v[188:191], v[76:79]
	v_mfma_f32_16x16x32_bf16 v[72:75], v[212:215], v[188:191], v[72:75]
	v_mfma_f32_16x16x32_bf16 v[68:71], v[204:207], v[196:199], v[68:71]
	v_mfma_f32_16x16x32_bf16 v[64:67], v[212:215], v[196:199], v[64:67]
	s_barrier
	ds_read_b128 v[144:147], v169 offset:16384
	ds_read_b128 v[152:155], v169 offset:17408
	ds_read_b128 v[156:159], v170 offset:16384
	ds_read_b128 v[180:183], v170 offset:17408
	ds_read_b128 v[184:187], v171 offset:16384
	ds_read_b128 v[188:191], v171 offset:17408
	ds_read_b128 v[192:195], v172 offset:16384
	ds_read_b128 v[196:199], v172 offset:17408
	s_waitcnt vmcnt(4)
	s_barrier
	s_waitcnt lgkmcnt(0)
	v_mfma_f32_16x16x32_bf16 v[60:63], v[128:131], v[144:147], v[60:63]
	v_mfma_f32_16x16x32_bf16 v[56:59], v[136:139], v[144:147], v[56:59]
	v_mfma_f32_16x16x32_bf16 v[40:43], v[136:139], v[184:187], v[40:43]
	v_mfma_f32_16x16x32_bf16 v[60:63], v[132:135], v[152:155], v[60:63]
	v_mfma_f32_16x16x32_bf16 v[56:59], v[140:143], v[152:155], v[56:59]
	v_mfma_f32_16x16x32_bf16 v[52:55], v[128:131], v[156:159], v[52:55]
	v_mfma_f32_16x16x32_bf16 v[48:51], v[136:139], v[156:159], v[48:51]
	v_mfma_f32_16x16x32_bf16 v[44:47], v[128:131], v[184:187], v[44:47]
	v_mfma_f32_16x16x32_bf16 v[40:43], v[140:143], v[188:191], v[40:43]
	v_mfma_f32_16x16x32_bf16 v[36:39], v[128:131], v[192:195], v[36:39]
	v_mfma_f32_16x16x32_bf16 v[32:35], v[136:139], v[192:195], v[32:35]
	v_mfma_f32_16x16x32_bf16 v[52:55], v[132:135], v[180:183], v[52:55]
	v_mfma_f32_16x16x32_bf16 v[216:219], v[140:143], v[180:183], v[48:51]
	v_mfma_f32_16x16x32_bf16 v[44:47], v[132:135], v[188:191], v[44:47]
	v_mfma_f32_16x16x32_bf16 v[220:223], v[132:135], v[196:199], v[36:39]
	v_mfma_f32_16x16x32_bf16 v[32:35], v[140:143], v[196:199], v[32:35]
	v_mfma_f32_16x16x32_bf16 v[16:19], v[208:211], v[156:159], v[16:19]
	v_mfma_f32_16x16x32_bf16 v[4:7], v[200:203], v[192:195], v[4:7]
	v_mfma_f32_16x16x32_bf16 v[0:3], v[208:211], v[192:195], v[0:3]
	v_mfma_f32_16x16x32_bf16 v[28:31], v[200:203], v[144:147], v[28:31]
	v_mfma_f32_16x16x32_bf16 v[24:27], v[208:211], v[144:147], v[24:27]
	v_mfma_f32_16x16x32_bf16 v[20:23], v[200:203], v[156:159], v[20:23]
	v_mfma_f32_16x16x32_bf16 v[16:19], v[212:215], v[180:183], v[16:19]
	v_mfma_f32_16x16x32_bf16 v[12:15], v[200:203], v[184:187], v[12:15]
	v_mfma_f32_16x16x32_bf16 v[8:11], v[208:211], v[184:187], v[8:11]
	v_mfma_f32_16x16x32_bf16 v[4:7], v[204:207], v[196:199], v[4:7]
	v_mfma_f32_16x16x32_bf16 v[0:3], v[212:215], v[196:199], v[0:3]
	v_mfma_f32_16x16x32_bf16 v[224:227], v[204:207], v[152:155], v[28:31]
	v_mfma_f32_16x16x32_bf16 v[24:27], v[212:215], v[152:155], v[24:27]
	v_mfma_f32_16x16x32_bf16 v[20:23], v[204:207], v[180:183], v[20:23]
	v_mfma_f32_16x16x32_bf16 v[152:155], v[204:207], v[188:191], v[12:15]
	v_mfma_f32_16x16x32_bf16 v[156:159], v[212:215], v[188:191], v[8:11]
	s_barrier
; #define LDA(dst, b, h)                                                                                               \
;   _Pragma("unroll") for (int m = 0; m < 4; ++m) _Pragma("unroll") for (int k = 0; k < 2; ++k) dst[m][k] =            \
;       *reinterpret_cast<const bf16x8*>(SA(b, h) + lds_byte(wr * 64 + m * 16 + fr, k * 32 + fq * 8))
; #define LDB(dst, b, h)                                                                                               \
;   _Pragma("unroll") for (int n = 0; n < 2; ++n) _Pragma("unroll") for (int k = 0; k < 2; ++k) dst[n][k] =            \
;       *reinterpret_cast<const bf16x8*>(SB(b, h) + lds_byte(wc * 32 + n * 16 + fr, k * 32 + fq * 8))
; #define WAIT_V(n) asm volatile("s_waitcnt vmcnt(" #n ")" ::: "memory")
; #define WAIT_L(n) asm volatile("s_waitcnt lgkmcnt(" #n ")" ::: "memory")
; #define BAR __builtin_amdgcn_s_barrier()
; template <int EPI>
; __device__ __forceinline__ void gemm_phase(const u16* __restrict__ A, const u16* __restrict__ Bt, const int K,
;                                            const int nN, char* shm, const EpiArgs& ea) {
;     ...
;       LDA(At, 0, 1); WAIT_V(4); BAR; WAIT_L(0); MMA(1, 0, At, B0); MMA(1, 1, At, B1); BAR;
;     }
;     {
;       LDB(B0, 1, 0); LDA(At, 1, 0); WAIT_V(2); BAR; WAIT_L(0); MMA(0, 0, At, B0); BAR;
;       LDB(B1, 1, 1); WAIT_V(0); BAR; WAIT_L(0); MMA(0, 1, At, B1); BAR;
;       LDA(At, 1, 1); BAR; WAIT_L(0); MMA(1, 0, At, B0); MMA(1, 1, At, B1); BAR;
;     }
;     if (wr == 0) BAR;
	s_nop 0
	ds_read_b128 v[8:11], v176
	ds_read_b128 v[12:15], v176 offset:1024
	ds_read_b128 v[180:183], v176 offset:2048
	ds_read_b128 v[184:187], v176 offset:3072
	ds_read_b128 v[128:131], v169 offset:32768
	ds_read_b128 v[132:135], v169 offset:33792
	ds_read_b128 v[188:191], v170 offset:32768
	ds_read_b128 v[192:195], v170 offset:33792
	ds_read_b128 v[196:199], v171 offset:32768
	ds_read_b128 v[200:203], v171 offset:33792
	ds_read_b128 v[204:207], v172 offset:32768
	ds_read_b128 v[208:211], v172 offset:33792
	s_waitcnt vmcnt(2)
	s_barrier
	s_waitcnt lgkmcnt(0)
	v_mfma_f32_16x16x32_bf16 v[48:51], v[8:11], v[188:191], v[116:119]
	v_mfma_f32_16x16x32_bf16 v[140:143], v[12:15], v[192:195], v[48:51]
	v_mfma_f32_16x16x32_bf16 v[48:51], v[180:183], v[188:191], v[112:115]
	v_mfma_f32_16x16x32_bf16 v[136:139], v[184:187], v[192:195], v[48:51]
	v_mfma_f32_16x16x32_bf16 v[48:51], v[8:11], v[196:199], v[108:111]
	v_mfma_f32_16x16x32_bf16 v[28:31], v[8:11], v[128:131], v[124:127]
	v_mfma_f32_16x16x32_bf16 v[124:127], v[12:15], v[200:203], v[48:51]
	v_mfma_f32_16x16x32_bf16 v[48:51], v[180:183], v[196:199], v[104:107]
	v_mfma_f32_16x16x32_bf16 v[36:39], v[180:183], v[128:131], v[120:123]
	v_mfma_f32_16x16x32_bf16 v[120:123], v[184:187], v[200:203], v[48:51]
	v_mfma_f32_16x16x32_bf16 v[48:51], v[8:11], v[204:207], v[100:103]
	v_mfma_f32_16x16x32_bf16 v[108:111], v[12:15], v[208:211], v[48:51]
	v_mfma_f32_16x16x32_bf16 v[48:51], v[180:183], v[204:207], v[96:99]
	v_mfma_f32_16x16x32_bf16 v[28:31], v[12:15], v[132:135], v[28:31]
	v_mfma_f32_16x16x32_bf16 v[36:39], v[184:187], v[132:135], v[36:39]
	v_mfma_f32_16x16x32_bf16 v[104:107], v[184:187], v[208:211], v[48:51]
	s_barrier
	ds_read_b128 v[212:215], v177
	ds_read_b128 v[228:231], v177 offset:1024
	ds_read_b128 v[232:235], v177 offset:2048
	ds_read_b128 v[236:239], v177 offset:3072
	s_waitcnt vmcnt(0)
	s_barrier
	s_waitcnt lgkmcnt(0)
	v_mfma_f32_16x16x32_bf16 v[48:51], v[212:215], v[128:131], v[92:95]
	v_mfma_f32_16x16x32_bf16 v[88:91], v[232:235], v[128:131], v[88:91]
	v_mfma_f32_16x16x32_bf16 v[84:87], v[212:215], v[188:191], v[84:87]
	v_mfma_f32_16x16x32_bf16 v[80:83], v[232:235], v[188:191], v[80:83]
	v_mfma_f32_16x16x32_bf16 v[76:79], v[212:215], v[196:199], v[76:79]
	v_mfma_f32_16x16x32_bf16 v[72:75], v[232:235], v[196:199], v[72:75]
	v_mfma_f32_16x16x32_bf16 v[68:71], v[212:215], v[204:207], v[68:71]
	v_mfma_f32_16x16x32_bf16 v[64:67], v[232:235], v[204:207], v[64:67]
	v_mfma_f32_16x16x32_bf16 v[48:51], v[228:231], v[132:135], v[48:51]
	v_mfma_f32_16x16x32_bf16 v[144:147], v[236:239], v[132:135], v[88:91]
	v_mfma_f32_16x16x32_bf16 v[132:135], v[228:231], v[192:195], v[84:87]
	v_mfma_f32_16x16x32_bf16 v[128:131], v[236:239], v[192:195], v[80:83]
	v_mfma_f32_16x16x32_bf16 v[116:119], v[228:231], v[200:203], v[76:79]
	v_mfma_f32_16x16x32_bf16 v[112:115], v[236:239], v[200:203], v[72:75]
	v_mfma_f32_16x16x32_bf16 v[100:103], v[228:231], v[208:211], v[68:71]
	v_mfma_f32_16x16x32_bf16 v[96:99], v[236:239], v[208:211], v[64:67]
	s_barrier
	s_nop 0
	ds_read_b128 v[64:67], v169 offset:49152
	ds_read_b128 v[68:71], v169 offset:50176
	ds_read_b128 v[188:191], v170 offset:49152
	ds_read_b128 v[192:195], v170 offset:50176
	ds_read_b128 v[196:199], v171 offset:49152
	ds_read_b128 v[200:203], v171 offset:50176
	ds_read_b128 v[204:207], v172 offset:49152
	ds_read_b128 v[208:211], v172 offset:50176
	s_barrier
	s_waitcnt lgkmcnt(0)
	v_mfma_f32_16x16x32_bf16 v[60:63], v[8:11], v[64:67], v[60:63]
	v_mfma_f32_16x16x32_bf16 v[52:55], v[8:11], v[188:191], v[52:55]
	v_mfma_f32_16x16x32_bf16 v[44:47], v[8:11], v[196:199], v[44:47]
	v_mfma_f32_16x16x32_bf16 v[8:11], v[8:11], v[204:207], v[220:223]
	v_mfma_f32_16x16x32_bf16 v[92:95], v[12:15], v[68:71], v[60:63]
	v_mfma_f32_16x16x32_bf16 v[56:59], v[180:183], v[64:67], v[56:59]
	v_mfma_f32_16x16x32_bf16 v[76:79], v[12:15], v[192:195], v[52:55]
	v_mfma_f32_16x16x32_bf16 v[52:55], v[180:183], v[188:191], v[216:219]
	v_mfma_f32_16x16x32_bf16 v[60:63], v[12:15], v[200:203], v[44:47]
	v_mfma_f32_16x16x32_bf16 v[40:43], v[180:183], v[196:199], v[40:43]
	v_mfma_f32_16x16x32_bf16 v[12:15], v[12:15], v[208:211], v[8:11]
	v_mfma_f32_16x16x32_bf16 v[8:11], v[180:183], v[204:207], v[32:35]
	v_mfma_f32_16x16x32_bf16 v[88:91], v[184:187], v[68:71], v[56:59]
	v_mfma_f32_16x16x32_bf16 v[72:75], v[184:187], v[192:195], v[52:55]
	v_mfma_f32_16x16x32_bf16 v[56:59], v[184:187], v[200:203], v[40:43]
	v_mfma_f32_16x16x32_bf16 v[8:11], v[184:187], v[208:211], v[8:11]
	v_mfma_f32_16x16x32_bf16 v[16:19], v[232:235], v[188:191], v[16:19]
	v_mfma_f32_16x16x32_bf16 v[32:35], v[212:215], v[64:67], v[224:227]
	v_mfma_f32_16x16x32_bf16 v[24:27], v[232:235], v[64:67], v[24:27]
	v_mfma_f32_16x16x32_bf16 v[64:67], v[236:239], v[192:195], v[16:19]
	v_mfma_f32_16x16x32_bf16 v[16:19], v[212:215], v[196:199], v[152:155]
	v_mfma_f32_16x16x32_bf16 v[20:23], v[212:215], v[188:191], v[20:23]
	v_mfma_f32_16x16x32_bf16 v[40:43], v[228:231], v[200:203], v[16:19]
	v_mfma_f32_16x16x32_bf16 v[16:19], v[232:235], v[196:199], v[156:159]
	v_mfma_f32_16x16x32_bf16 v[4:7], v[212:215], v[204:207], v[4:7]
	v_mfma_f32_16x16x32_bf16 v[0:3], v[232:235], v[204:207], v[0:3]
	v_mfma_f32_16x16x32_bf16 v[84:87], v[228:231], v[68:71], v[32:35]
	v_mfma_f32_16x16x32_bf16 v[80:83], v[236:239], v[68:71], v[24:27]
	v_mfma_f32_16x16x32_bf16 v[68:71], v[228:231], v[192:195], v[20:23]
	v_mfma_f32_16x16x32_bf16 v[16:19], v[236:239], v[200:203], v[16:19]
	v_mfma_f32_16x16x32_bf16 v[4:7], v[228:231], v[208:211], v[4:7]
	v_mfma_f32_16x16x32_bf16 v[0:3], v[236:239], v[208:211], v[0:3]
	s_andn2_b64 vcc, exec, s[36:37]
	s_barrier
	s_cbranch_vccz .LBB0_380
	s_andn2_b64 vcc, exec, s[4:5]
	s_cbranch_vccz .LBB0_381

.LBB0_381:
	s_lshr_b32 s4, s70, 7
	s_mov_b32 m0, s54
	s_mul_i32 s4, s4, 0x84000
	s_mov_b32 s26, s2
	s_mov_b32 s27, s3
	buffer_load_dwordx4 v161, s[24:27], s4 offen lds
	s_mov_b32 m0, s55
	s_or_b32 s5, s4, 0x2000
	buffer_load_dwordx4 v161, s[24:27], s5 offen lds
	s_lshr_b32 s5, s71, 7
	s_mul_i32 s5, s5, 0x84000
	s_mov_b32 m0, s49
	s_or_b32 s43, s5, 0x2000
	buffer_load_dwordx4 v161, s[0:3], s5 offen lds
	s_mov_b32 m0, s56
	s_nop 0
	buffer_load_dwordx4 v161, s[0:3], s43 offen lds
	s_mov_b32 m0, s57
	s_add_i32 s43, s4, 0x84000
	buffer_load_dwordx4 v161, s[24:27], s43 offen lds
	s_mov_b32 m0, s58
	s_add_i32 s43, s4, 0x86000
	buffer_load_dwordx4 v161, s[24:27], s43 offen lds
	s_mov_b32 m0, s59
	s_add_i32 s43, s5, 0x84000
	buffer_load_dwordx4 v161, s[0:3], s43 offen lds
	s_mov_b32 m0, s60
	s_add_i32 s43, s5, 0x86000
	buffer_load_dwordx4 v161, s[0:3], s43 offen lds
	s_mov_b32 m0, s61
	s_or_b32 s43, s4, 0x4000
	buffer_load_dwordx4 v161, s[24:27], s43 offen lds
	s_mov_b32 m0, s62
	s_or_b32 s43, s4, 0x6000
	buffer_load_dwordx4 v161, s[24:27], s43 offen lds
	s_or_b32 s43, s5, 0x4000
	s_mov_b32 m0, s63
	s_or_b32 s5, s5, 0x6000
	buffer_load_dwordx4 v161, s[0:3], s43 offen lds
	s_mov_b32 m0, s64
	s_nop 0
	buffer_load_dwordx4 v161, s[0:3], s5 offen lds
	s_add_i32 s5, s4, 0x88000
	s_mov_b32 m0, s65
	s_add_i32 s4, s4, 0x8a000
	buffer_load_dwordx4 v161, s[24:27], s5 offen lds
	s_mov_b32 m0, s66
	s_nop 0
	buffer_load_dwordx4 v161, s[24:27], s4 offen lds
	s_mov_b64 s[4:5], -1
	s_and_b64 vcc, exec, s[38:39]
	s_cbranch_vccz .LBB0_314

; #define LDA(dst, b, h)                                                                                               \
;   _Pragma("unroll") for (int m = 0; m < 4; ++m) _Pragma("unroll") for (int k = 0; k < 2; ++k) dst[m][k] =            \
;       *reinterpret_cast<const bf16x8*>(SA(b, h) + lds_byte(wr * 64 + m * 16 + fr, k * 32 + fq * 8))
; #define LDB(dst, b, h)                                                                                               \
;   _Pragma("unroll") for (int n = 0; n < 2; ++n) _Pragma("unroll") for (int k = 0; k < 2; ++k) dst[n][k] =            \
;       *reinterpret_cast<const bf16x8*>(SB(b, h) + lds_byte(wc * 32 + n * 16 + fr, k * 32 + fq * 8))
; #define WAIT_V(n) asm volatile("s_waitcnt vmcnt(" #n ")" ::: "memory")
; #define WAIT_L(n) asm volatile("s_waitcnt lgkmcnt(" #n ")" ::: "memory")
; #define BAR __builtin_amdgcn_s_barrier()
; #define SCHED __builtin_amdgcn_sched_barrier(0)
; template <int EPI>
; __device__ __forceinline__ void gemm_phase(const u16* __restrict__ A, const u16* __restrict__ Bt, const int K,
;                                            const int nN, char* shm, const EpiArgs& ea) {
;     ...
;       LDB(B0, 0, 0); SCHED; LDA(At, 0, 0); STAGE(SA(1, 1), rA, brow + HALF, t + 1);
;       WAIT_V(10); WAIT_L(8); BAR; WAIT_L(0); MMA(0, 0, At, B0); BAR; SCHED;
;       LDB(B1, 0, 1); STAGE(SB(0, 0), rB, bcol, t + 2);
;       WAIT_V(10); BAR; WAIT_L(0); MMA(0, 1, At, B1); BAR;
;       LDA(At, 0, 1); STAGE(SA(0, 0), rA, brow, t + 2);
;       BAR; WAIT_L(0); MMA(1, 0, At, B0); BAR; SCHED;
;       STAGE(SB(0, 1), rB, bcol + HALF, t + 2);
;       WAIT_V(10); BAR; MMA(1, 1, At, B1); BAR;
;       LDB(B0, 1, 0); SCHED; LDA(At, 1, 0); STAGE(SA(0, 1), rA, brow + HALF, t + 2);
.LBB0_492:
	ds_read_b128 v[130:133], v146
	ds_read_b128 v[134:137], v146 offset:1024
	ds_read_b128 v[138:141], v146 offset:2048
	ds_read_b128 v[154:157], v146 offset:3072
	s_add_i32 s65, s59, s64
	s_mov_b32 m0, s34
	s_add_i32 s10, s65, 0x4000
	ds_read_b128 v[158:161], v147
	ds_read_b128 v[162:165], v147 offset:1024
	ds_read_b128 v[166:169], v148
	ds_read_b128 v[170:173], v148 offset:1024
	ds_read_b128 v[176:179], v149
	ds_read_b128 v[180:183], v149 offset:1024
	ds_read_b128 v[184:187], v150
	ds_read_b128 v[188:191], v150 offset:1024
	buffer_load_dwordx4 v142, s[0:3], s10 offen lds
	s_mov_b32 m0, s35
	s_add_i32 s10, s65, 0x6000
	buffer_load_dwordx4 v142, s[0:3], s10 offen lds
	s_waitcnt vmcnt(10)
	s_waitcnt lgkmcnt(8)
	s_barrier
	s_waitcnt lgkmcnt(0)
	v_mfma_f32_16x16x32_bf16 v[124:127], v[130:133], v[158:161], v[124:127]
	v_mfma_f32_16x16x32_bf16 v[120:123], v[138:141], v[158:161], v[120:123]
	v_mfma_f32_16x16x32_bf16 v[116:119], v[130:133], v[166:169], v[116:119]
	v_mfma_f32_16x16x32_bf16 v[112:115], v[138:141], v[166:169], v[112:115]
	v_mfma_f32_16x16x32_bf16 v[108:111], v[130:133], v[176:179], v[108:111]
	v_mfma_f32_16x16x32_bf16 v[104:107], v[138:141], v[176:179], v[104:107]
	v_mfma_f32_16x16x32_bf16 v[100:103], v[130:133], v[184:187], v[100:103]
	v_mfma_f32_16x16x32_bf16 v[96:99], v[138:141], v[184:187], v[96:99]
	v_mfma_f32_16x16x32_bf16 v[124:127], v[134:137], v[162:165], v[124:127]
	v_mfma_f32_16x16x32_bf16 v[120:123], v[154:157], v[162:165], v[120:123]
	v_mfma_f32_16x16x32_bf16 v[116:119], v[134:137], v[170:173], v[116:119]
	v_mfma_f32_16x16x32_bf16 v[112:115], v[154:157], v[170:173], v[112:115]
	v_mfma_f32_16x16x32_bf16 v[108:111], v[134:137], v[180:183], v[108:111]
	v_mfma_f32_16x16x32_bf16 v[104:107], v[154:157], v[180:183], v[104:107]
	v_mfma_f32_16x16x32_bf16 v[100:103], v[134:137], v[188:191], v[100:103]
	v_mfma_f32_16x16x32_bf16 v[96:99], v[154:157], v[188:191], v[96:99]
	s_barrier
	s_add_i32 s66, s62, s64
	s_mov_b32 m0, s36
	s_add_i32 s67, s66, 0x8000
	s_mov_b32 s10, s2
	s_mov_b32 s11, s3
	ds_read_b128 v[192:195], v151
	ds_read_b128 v[196:199], v151 offset:1024
	ds_read_b128 v[200:203], v151 offset:2048
	ds_read_b128 v[204:207], v151 offset:3072
	buffer_load_dwordx4 v142, s[8:11], s67 offen lds
	s_mov_b32 m0, s37
	s_add_i32 s67, s66, 0xa000
	buffer_load_dwordx4 v142, s[8:11], s67 offen lds
	s_waitcnt vmcnt(10)
	s_barrier
	s_waitcnt lgkmcnt(0)
	v_mfma_f32_16x16x32_bf16 v[92:95], v[192:195], v[158:161], v[92:95]
	v_mfma_f32_16x16x32_bf16 v[88:91], v[200:203], v[158:161], v[88:91]
	v_mfma_f32_16x16x32_bf16 v[84:87], v[192:195], v[166:169], v[84:87]
	v_mfma_f32_16x16x32_bf16 v[80:83], v[200:203], v[166:169], v[80:83]
	v_mfma_f32_16x16x32_bf16 v[76:79], v[192:195], v[176:179], v[76:79]
	v_mfma_f32_16x16x32_bf16 v[72:75], v[200:203], v[176:179], v[72:75]
	v_mfma_f32_16x16x32_bf16 v[68:71], v[192:195], v[184:187], v[68:71]
	v_mfma_f32_16x16x32_bf16 v[64:67], v[200:203], v[184:187], v[64:67]
	v_mfma_f32_16x16x32_bf16 v[92:95], v[196:199], v[162:165], v[92:95]
	v_mfma_f32_16x16x32_bf16 v[88:91], v[204:207], v[162:165], v[88:91]
	v_mfma_f32_16x16x32_bf16 v[84:87], v[196:199], v[170:173], v[84:87]
	v_mfma_f32_16x16x32_bf16 v[80:83], v[204:207], v[170:173], v[80:83]
	v_mfma_f32_16x16x32_bf16 v[76:79], v[196:199], v[180:183], v[76:79]
	v_mfma_f32_16x16x32_bf16 v[72:75], v[204:207], v[180:183], v[72:75]
	v_mfma_f32_16x16x32_bf16 v[68:71], v[196:199], v[188:191], v[68:71]
	v_mfma_f32_16x16x32_bf16 v[64:67], v[204:207], v[188:191], v[64:67]
	s_add_i32 s67, s61, s64
	s_mov_b32 m0, s27
	s_add_i32 s68, s67, 0x8000
	s_barrier
	ds_read_b128 v[158:161], v147 offset:16384
	ds_read_b128 v[162:165], v147 offset:17408
	ds_read_b128 v[166:169], v148 offset:16384
	ds_read_b128 v[170:173], v148 offset:17408
	ds_read_b128 v[176:179], v149 offset:16384
	ds_read_b128 v[180:183], v149 offset:17408
	ds_read_b128 v[184:187], v150 offset:16384
	ds_read_b128 v[188:191], v150 offset:17408
	buffer_load_dwordx4 v142, s[0:3], s68 offen lds
	s_mov_b32 m0, s38
	s_add_i32 s68, s67, 0xa000
	buffer_load_dwordx4 v142, s[0:3], s68 offen lds
	s_barrier
	s_waitcnt lgkmcnt(0)
	v_mfma_f32_16x16x32_bf16 v[60:63], v[130:133], v[158:161], v[60:63]
	v_mfma_f32_16x16x32_bf16 v[56:59], v[138:141], v[158:161], v[56:59]
	v_mfma_f32_16x16x32_bf16 v[52:55], v[130:133], v[166:169], v[52:55]
	v_mfma_f32_16x16x32_bf16 v[48:51], v[138:141], v[166:169], v[48:51]
	v_mfma_f32_16x16x32_bf16 v[44:47], v[130:133], v[176:179], v[44:47]
	v_mfma_f32_16x16x32_bf16 v[40:43], v[138:141], v[176:179], v[40:43]
	v_mfma_f32_16x16x32_bf16 v[36:39], v[130:133], v[184:187], v[36:39]
	v_mfma_f32_16x16x32_bf16 v[32:35], v[138:141], v[184:187], v[32:35]
	v_mfma_f32_16x16x32_bf16 v[60:63], v[134:137], v[162:165], v[60:63]
	v_mfma_f32_16x16x32_bf16 v[56:59], v[154:157], v[162:165], v[56:59]
	v_mfma_f32_16x16x32_bf16 v[52:55], v[134:137], v[170:173], v[52:55]
	v_mfma_f32_16x16x32_bf16 v[48:51], v[154:157], v[170:173], v[48:51]
	v_mfma_f32_16x16x32_bf16 v[44:47], v[134:137], v[180:183], v[44:47]
	v_mfma_f32_16x16x32_bf16 v[40:43], v[154:157], v[180:183], v[40:43]
	v_mfma_f32_16x16x32_bf16 v[36:39], v[134:137], v[188:191], v[36:39]
	v_mfma_f32_16x16x32_bf16 v[32:35], v[154:157], v[188:191], v[32:35]
	s_barrier
	s_add_i32 s68, s60, s64
	s_mov_b32 m0, s39
	s_add_i32 s69, s68, 0x8000
	buffer_load_dwordx4 v142, s[8:11], s69 offen lds
	s_mov_b32 m0, s40
	s_add_i32 s69, s68, 0xa000
	buffer_load_dwordx4 v142, s[8:11], s69 offen lds
	s_waitcnt vmcnt(10)
	s_barrier
; #define LDA(dst, b, h)                                                                                               \
;   _Pragma("unroll") for (int m = 0; m < 4; ++m) _Pragma("unroll") for (int k = 0; k < 2; ++k) dst[m][k] =            \
;       *reinterpret_cast<const bf16x8*>(SA(b, h) + lds_byte(wr * 64 + m * 16 + fr, k * 32 + fq * 8))
; #define LDB(dst, b, h)                                                                                               \
;   _Pragma("unroll") for (int n = 0; n < 2; ++n) _Pragma("unroll") for (int k = 0; k < 2; ++k) dst[n][k] =            \
;       *reinterpret_cast<const bf16x8*>(SB(b, h) + lds_byte(wc * 32 + n * 16 + fr, k * 32 + fq * 8))
; #define WAIT_V(n) asm volatile("s_waitcnt vmcnt(" #n ")" ::: "memory")
; #define WAIT_L(n) asm volatile("s_waitcnt lgkmcnt(" #n ")" ::: "memory")
; #define BAR __builtin_amdgcn_s_barrier()
; #define SCHED __builtin_amdgcn_sched_barrier(0)
; template <int EPI>
; __device__ __forceinline__ void gemm_phase(const u16* __restrict__ A, const u16* __restrict__ Bt, const int K,
;                                            const int nN, char* shm, const EpiArgs& ea) {
;     ...
;       LDB(B0, 1, 0); SCHED; LDA(At, 1, 0); STAGE(SA(0, 1), rA, brow + HALF, t + 2);
;       WAIT_V(10); WAIT_L(8); BAR; WAIT_L(0); MMA(0, 0, At, B0); BAR; SCHED;
;       LDB(B1, 1, 1); STAGE(SB(1, 0), rB, bcol, t + 3);
;       WAIT_V(10); BAR; WAIT_L(0); MMA(0, 1, At, B1); BAR;
;       LDA(At, 1, 1); STAGE(SA(1, 0), rA, brow, t + 3);
;       BAR; WAIT_L(0); MMA(1, 0, At, B0); BAR; SCHED;
;       STAGE(SB(1, 1), rB, bcol + HALF, t + 3);
	v_mfma_f32_16x16x32_bf16 v[28:31], v[192:195], v[158:161], v[28:31]
	v_mfma_f32_16x16x32_bf16 v[24:27], v[200:203], v[158:161], v[24:27]
	v_mfma_f32_16x16x32_bf16 v[20:23], v[192:195], v[166:169], v[20:23]
	v_mfma_f32_16x16x32_bf16 v[16:19], v[200:203], v[166:169], v[16:19]
	v_mfma_f32_16x16x32_bf16 v[12:15], v[192:195], v[176:179], v[12:15]
	v_mfma_f32_16x16x32_bf16 v[8:11], v[200:203], v[176:179], v[8:11]
	v_mfma_f32_16x16x32_bf16 v[4:7], v[192:195], v[184:187], v[4:7]
	v_mfma_f32_16x16x32_bf16 v[0:3], v[200:203], v[184:187], v[0:3]
	v_mfma_f32_16x16x32_bf16 v[28:31], v[196:199], v[162:165], v[28:31]
	v_mfma_f32_16x16x32_bf16 v[24:27], v[204:207], v[162:165], v[24:27]
	v_mfma_f32_16x16x32_bf16 v[20:23], v[196:199], v[170:173], v[20:23]
	v_mfma_f32_16x16x32_bf16 v[16:19], v[204:207], v[170:173], v[16:19]
	v_mfma_f32_16x16x32_bf16 v[12:15], v[196:199], v[180:183], v[12:15]
	v_mfma_f32_16x16x32_bf16 v[8:11], v[204:207], v[180:183], v[8:11]
	v_mfma_f32_16x16x32_bf16 v[4:7], v[196:199], v[188:191], v[4:7]
	v_mfma_f32_16x16x32_bf16 v[0:3], v[204:207], v[188:191], v[0:3]
	s_barrier
	ds_read_b128 v[130:133], v152
	ds_read_b128 v[134:137], v152 offset:1024
	ds_read_b128 v[138:141], v152 offset:2048
	ds_read_b128 v[154:157], v152 offset:3072
	s_mov_b32 m0, s41
	s_add_i32 s69, s65, 0x8000
	ds_read_b128 v[158:161], v147 offset:32768
	ds_read_b128 v[162:165], v147 offset:33792
	ds_read_b128 v[166:169], v148 offset:32768
	ds_read_b128 v[170:173], v148 offset:33792
	ds_read_b128 v[176:179], v149 offset:32768
	ds_read_b128 v[180:183], v149 offset:33792
	ds_read_b128 v[184:187], v150 offset:32768
	ds_read_b128 v[188:191], v150 offset:33792
	buffer_load_dwordx4 v142, s[0:3], s69 offen lds
	s_mov_b32 m0, s42
	s_add_i32 s65, s65, 0xa000
	buffer_load_dwordx4 v142, s[0:3], s65 offen lds
	s_waitcnt vmcnt(10)
	s_waitcnt lgkmcnt(8)
	s_barrier
	s_waitcnt lgkmcnt(0)
	v_mfma_f32_16x16x32_bf16 v[124:127], v[130:133], v[158:161], v[124:127]
	v_mfma_f32_16x16x32_bf16 v[120:123], v[138:141], v[158:161], v[120:123]
	v_mfma_f32_16x16x32_bf16 v[116:119], v[130:133], v[166:169], v[116:119]
	v_mfma_f32_16x16x32_bf16 v[112:115], v[138:141], v[166:169], v[112:115]
	v_mfma_f32_16x16x32_bf16 v[108:111], v[130:133], v[176:179], v[108:111]
	v_mfma_f32_16x16x32_bf16 v[104:107], v[138:141], v[176:179], v[104:107]
	v_mfma_f32_16x16x32_bf16 v[100:103], v[130:133], v[184:187], v[100:103]
	v_mfma_f32_16x16x32_bf16 v[96:99], v[138:141], v[184:187], v[96:99]
	v_mfma_f32_16x16x32_bf16 v[124:127], v[134:137], v[162:165], v[124:127]
	v_mfma_f32_16x16x32_bf16 v[120:123], v[154:157], v[162:165], v[120:123]
	v_mfma_f32_16x16x32_bf16 v[116:119], v[134:137], v[170:173], v[116:119]
	v_mfma_f32_16x16x32_bf16 v[112:115], v[154:157], v[170:173], v[112:115]
	v_mfma_f32_16x16x32_bf16 v[108:111], v[134:137], v[180:183], v[108:111]
	v_mfma_f32_16x16x32_bf16 v[104:107], v[154:157], v[180:183], v[104:107]
	v_mfma_f32_16x16x32_bf16 v[100:103], v[134:137], v[188:191], v[100:103]
	v_mfma_f32_16x16x32_bf16 v[96:99], v[154:157], v[188:191], v[96:99]
	s_barrier
	s_mov_b32 m0, s43
	s_add_i32 s65, s66, 0xc000
	ds_read_b128 v[192:195], v153
	ds_read_b128 v[196:199], v153 offset:1024
	ds_read_b128 v[200:203], v153 offset:2048
	ds_read_b128 v[204:207], v153 offset:3072
	buffer_load_dwordx4 v142, s[8:11], s65 offen lds
	s_mov_b32 m0, s48
	s_add_i32 s66, s66, 0xe000
	buffer_load_dwordx4 v142, s[8:11], s66 offen lds
	s_waitcnt vmcnt(10)
	s_barrier
	s_waitcnt lgkmcnt(0)
	v_mfma_f32_16x16x32_bf16 v[92:95], v[192:195], v[158:161], v[92:95]
	v_mfma_f32_16x16x32_bf16 v[88:91], v[200:203], v[158:161], v[88:91]
	v_mfma_f32_16x16x32_bf16 v[84:87], v[192:195], v[166:169], v[84:87]
	v_mfma_f32_16x16x32_bf16 v[80:83], v[200:203], v[166:169], v[80:83]
	v_mfma_f32_16x16x32_bf16 v[76:79], v[192:195], v[176:179], v[76:79]
	v_mfma_f32_16x16x32_bf16 v[72:75], v[200:203], v[176:179], v[72:75]
	v_mfma_f32_16x16x32_bf16 v[68:71], v[192:195], v[184:187], v[68:71]
	v_mfma_f32_16x16x32_bf16 v[64:67], v[200:203], v[184:187], v[64:67]
	v_mfma_f32_16x16x32_bf16 v[92:95], v[196:199], v[162:165], v[92:95]
	v_mfma_f32_16x16x32_bf16 v[88:91], v[204:207], v[162:165], v[88:91]
	v_mfma_f32_16x16x32_bf16 v[84:87], v[196:199], v[170:173], v[84:87]
	v_mfma_f32_16x16x32_bf16 v[80:83], v[204:207], v[170:173], v[80:83]
	v_mfma_f32_16x16x32_bf16 v[76:79], v[196:199], v[180:183], v[76:79]
	v_mfma_f32_16x16x32_bf16 v[72:75], v[204:207], v[180:183], v[72:75]
	v_mfma_f32_16x16x32_bf16 v[68:71], v[196:199], v[188:191], v[68:71]
	v_mfma_f32_16x16x32_bf16 v[64:67], v[204:207], v[188:191], v[64:67]
	s_mov_b32 m0, s49
	s_add_i32 s65, s67, 0xc000
	s_barrier
	ds_read_b128 v[158:161], v147 offset:49152
	ds_read_b128 v[162:165], v147 offset:50176
	ds_read_b128 v[166:169], v148 offset:49152
	ds_read_b128 v[170:173], v148 offset:50176
	ds_read_b128 v[176:179], v149 offset:49152
	ds_read_b128 v[180:183], v149 offset:50176
	ds_read_b128 v[184:187], v150 offset:49152
	ds_read_b128 v[188:191], v150 offset:50176
	buffer_load_dwordx4 v142, s[0:3], s65 offen lds
	s_mov_b32 m0, s50
	s_add_i32 s67, s67, 0xe000
	buffer_load_dwordx4 v142, s[0:3], s67 offen lds
	s_barrier
; #define LDA(dst, b, h)                                                                                               \
;   _Pragma("unroll") for (int m = 0; m < 4; ++m) _Pragma("unroll") for (int k = 0; k < 2; ++k) dst[m][k] =            \
;       *reinterpret_cast<const bf16x8*>(SA(b, h) + lds_byte(wr * 64 + m * 16 + fr, k * 32 + fq * 8))
; #define LDB(dst, b, h)                                                                                               \
;   _Pragma("unroll") for (int n = 0; n < 2; ++n) _Pragma("unroll") for (int k = 0; k < 2; ++k) dst[n][k] =            \
;       *reinterpret_cast<const bf16x8*>(SB(b, h) + lds_byte(wc * 32 + n * 16 + fr, k * 32 + fq * 8))
; #define WAIT_V(n) asm volatile("s_waitcnt vmcnt(" #n ")" ::: "memory")
; #define WAIT_L(n) asm volatile("s_waitcnt lgkmcnt(" #n ")" ::: "memory")
; #define BAR __builtin_amdgcn_s_barrier()
; #define SCHED __builtin_amdgcn_sched_barrier(0)
; template <int EPI>
; __device__ __forceinline__ void gemm_phase(const u16* __restrict__ A, const u16* __restrict__ Bt, const int K,
;                                            const int nN, char* shm, const EpiArgs& ea) {
;     ...
;       BAR; WAIT_L(0); MMA(1, 0, At, B0); BAR; SCHED;
;       STAGE(SB(1, 1), rB, bcol + HALF, t + 3);
;       WAIT_V(10); BAR; MMA(1, 1, At, B1); BAR;
;     }
;     float eC = 0.f, eB = 0.f;
;     float2 eS = make_float2(0.f, 0.f);
;     if (EPI == EPI_IN || EPI == EPI_SWIGLU_LN) {
;       if (wr == 0) {
;         eC = ea.c1[bcol + tid];
;         eS = *(const float2*)(ea.st_in + (size_t)(brow + tid) * 2);
;       } else {
;         eC = ea.c2[bcol + tid - 256];
;         if (EPI == EPI_IN) eB = ea.bias[bcol + tid - 256];
;       }
;     }
;     {
;       LDB(B0, 0, 0); LDA(At, 0, 0); STAGE(SA(1, 1), rA, brow + HALF, nt - 1);
;       WAIT_V(10); BAR; WAIT_L(0); MMA(0, 0, At, B0); BAR;
;       LDB(B1, 0, 1); WAIT_V(8); BAR; WAIT_L(0); MMA(0, 1, At, B1); BAR;
;       LDA(At, 0, 1); WAIT_V(4); BAR; WAIT_L(0); MMA(1, 0, At, B0); MMA(1, 1, At, B1); BAR;
;     }
;     {
;       LDB(B0, 1, 0); LDA(At, 1, 0); WAIT_V(2); BAR; WAIT_L(0); MMA(0, 0, At, B0); BAR;
	s_waitcnt lgkmcnt(0)
	v_mfma_f32_16x16x32_bf16 v[60:63], v[130:133], v[158:161], v[60:63]
	v_mfma_f32_16x16x32_bf16 v[56:59], v[138:141], v[158:161], v[56:59]
	v_mfma_f32_16x16x32_bf16 v[52:55], v[130:133], v[166:169], v[52:55]
	v_mfma_f32_16x16x32_bf16 v[48:51], v[138:141], v[166:169], v[48:51]
	v_mfma_f32_16x16x32_bf16 v[44:47], v[130:133], v[176:179], v[44:47]
	v_mfma_f32_16x16x32_bf16 v[40:43], v[138:141], v[176:179], v[40:43]
	v_mfma_f32_16x16x32_bf16 v[36:39], v[130:133], v[184:187], v[36:39]
	v_mfma_f32_16x16x32_bf16 v[32:35], v[138:141], v[184:187], v[32:35]
	v_mfma_f32_16x16x32_bf16 v[60:63], v[134:137], v[162:165], v[60:63]
	v_mfma_f32_16x16x32_bf16 v[56:59], v[154:157], v[162:165], v[56:59]
	v_mfma_f32_16x16x32_bf16 v[52:55], v[134:137], v[170:173], v[52:55]
	v_mfma_f32_16x16x32_bf16 v[48:51], v[154:157], v[170:173], v[48:51]
	v_mfma_f32_16x16x32_bf16 v[44:47], v[134:137], v[180:183], v[44:47]
	v_mfma_f32_16x16x32_bf16 v[40:43], v[154:157], v[180:183], v[40:43]
	v_mfma_f32_16x16x32_bf16 v[36:39], v[134:137], v[188:191], v[36:39]
	v_mfma_f32_16x16x32_bf16 v[32:35], v[154:157], v[188:191], v[32:35]
	s_barrier
	s_mov_b32 m0, s51
	s_add_i32 s65, s68, 0xc000
	buffer_load_dwordx4 v142, s[8:11], s65 offen lds
	s_mov_b32 m0, s52
	s_add_i32 s68, s68, 0xe000
	buffer_load_dwordx4 v142, s[8:11], s68 offen lds
	s_waitcnt vmcnt(10)
	s_barrier
	v_mfma_f32_16x16x32_bf16 v[28:31], v[192:195], v[158:161], v[28:31]
	v_mfma_f32_16x16x32_bf16 v[24:27], v[200:203], v[158:161], v[24:27]
	v_mfma_f32_16x16x32_bf16 v[20:23], v[192:195], v[166:169], v[20:23]
	v_mfma_f32_16x16x32_bf16 v[16:19], v[200:203], v[166:169], v[16:19]
	v_mfma_f32_16x16x32_bf16 v[12:15], v[192:195], v[176:179], v[12:15]
	v_mfma_f32_16x16x32_bf16 v[8:11], v[200:203], v[176:179], v[8:11]
	v_mfma_f32_16x16x32_bf16 v[4:7], v[192:195], v[184:187], v[4:7]
	v_mfma_f32_16x16x32_bf16 v[0:3], v[200:203], v[184:187], v[0:3]
	v_mfma_f32_16x16x32_bf16 v[28:31], v[196:199], v[162:165], v[28:31]
	v_mfma_f32_16x16x32_bf16 v[24:27], v[204:207], v[162:165], v[24:27]
	v_mfma_f32_16x16x32_bf16 v[20:23], v[196:199], v[170:173], v[20:23]
	v_mfma_f32_16x16x32_bf16 v[16:19], v[204:207], v[170:173], v[16:19]
	v_mfma_f32_16x16x32_bf16 v[12:15], v[196:199], v[180:183], v[12:15]
	v_mfma_f32_16x16x32_bf16 v[8:11], v[204:207], v[180:183], v[8:11]
	v_mfma_f32_16x16x32_bf16 v[4:7], v[196:199], v[188:191], v[4:7]
	v_mfma_f32_16x16x32_bf16 v[0:3], v[204:207], v[188:191], v[0:3]
	s_add_i32 s63, s63, 2
	s_add_i32 s64, s64, 0x8000
	s_cmp_lt_u32 s63, 28
	s_barrier
	s_cbranch_scc1 .LBB0_492
	s_mov_b32 m0, s34
	s_add_i32 s10, s59, 0x7c000
	ds_read_b128 v[130:133], v146
	ds_read_b128 v[134:137], v146 offset:1024
	ds_read_b128 v[138:141], v146 offset:2048
	ds_read_b128 v[154:157], v146 offset:3072
	ds_read_b128 v[158:161], v147
	ds_read_b128 v[162:165], v147 offset:1024
	ds_read_b128 v[166:169], v148
	ds_read_b128 v[170:173], v148 offset:1024
	ds_read_b128 v[176:179], v149
	ds_read_b128 v[180:183], v149 offset:1024
	ds_read_b128 v[184:187], v150
	ds_read_b128 v[188:191], v150 offset:1024
	buffer_load_dwordx4 v142, s[0:3], s10 offen lds
	s_mov_b32 m0, s35
	s_add_i32 s59, s59, 0x7e000
	buffer_load_dwordx4 v142, s[0:3], s59 offen lds
	s_waitcnt vmcnt(10)
	s_barrier
	s_waitcnt lgkmcnt(0)
	v_mfma_f32_16x16x32_bf16 v[124:127], v[130:133], v[158:161], v[124:127]
	v_mfma_f32_16x16x32_bf16 v[120:123], v[138:141], v[158:161], v[120:123]
	v_mfma_f32_16x16x32_bf16 v[116:119], v[130:133], v[166:169], v[116:119]
	v_mfma_f32_16x16x32_bf16 v[112:115], v[138:141], v[166:169], v[112:115]
	v_mfma_f32_16x16x32_bf16 v[100:103], v[130:133], v[184:187], v[100:103]
	v_mfma_f32_16x16x32_bf16 v[96:99], v[138:141], v[184:187], v[96:99]
	v_mfma_f32_16x16x32_bf16 v[124:127], v[134:137], v[162:165], v[124:127]
	v_mfma_f32_16x16x32_bf16 v[120:123], v[154:157], v[162:165], v[120:123]
	v_mfma_f32_16x16x32_bf16 v[116:119], v[134:137], v[170:173], v[116:119]
	v_mfma_f32_16x16x32_bf16 v[112:115], v[154:157], v[170:173], v[112:115]
	v_mfma_f32_16x16x32_bf16 v[108:111], v[130:133], v[176:179], v[108:111]
	v_mfma_f32_16x16x32_bf16 v[104:107], v[138:141], v[176:179], v[104:107]
	v_mfma_f32_16x16x32_bf16 v[100:103], v[134:137], v[188:191], v[100:103]
	v_mfma_f32_16x16x32_bf16 v[96:99], v[154:157], v[188:191], v[96:99]
	v_mfma_f32_16x16x32_bf16 v[192:195], v[134:137], v[180:183], v[108:111]
	v_mfma_f32_16x16x32_bf16 v[196:199], v[154:157], v[180:183], v[104:107]
	s_barrier
	s_nop 0
	ds_read_b128 v[104:107], v151
	ds_read_b128 v[108:111], v151 offset:1024
	ds_read_b128 v[200:203], v151 offset:2048
	ds_read_b128 v[204:207], v151 offset:3072
	s_waitcnt vmcnt(8)
	s_barrier
	s_waitcnt lgkmcnt(0)
	v_mfma_f32_16x16x32_bf16 v[84:87], v[104:107], v[166:169], v[84:87]
	v_mfma_f32_16x16x32_bf16 v[80:83], v[200:203], v[166:169], v[80:83]
	v_mfma_f32_16x16x32_bf16 v[68:71], v[104:107], v[184:187], v[68:71]
	v_mfma_f32_16x16x32_bf16 v[64:67], v[200:203], v[184:187], v[64:67]
	v_mfma_f32_16x16x32_bf16 v[92:95], v[104:107], v[158:161], v[92:95]
	v_mfma_f32_16x16x32_bf16 v[88:91], v[200:203], v[158:161], v[88:91]
	v_mfma_f32_16x16x32_bf16 v[84:87], v[108:111], v[170:173], v[84:87]
	v_mfma_f32_16x16x32_bf16 v[80:83], v[204:207], v[170:173], v[80:83]
	v_mfma_f32_16x16x32_bf16 v[76:79], v[104:107], v[176:179], v[76:79]
	v_mfma_f32_16x16x32_bf16 v[72:75], v[200:203], v[176:179], v[72:75]
	v_mfma_f32_16x16x32_bf16 v[68:71], v[108:111], v[188:191], v[68:71]
	v_mfma_f32_16x16x32_bf16 v[64:67], v[204:207], v[188:191], v[64:67]
	v_mfma_f32_16x16x32_bf16 v[208:211], v[108:111], v[162:165], v[92:95]
	v_mfma_f32_16x16x32_bf16 v[158:161], v[204:207], v[162:165], v[88:91]
	v_mfma_f32_16x16x32_bf16 v[162:165], v[108:111], v[180:183], v[76:79]
	v_mfma_f32_16x16x32_bf16 v[166:169], v[204:207], v[180:183], v[72:75]
	s_barrier
; #define LDA(dst, b, h)                                                                                               \
;   _Pragma("unroll") for (int m = 0; m < 4; ++m) _Pragma("unroll") for (int k = 0; k < 2; ++k) dst[m][k] =            \
;       *reinterpret_cast<const bf16x8*>(SA(b, h) + lds_byte(wr * 64 + m * 16 + fr, k * 32 + fq * 8))
; #define LDB(dst, b, h)                                                                                               \
;   _Pragma("unroll") for (int n = 0; n < 2; ++n) _Pragma("unroll") for (int k = 0; k < 2; ++k) dst[n][k] =            \
;       *reinterpret_cast<const bf16x8*>(SB(b, h) + lds_byte(wc * 32 + n * 16 + fr, k * 32 + fq * 8))
; #define WAIT_V(n) asm volatile("s_waitcnt vmcnt(" #n ")" ::: "memory")
; #define WAIT_L(n) asm volatile("s_waitcnt lgkmcnt(" #n ")" ::: "memory")
; #define BAR __builtin_amdgcn_s_barrier()
; template <int EPI>
; __device__ __forceinline__ void gemm_phase(const u16* __restrict__ A, const u16* __restrict__ Bt, const int K,
;                                            const int nN, char* shm, const EpiArgs& ea) {
;     ...
;       LDA(At, 0, 1); WAIT_V(4); BAR; WAIT_L(0); MMA(1, 0, At, B0); MMA(1, 1, At, B1); BAR;
;     }
;     {
;       LDB(B0, 1, 0); LDA(At, 1, 0); WAIT_V(2); BAR; WAIT_L(0); MMA(0, 0, At, B0); BAR;
;       LDB(B1, 1, 1); WAIT_V(0); BAR; WAIT_L(0); MMA(0, 1, At, B1); BAR;
;       LDA(At, 1, 1); BAR; WAIT_L(0); MMA(1, 0, At, B0); MMA(1, 1, At, B1); BAR;
	s_nop 0
	ds_read_b128 v[72:75], v147 offset:16384
	ds_read_b128 v[76:79], v147 offset:17408
	ds_read_b128 v[88:91], v148 offset:16384
	ds_read_b128 v[92:95], v148 offset:17408
	ds_read_b128 v[170:173], v149 offset:16384
	ds_read_b128 v[176:179], v149 offset:17408
	ds_read_b128 v[180:183], v150 offset:16384
	ds_read_b128 v[184:187], v150 offset:17408
	s_waitcnt vmcnt(4)
	s_barrier
	s_waitcnt lgkmcnt(0)
	v_mfma_f32_16x16x32_bf16 v[60:63], v[130:133], v[72:75], v[60:63]
	v_mfma_f32_16x16x32_bf16 v[52:55], v[130:133], v[88:91], v[52:55]
	v_mfma_f32_16x16x32_bf16 v[48:51], v[138:141], v[88:91], v[48:51]
	v_mfma_f32_16x16x32_bf16 v[36:39], v[130:133], v[180:183], v[36:39]
	v_mfma_f32_16x16x32_bf16 v[32:35], v[138:141], v[180:183], v[32:35]
	v_mfma_f32_16x16x32_bf16 v[60:63], v[134:137], v[76:79], v[60:63]
	v_mfma_f32_16x16x32_bf16 v[56:59], v[138:141], v[72:75], v[56:59]
	v_mfma_f32_16x16x32_bf16 v[52:55], v[134:137], v[92:95], v[52:55]
	v_mfma_f32_16x16x32_bf16 v[48:51], v[154:157], v[92:95], v[48:51]
	v_mfma_f32_16x16x32_bf16 v[44:47], v[130:133], v[170:173], v[44:47]
	v_mfma_f32_16x16x32_bf16 v[40:43], v[138:141], v[170:173], v[40:43]
	v_mfma_f32_16x16x32_bf16 v[36:39], v[134:137], v[184:187], v[36:39]
	v_mfma_f32_16x16x32_bf16 v[32:35], v[154:157], v[184:187], v[32:35]
	v_mfma_f32_16x16x32_bf16 v[188:191], v[154:157], v[76:79], v[56:59]
	v_mfma_f32_16x16x32_bf16 v[212:215], v[134:137], v[176:179], v[44:47]
	v_mfma_f32_16x16x32_bf16 v[216:219], v[154:157], v[176:179], v[40:43]
	v_mfma_f32_16x16x32_bf16 v[20:23], v[104:107], v[88:91], v[20:23]
	v_mfma_f32_16x16x32_bf16 v[16:19], v[200:203], v[88:91], v[16:19]
	v_mfma_f32_16x16x32_bf16 v[4:7], v[104:107], v[180:183], v[4:7]
	v_mfma_f32_16x16x32_bf16 v[0:3], v[200:203], v[180:183], v[0:3]
	v_mfma_f32_16x16x32_bf16 v[28:31], v[104:107], v[72:75], v[28:31]
	v_mfma_f32_16x16x32_bf16 v[24:27], v[200:203], v[72:75], v[24:27]
	v_mfma_f32_16x16x32_bf16 v[20:23], v[108:111], v[92:95], v[20:23]
	v_mfma_f32_16x16x32_bf16 v[16:19], v[204:207], v[92:95], v[16:19]
	v_mfma_f32_16x16x32_bf16 v[12:15], v[104:107], v[170:173], v[12:15]
	v_mfma_f32_16x16x32_bf16 v[8:11], v[200:203], v[170:173], v[8:11]
	v_mfma_f32_16x16x32_bf16 v[4:7], v[108:111], v[184:187], v[4:7]
	v_mfma_f32_16x16x32_bf16 v[0:3], v[204:207], v[184:187], v[0:3]
	v_mfma_f32_16x16x32_bf16 v[130:133], v[108:111], v[76:79], v[28:31]
	v_mfma_f32_16x16x32_bf16 v[134:137], v[204:207], v[76:79], v[24:27]
	v_mfma_f32_16x16x32_bf16 v[138:141], v[108:111], v[176:179], v[12:15]
	v_mfma_f32_16x16x32_bf16 v[154:157], v[204:207], v[176:179], v[8:11]
	s_barrier
	s_nop 0
	ds_read_b128 v[8:11], v152
	ds_read_b128 v[12:15], v152 offset:1024
	ds_read_b128 v[170:173], v152 offset:2048
	ds_read_b128 v[176:179], v152 offset:3072
	ds_read_b128 v[24:27], v147 offset:32768
	ds_read_b128 v[28:31], v147 offset:33792
	ds_read_b128 v[40:43], v148 offset:32768
	ds_read_b128 v[44:47], v148 offset:33792
	ds_read_b128 v[56:59], v149 offset:32768
	ds_read_b128 v[180:183], v149 offset:33792
	ds_read_b128 v[184:187], v150 offset:32768
	ds_read_b128 v[200:203], v150 offset:33792
	s_waitcnt vmcnt(2)
	s_barrier
	s_waitcnt lgkmcnt(0)
	v_mfma_f32_16x16x32_bf16 v[72:75], v[8:11], v[24:27], v[124:127]
	v_mfma_f32_16x16x32_bf16 v[124:127], v[12:15], v[28:31], v[72:75]
	v_mfma_f32_16x16x32_bf16 v[72:75], v[170:173], v[24:27], v[120:123]
	v_mfma_f32_16x16x32_bf16 v[120:123], v[176:179], v[28:31], v[72:75]
	v_mfma_f32_16x16x32_bf16 v[72:75], v[8:11], v[40:43], v[116:119]
	v_mfma_f32_16x16x32_bf16 v[104:107], v[12:15], v[44:47], v[72:75]
	v_mfma_f32_16x16x32_bf16 v[72:75], v[170:173], v[40:43], v[112:115]
	v_mfma_f32_16x16x32_bf16 v[108:111], v[176:179], v[44:47], v[72:75]
	v_mfma_f32_16x16x32_bf16 v[72:75], v[8:11], v[56:59], v[192:195]
	v_mfma_f32_16x16x32_bf16 v[88:91], v[12:15], v[180:183], v[72:75]
	v_mfma_f32_16x16x32_bf16 v[72:75], v[170:173], v[56:59], v[196:199]
	v_mfma_f32_16x16x32_bf16 v[92:95], v[176:179], v[180:183], v[72:75]
	v_mfma_f32_16x16x32_bf16 v[72:75], v[8:11], v[184:187], v[100:103]
	v_mfma_f32_16x16x32_bf16 v[76:79], v[170:173], v[184:187], v[96:99]
	v_mfma_f32_16x16x32_bf16 v[72:75], v[12:15], v[200:203], v[72:75]
	v_mfma_f32_16x16x32_bf16 v[76:79], v[176:179], v[200:203], v[76:79]
	s_barrier
	ds_read_b128 v[192:195], v153
	ds_read_b128 v[196:199], v153 offset:1024
	ds_read_b128 v[204:207], v153 offset:2048
	ds_read_b128 v[220:223], v153 offset:3072
	s_waitcnt vmcnt(0)
	s_barrier
; #define LDA(dst, b, h)                                                                                               \
;   _Pragma("unroll") for (int m = 0; m < 4; ++m) _Pragma("unroll") for (int k = 0; k < 2; ++k) dst[m][k] =            \
;       *reinterpret_cast<const bf16x8*>(SA(b, h) + lds_byte(wr * 64 + m * 16 + fr, k * 32 + fq * 8))
; #define LDB(dst, b, h)                                                                                               \
;   _Pragma("unroll") for (int n = 0; n < 2; ++n) _Pragma("unroll") for (int k = 0; k < 2; ++k) dst[n][k] =            \
;       *reinterpret_cast<const bf16x8*>(SB(b, h) + lds_byte(wc * 32 + n * 16 + fr, k * 32 + fq * 8))
; #define WAIT_V(n) asm volatile("s_waitcnt vmcnt(" #n ")" ::: "memory")
; #define WAIT_L(n) asm volatile("s_waitcnt lgkmcnt(" #n ")" ::: "memory")
; #define BAR __builtin_amdgcn_s_barrier()
; template <int EPI>
; __device__ __forceinline__ void gemm_phase(const u16* __restrict__ A, const u16* __restrict__ Bt, const int K,
;                                            const int nN, char* shm, const EpiArgs& ea) {
;     ...
;       LDB(B0, 1, 0); LDA(At, 1, 0); WAIT_V(2); BAR; WAIT_L(0); MMA(0, 0, At, B0); BAR;
;       LDB(B1, 1, 1); WAIT_V(0); BAR; WAIT_L(0); MMA(0, 1, At, B1); BAR;
;       LDA(At, 1, 1); BAR; WAIT_L(0); MMA(1, 0, At, B0); MMA(1, 1, At, B1); BAR;
;     }
;     if (wr == 0) BAR;
;     if (has_next) STAGE7(brow2, bcol2);
	s_waitcnt lgkmcnt(0)
	v_mfma_f32_16x16x32_bf16 v[96:99], v[192:195], v[24:27], v[208:211]
	v_mfma_f32_16x16x32_bf16 v[24:27], v[204:207], v[24:27], v[158:161]
	v_mfma_f32_16x16x32_bf16 v[112:115], v[220:223], v[28:31], v[24:27]
	v_mfma_f32_16x16x32_bf16 v[24:27], v[192:195], v[40:43], v[84:87]
	v_mfma_f32_16x16x32_bf16 v[100:103], v[196:199], v[44:47], v[24:27]
	v_mfma_f32_16x16x32_bf16 v[24:27], v[204:207], v[40:43], v[80:83]
	v_mfma_f32_16x16x32_bf16 v[116:119], v[196:199], v[28:31], v[96:99]
	v_mfma_f32_16x16x32_bf16 v[96:99], v[220:223], v[44:47], v[24:27]
	v_mfma_f32_16x16x32_bf16 v[24:27], v[192:195], v[56:59], v[162:165]
	v_mfma_f32_16x16x32_bf16 v[84:87], v[196:199], v[180:183], v[24:27]
	v_mfma_f32_16x16x32_bf16 v[24:27], v[204:207], v[56:59], v[166:169]
	v_mfma_f32_16x16x32_bf16 v[80:83], v[220:223], v[180:183], v[24:27]
	v_mfma_f32_16x16x32_bf16 v[24:27], v[192:195], v[184:187], v[68:71]
	v_mfma_f32_16x16x32_bf16 v[68:71], v[196:199], v[200:203], v[24:27]
	v_mfma_f32_16x16x32_bf16 v[24:27], v[204:207], v[184:187], v[64:67]
	v_mfma_f32_16x16x32_bf16 v[64:67], v[220:223], v[200:203], v[24:27]
	s_barrier
	ds_read_b128 v[158:161], v147 offset:49152
	ds_read_b128 v[162:165], v147 offset:50176
	ds_read_b128 v[166:169], v148 offset:49152
	ds_read_b128 v[180:183], v148 offset:50176
	ds_read_b128 v[184:187], v149 offset:49152
	ds_read_b128 v[200:203], v149 offset:50176
	ds_read_b128 v[208:211], v150 offset:49152
	ds_read_b128 v[224:227], v150 offset:50176
	s_barrier
	s_waitcnt lgkmcnt(0)
	v_mfma_f32_16x16x32_bf16 v[24:27], v[8:11], v[158:161], v[60:63]
	v_mfma_f32_16x16x32_bf16 v[56:59], v[12:15], v[162:165], v[24:27]
	v_mfma_f32_16x16x32_bf16 v[24:27], v[170:173], v[158:161], v[188:191]
	v_mfma_f32_16x16x32_bf16 v[60:63], v[176:179], v[162:165], v[24:27]
	v_mfma_f32_16x16x32_bf16 v[24:27], v[8:11], v[166:169], v[52:55]
	v_mfma_f32_16x16x32_bf16 v[40:43], v[12:15], v[180:183], v[24:27]
	v_mfma_f32_16x16x32_bf16 v[24:27], v[170:173], v[166:169], v[48:51]
	v_mfma_f32_16x16x32_bf16 v[44:47], v[176:179], v[180:183], v[24:27]
	v_mfma_f32_16x16x32_bf16 v[24:27], v[8:11], v[184:187], v[212:215]
	v_mfma_f32_16x16x32_bf16 v[8:11], v[8:11], v[208:211], v[36:39]
	v_mfma_f32_16x16x32_bf16 v[24:27], v[12:15], v[200:203], v[24:27]
	v_mfma_f32_16x16x32_bf16 v[28:31], v[170:173], v[184:187], v[216:219]
	v_mfma_f32_16x16x32_bf16 v[8:11], v[12:15], v[224:227], v[8:11]
	v_mfma_f32_16x16x32_bf16 v[12:15], v[170:173], v[208:211], v[32:35]
	v_mfma_f32_16x16x32_bf16 v[28:31], v[176:179], v[200:203], v[28:31]
	v_mfma_f32_16x16x32_bf16 v[12:15], v[176:179], v[224:227], v[12:15]
	v_mfma_f32_16x16x32_bf16 v[32:35], v[192:195], v[158:161], v[130:133]
	v_mfma_f32_16x16x32_bf16 v[52:55], v[196:199], v[162:165], v[32:35]
	v_mfma_f32_16x16x32_bf16 v[32:35], v[204:207], v[158:161], v[134:137]
	v_mfma_f32_16x16x32_bf16 v[16:19], v[204:207], v[166:169], v[16:19]
	v_mfma_f32_16x16x32_bf16 v[48:51], v[220:223], v[162:165], v[32:35]
	v_mfma_f32_16x16x32_bf16 v[20:23], v[192:195], v[166:169], v[20:23]
	v_mfma_f32_16x16x32_bf16 v[32:35], v[220:223], v[180:183], v[16:19]
	v_mfma_f32_16x16x32_bf16 v[16:19], v[192:195], v[184:187], v[138:141]
	v_mfma_f32_16x16x32_bf16 v[36:39], v[196:199], v[180:183], v[20:23]
	v_mfma_f32_16x16x32_bf16 v[20:23], v[196:199], v[200:203], v[16:19]
	v_mfma_f32_16x16x32_bf16 v[16:19], v[204:207], v[184:187], v[154:157]
	v_mfma_f32_16x16x32_bf16 v[4:7], v[192:195], v[208:211], v[4:7]
	v_mfma_f32_16x16x32_bf16 v[0:3], v[204:207], v[208:211], v[0:3]
	v_mfma_f32_16x16x32_bf16 v[16:19], v[220:223], v[200:203], v[16:19]
	v_mfma_f32_16x16x32_bf16 v[4:7], v[196:199], v[224:227], v[4:7]
	v_mfma_f32_16x16x32_bf16 v[0:3], v[220:223], v[224:227], v[0:3]
	s_andn2_b64 vcc, exec, s[18:19]
	s_barrier
	s_cbranch_vccnz .LBB0_495
	s_barrier
.LBB0_495:
	s_andn2_b64 vcc, exec, s[30:31]
	s_cbranch_vccnz .LBB0_497
	s_lshr_b32 s10, s56, 7
	s_mov_b32 m0, s36
	s_mul_i32 s30, s10, 0x84000
	s_mov_b32 s10, s2
	s_mov_b32 s11, s3
	buffer_load_dwordx4 v142, s[8:11], s30 offen lds
	s_mov_b32 m0, s37
	s_or_b32 s31, s30, 0x2000
	buffer_load_dwordx4 v142, s[8:11], s31 offen lds
	s_lshr_b32 s31, s57, 7
	s_mul_i32 s31, s31, 0x84000
	s_mov_b32 m0, s27
	s_or_b32 s59, s31, 0x2000
	buffer_load_dwordx4 v142, s[0:3], s31 offen lds
	s_mov_b32 m0, s38
	s_nop 0
	buffer_load_dwordx4 v142, s[0:3], s59 offen lds
	s_mov_b32 m0, s39
	s_add_i32 s59, s30, 0x84000
	buffer_load_dwordx4 v142, s[8:11], s59 offen lds
	s_mov_b32 m0, s40
	s_add_i32 s59, s30, 0x86000
	buffer_load_dwordx4 v142, s[8:11], s59 offen lds
	s_mov_b32 m0, s41
	s_add_i32 s59, s31, 0x84000
	buffer_load_dwordx4 v142, s[0:3], s59 offen lds
	s_mov_b32 m0, s42
	s_add_i32 s59, s31, 0x86000
	buffer_load_dwordx4 v142, s[0:3], s59 offen lds
	s_mov_b32 m0, s43
	s_or_b32 s59, s30, 0x4000
	buffer_load_dwordx4 v142, s[8:11], s59 offen lds
	s_mov_b32 m0, s48
	s_or_b32 s59, s30, 0x6000
	buffer_load_dwordx4 v142, s[8:11], s59 offen lds
	s_or_b32 s59, s31, 0x4000
	s_mov_b32 m0, s49
	s_or_b32 s31, s31, 0x6000
	buffer_load_dwordx4 v142, s[0:3], s59 offen lds
	s_mov_b32 m0, s50
	s_nop 0
	buffer_load_dwordx4 v142, s[0:3], s31 offen lds
	s_add_i32 s31, s30, 0x88000
	s_mov_b32 m0, s51
	s_add_i32 s30, s30, 0x8a000
	buffer_load_dwordx4 v142, s[8:11], s31 offen lds
	s_mov_b32 m0, s52
	s_nop 0
	buffer_load_dwordx4 v142, s[8:11], s30 offen lds

; #define LDA(dst, b, h)                                                                                               \
;   _Pragma("unroll") for (int m = 0; m < 4; ++m) _Pragma("unroll") for (int k = 0; k < 2; ++k) dst[m][k] =            \
;       *reinterpret_cast<const bf16x8*>(SA(b, h) + lds_byte(wr * 64 + m * 16 + fr, k * 32 + fq * 8))
; #define LDB(dst, b, h)                                                                                               \
;   _Pragma("unroll") for (int n = 0; n < 2; ++n) _Pragma("unroll") for (int k = 0; k < 2; ++k) dst[n][k] =            \
;       *reinterpret_cast<const bf16x8*>(SB(b, h) + lds_byte(wc * 32 + n * 16 + fr, k * 32 + fq * 8))
; #define WAIT_V(n) asm volatile("s_waitcnt vmcnt(" #n ")" ::: "memory")
; #define WAIT_L(n) asm volatile("s_waitcnt lgkmcnt(" #n ")" ::: "memory")
; #define BAR __builtin_amdgcn_s_barrier()
; #define SCHED __builtin_amdgcn_sched_barrier(0)
; template <int EPI>
; __device__ __forceinline__ void gemm_phase(const u16* __restrict__ A, const u16* __restrict__ Bt, const int K,
;                                            const int nN, char* shm, const EpiArgs& ea) {
;     ...
;     for (int t = 0; t < nt - 2; t += 2) {
;       LDB(B0, 0, 0); SCHED; LDA(At, 0, 0); STAGE(SA(1, 1), rA, brow + HALF, t + 1);
;       WAIT_V(10); WAIT_L(8); BAR; WAIT_L(0); MMA(0, 0, At, B0); BAR; SCHED;
;       LDB(B1, 0, 1); STAGE(SB(0, 0), rB, bcol, t + 2);
;       WAIT_V(10); BAR; WAIT_L(0); MMA(0, 1, At, B1); BAR;
;       LDA(At, 0, 1); STAGE(SA(0, 0), rA, brow, t + 2);
;       BAR; WAIT_L(0); MMA(1, 0, At, B0); BAR; SCHED;
;       STAGE(SB(0, 1), rB, bcol + HALF, t + 2);
;       WAIT_V(10); BAR; MMA(1, 1, At, B1); BAR;
.LBB0_565:
	ds_read_b128 v[128:131], v183
	ds_read_b128 v[132:135], v183 offset:1024
	ds_read_b128 v[136:139], v183 offset:2048
	ds_read_b128 v[140:143], v183 offset:3072
	s_add_i32 s64, s58, s63
	s_mov_b32 m0, s46
	s_add_i32 s6, s64, 0x4000
	ds_read_b128 v[144:147], v184
	ds_read_b128 v[148:151], v184 offset:1024
	ds_read_b128 v[152:155], v185
	ds_read_b128 v[156:159], v185 offset:1024
	ds_read_b128 v[160:163], v186
	ds_read_b128 v[164:167], v186 offset:1024
	ds_read_b128 v[168:171], v187
	ds_read_b128 v[192:195], v187 offset:1024
	buffer_load_dwordx4 v175, s[0:3], s6 offen lds
	s_mov_b32 m0, s47
	s_add_i32 s6, s64, 0x6000
	buffer_load_dwordx4 v175, s[0:3], s6 offen lds
	s_waitcnt vmcnt(10)
	s_waitcnt lgkmcnt(8)
	s_barrier
	s_waitcnt lgkmcnt(0)
	v_mfma_f32_16x16x32_bf16 v[124:127], v[128:131], v[144:147], v[124:127]
	v_mfma_f32_16x16x32_bf16 v[120:123], v[136:139], v[144:147], v[120:123]
	v_mfma_f32_16x16x32_bf16 v[116:119], v[128:131], v[152:155], v[116:119]
	v_mfma_f32_16x16x32_bf16 v[112:115], v[136:139], v[152:155], v[112:115]
	v_mfma_f32_16x16x32_bf16 v[108:111], v[128:131], v[160:163], v[108:111]
	v_mfma_f32_16x16x32_bf16 v[104:107], v[136:139], v[160:163], v[104:107]
	v_mfma_f32_16x16x32_bf16 v[100:103], v[128:131], v[168:171], v[100:103]
	v_mfma_f32_16x16x32_bf16 v[96:99], v[136:139], v[168:171], v[96:99]
	v_mfma_f32_16x16x32_bf16 v[124:127], v[132:135], v[148:151], v[124:127]
	v_mfma_f32_16x16x32_bf16 v[120:123], v[140:143], v[148:151], v[120:123]
	v_mfma_f32_16x16x32_bf16 v[116:119], v[132:135], v[156:159], v[116:119]
	v_mfma_f32_16x16x32_bf16 v[112:115], v[140:143], v[156:159], v[112:115]
	v_mfma_f32_16x16x32_bf16 v[108:111], v[132:135], v[164:167], v[108:111]
	v_mfma_f32_16x16x32_bf16 v[104:107], v[140:143], v[164:167], v[104:107]
	v_mfma_f32_16x16x32_bf16 v[100:103], v[132:135], v[192:195], v[100:103]
	v_mfma_f32_16x16x32_bf16 v[96:99], v[140:143], v[192:195], v[96:99]
	s_barrier
	s_add_i32 s65, s61, s63
	s_mov_b32 m0, s30
	s_add_i32 s66, s65, 0x8000
	s_mov_b32 s6, s2
	s_mov_b32 s7, s3
	ds_read_b128 v[196:199], v188
	ds_read_b128 v[200:203], v188 offset:1024
	ds_read_b128 v[204:207], v188 offset:2048
	ds_read_b128 v[208:211], v188 offset:3072
	buffer_load_dwordx4 v175, s[4:7], s66 offen lds
	s_mov_b32 m0, s31
	s_add_i32 s66, s65, 0xa000
	buffer_load_dwordx4 v175, s[4:7], s66 offen lds
	s_waitcnt vmcnt(10)
	s_barrier
	s_waitcnt lgkmcnt(0)
	v_mfma_f32_16x16x32_bf16 v[92:95], v[196:199], v[144:147], v[92:95]
	v_mfma_f32_16x16x32_bf16 v[88:91], v[204:207], v[144:147], v[88:91]
	v_mfma_f32_16x16x32_bf16 v[84:87], v[196:199], v[152:155], v[84:87]
	v_mfma_f32_16x16x32_bf16 v[80:83], v[204:207], v[152:155], v[80:83]
	v_mfma_f32_16x16x32_bf16 v[76:79], v[196:199], v[160:163], v[76:79]
	v_mfma_f32_16x16x32_bf16 v[72:75], v[204:207], v[160:163], v[72:75]
	v_mfma_f32_16x16x32_bf16 v[68:71], v[196:199], v[168:171], v[68:71]
	v_mfma_f32_16x16x32_bf16 v[64:67], v[204:207], v[168:171], v[64:67]
	v_mfma_f32_16x16x32_bf16 v[92:95], v[200:203], v[148:151], v[92:95]
	v_mfma_f32_16x16x32_bf16 v[88:91], v[208:211], v[148:151], v[88:91]
	v_mfma_f32_16x16x32_bf16 v[84:87], v[200:203], v[156:159], v[84:87]
	v_mfma_f32_16x16x32_bf16 v[80:83], v[208:211], v[156:159], v[80:83]
	v_mfma_f32_16x16x32_bf16 v[76:79], v[200:203], v[164:167], v[76:79]
	v_mfma_f32_16x16x32_bf16 v[72:75], v[208:211], v[164:167], v[72:75]
	v_mfma_f32_16x16x32_bf16 v[68:71], v[200:203], v[192:195], v[68:71]
	v_mfma_f32_16x16x32_bf16 v[64:67], v[208:211], v[192:195], v[64:67]
	s_add_i32 s66, s60, s63
	s_mov_b32 m0, s33
	s_add_i32 s67, s66, 0x8000
	s_barrier
	ds_read_b128 v[144:147], v184 offset:16384
	ds_read_b128 v[148:151], v184 offset:17408
	ds_read_b128 v[152:155], v185 offset:16384
	ds_read_b128 v[156:159], v185 offset:17408
	ds_read_b128 v[160:163], v186 offset:16384
	ds_read_b128 v[164:167], v186 offset:17408
	ds_read_b128 v[168:171], v187 offset:16384
	ds_read_b128 v[192:195], v187 offset:17408
	buffer_load_dwordx4 v175, s[0:3], s67 offen lds
	s_mov_b32 m0, s34
	s_add_i32 s67, s66, 0xa000
	buffer_load_dwordx4 v175, s[0:3], s67 offen lds
	s_barrier
	s_waitcnt lgkmcnt(0)
	v_mfma_f32_16x16x32_bf16 v[60:63], v[128:131], v[144:147], v[60:63]
	v_mfma_f32_16x16x32_bf16 v[56:59], v[136:139], v[144:147], v[56:59]
	v_mfma_f32_16x16x32_bf16 v[52:55], v[128:131], v[152:155], v[52:55]
	v_mfma_f32_16x16x32_bf16 v[48:51], v[136:139], v[152:155], v[48:51]
	v_mfma_f32_16x16x32_bf16 v[44:47], v[128:131], v[160:163], v[44:47]
	v_mfma_f32_16x16x32_bf16 v[40:43], v[136:139], v[160:163], v[40:43]
	v_mfma_f32_16x16x32_bf16 v[36:39], v[128:131], v[168:171], v[36:39]
	v_mfma_f32_16x16x32_bf16 v[32:35], v[136:139], v[168:171], v[32:35]
	v_mfma_f32_16x16x32_bf16 v[60:63], v[132:135], v[148:151], v[60:63]
	v_mfma_f32_16x16x32_bf16 v[56:59], v[140:143], v[148:151], v[56:59]
	v_mfma_f32_16x16x32_bf16 v[52:55], v[132:135], v[156:159], v[52:55]
	v_mfma_f32_16x16x32_bf16 v[48:51], v[140:143], v[156:159], v[48:51]
	v_mfma_f32_16x16x32_bf16 v[44:47], v[132:135], v[164:167], v[44:47]
	v_mfma_f32_16x16x32_bf16 v[40:43], v[140:143], v[164:167], v[40:43]
	v_mfma_f32_16x16x32_bf16 v[36:39], v[132:135], v[192:195], v[36:39]
	v_mfma_f32_16x16x32_bf16 v[32:35], v[140:143], v[192:195], v[32:35]
	s_barrier
	s_add_i32 s67, s59, s63
	s_mov_b32 m0, s35
	s_add_i32 s68, s67, 0x8000
	buffer_load_dwordx4 v175, s[4:7], s68 offen lds
	s_mov_b32 m0, s36
	s_add_i32 s68, s67, 0xa000
	buffer_load_dwordx4 v175, s[4:7], s68 offen lds
	s_waitcnt vmcnt(10)
	s_barrier
; #define LDA(dst, b, h)                                                                                               \
;   _Pragma("unroll") for (int m = 0; m < 4; ++m) _Pragma("unroll") for (int k = 0; k < 2; ++k) dst[m][k] =            \
;       *reinterpret_cast<const bf16x8*>(SA(b, h) + lds_byte(wr * 64 + m * 16 + fr, k * 32 + fq * 8))
; #define LDB(dst, b, h)                                                                                               \
;   _Pragma("unroll") for (int n = 0; n < 2; ++n) _Pragma("unroll") for (int k = 0; k < 2; ++k) dst[n][k] =            \
;       *reinterpret_cast<const bf16x8*>(SB(b, h) + lds_byte(wc * 32 + n * 16 + fr, k * 32 + fq * 8))
; #define WAIT_V(n) asm volatile("s_waitcnt vmcnt(" #n ")" ::: "memory")
; #define WAIT_L(n) asm volatile("s_waitcnt lgkmcnt(" #n ")" ::: "memory")
; #define BAR __builtin_amdgcn_s_barrier()
; #define SCHED __builtin_amdgcn_sched_barrier(0)
; template <int EPI>
; __device__ __forceinline__ void gemm_phase(const u16* __restrict__ A, const u16* __restrict__ Bt, const int K,
;                                            const int nN, char* shm, const EpiArgs& ea) {
;     ...
;       WAIT_V(10); BAR; WAIT_L(0); MMA(0, 1, At, B1); BAR;
;       LDA(At, 0, 1); STAGE(SA(0, 0), rA, brow, t + 2);
;       BAR; WAIT_L(0); MMA(1, 0, At, B0); BAR; SCHED;
;       STAGE(SB(0, 1), rB, bcol + HALF, t + 2);
;       WAIT_V(10); BAR; MMA(1, 1, At, B1); BAR;
;       LDB(B0, 1, 0); SCHED; LDA(At, 1, 0); STAGE(SA(0, 1), rA, brow + HALF, t + 2);
;       WAIT_V(10); WAIT_L(8); BAR; WAIT_L(0); MMA(0, 0, At, B0); BAR; SCHED;
;       LDB(B1, 1, 1); STAGE(SB(1, 0), rB, bcol, t + 3);
;       WAIT_V(10); BAR; WAIT_L(0); MMA(0, 1, At, B1); BAR;
	v_mfma_f32_16x16x32_bf16 v[28:31], v[196:199], v[144:147], v[28:31]
	v_mfma_f32_16x16x32_bf16 v[24:27], v[204:207], v[144:147], v[24:27]
	v_mfma_f32_16x16x32_bf16 v[20:23], v[196:199], v[152:155], v[20:23]
	v_mfma_f32_16x16x32_bf16 v[16:19], v[204:207], v[152:155], v[16:19]
	v_mfma_f32_16x16x32_bf16 v[12:15], v[196:199], v[160:163], v[12:15]
	v_mfma_f32_16x16x32_bf16 v[8:11], v[204:207], v[160:163], v[8:11]
	v_mfma_f32_16x16x32_bf16 v[4:7], v[196:199], v[168:171], v[4:7]
	v_mfma_f32_16x16x32_bf16 v[0:3], v[204:207], v[168:171], v[0:3]
	v_mfma_f32_16x16x32_bf16 v[28:31], v[200:203], v[148:151], v[28:31]
	v_mfma_f32_16x16x32_bf16 v[24:27], v[208:211], v[148:151], v[24:27]
	v_mfma_f32_16x16x32_bf16 v[20:23], v[200:203], v[156:159], v[20:23]
	v_mfma_f32_16x16x32_bf16 v[16:19], v[208:211], v[156:159], v[16:19]
	v_mfma_f32_16x16x32_bf16 v[12:15], v[200:203], v[164:167], v[12:15]
	v_mfma_f32_16x16x32_bf16 v[8:11], v[208:211], v[164:167], v[8:11]
	v_mfma_f32_16x16x32_bf16 v[4:7], v[200:203], v[192:195], v[4:7]
	v_mfma_f32_16x16x32_bf16 v[0:3], v[208:211], v[192:195], v[0:3]
	s_barrier
	ds_read_b128 v[128:131], v189
	ds_read_b128 v[132:135], v189 offset:1024
	ds_read_b128 v[136:139], v189 offset:2048
	ds_read_b128 v[140:143], v189 offset:3072
	s_mov_b32 m0, s37
	s_add_i32 s68, s64, 0x8000
	ds_read_b128 v[144:147], v184 offset:32768
	ds_read_b128 v[148:151], v184 offset:33792
	ds_read_b128 v[152:155], v185 offset:32768
	ds_read_b128 v[156:159], v185 offset:33792
	ds_read_b128 v[160:163], v186 offset:32768
	ds_read_b128 v[164:167], v186 offset:33792
	ds_read_b128 v[168:171], v187 offset:32768
	ds_read_b128 v[192:195], v187 offset:33792
	buffer_load_dwordx4 v175, s[0:3], s68 offen lds
	s_mov_b32 m0, s38
	s_add_i32 s64, s64, 0xa000
	buffer_load_dwordx4 v175, s[0:3], s64 offen lds
	s_waitcnt vmcnt(10)
	s_waitcnt lgkmcnt(8)
	s_barrier
	s_waitcnt lgkmcnt(0)
	v_mfma_f32_16x16x32_bf16 v[124:127], v[128:131], v[144:147], v[124:127]
	v_mfma_f32_16x16x32_bf16 v[120:123], v[136:139], v[144:147], v[120:123]
	v_mfma_f32_16x16x32_bf16 v[116:119], v[128:131], v[152:155], v[116:119]
	v_mfma_f32_16x16x32_bf16 v[112:115], v[136:139], v[152:155], v[112:115]
	v_mfma_f32_16x16x32_bf16 v[108:111], v[128:131], v[160:163], v[108:111]
	v_mfma_f32_16x16x32_bf16 v[104:107], v[136:139], v[160:163], v[104:107]
	v_mfma_f32_16x16x32_bf16 v[100:103], v[128:131], v[168:171], v[100:103]
	v_mfma_f32_16x16x32_bf16 v[96:99], v[136:139], v[168:171], v[96:99]
	v_mfma_f32_16x16x32_bf16 v[124:127], v[132:135], v[148:151], v[124:127]
	v_mfma_f32_16x16x32_bf16 v[120:123], v[140:143], v[148:151], v[120:123]
	v_mfma_f32_16x16x32_bf16 v[116:119], v[132:135], v[156:159], v[116:119]
	v_mfma_f32_16x16x32_bf16 v[112:115], v[140:143], v[156:159], v[112:115]
	v_mfma_f32_16x16x32_bf16 v[108:111], v[132:135], v[164:167], v[108:111]
	v_mfma_f32_16x16x32_bf16 v[104:107], v[140:143], v[164:167], v[104:107]
	v_mfma_f32_16x16x32_bf16 v[100:103], v[132:135], v[192:195], v[100:103]
	v_mfma_f32_16x16x32_bf16 v[96:99], v[140:143], v[192:195], v[96:99]
	s_barrier
	s_mov_b32 m0, s39
	s_add_i32 s64, s65, 0xc000
	ds_read_b128 v[196:199], v190
	ds_read_b128 v[200:203], v190 offset:1024
	ds_read_b128 v[204:207], v190 offset:2048
	ds_read_b128 v[208:211], v190 offset:3072
	buffer_load_dwordx4 v175, s[4:7], s64 offen lds
	s_mov_b32 m0, s40
	s_add_i32 s65, s65, 0xe000
	buffer_load_dwordx4 v175, s[4:7], s65 offen lds
	s_waitcnt vmcnt(10)
	s_barrier
; #define LDA(dst, b, h)                                                                                               \
;   _Pragma("unroll") for (int m = 0; m < 4; ++m) _Pragma("unroll") for (int k = 0; k < 2; ++k) dst[m][k] =            \
;       *reinterpret_cast<const bf16x8*>(SA(b, h) + lds_byte(wr * 64 + m * 16 + fr, k * 32 + fq * 8))
; #define LDB(dst, b, h)                                                                                               \
;   _Pragma("unroll") for (int n = 0; n < 2; ++n) _Pragma("unroll") for (int k = 0; k < 2; ++k) dst[n][k] =            \
;       *reinterpret_cast<const bf16x8*>(SB(b, h) + lds_byte(wc * 32 + n * 16 + fr, k * 32 + fq * 8))
; #define WAIT_V(n) asm volatile("s_waitcnt vmcnt(" #n ")" ::: "memory")
; #define WAIT_L(n) asm volatile("s_waitcnt lgkmcnt(" #n ")" ::: "memory")
; #define BAR __builtin_amdgcn_s_barrier()
; #define SCHED __builtin_amdgcn_sched_barrier(0)
; template <int EPI>
; __device__ __forceinline__ void gemm_phase(const u16* __restrict__ A, const u16* __restrict__ Bt, const int K,
;                                            const int nN, char* shm, const EpiArgs& ea) {
;     ...
;       WAIT_V(10); BAR; MMA(1, 1, At, B1); BAR;
;       LDB(B0, 1, 0); SCHED; LDA(At, 1, 0); STAGE(SA(0, 1), rA, brow + HALF, t + 2);
;       WAIT_V(10); WAIT_L(8); BAR; WAIT_L(0); MMA(0, 0, At, B0); BAR; SCHED;
;       LDB(B1, 1, 1); STAGE(SB(1, 0), rB, bcol, t + 3);
;       WAIT_V(10); BAR; WAIT_L(0); MMA(0, 1, At, B1); BAR;
;       LDA(At, 1, 1); STAGE(SA(1, 0), rA, brow, t + 3);
;       BAR; WAIT_L(0); MMA(1, 0, At, B0); BAR; SCHED;
;       STAGE(SB(1, 1), rB, bcol + HALF, t + 3);
;       WAIT_V(10); BAR; MMA(1, 1, At, B1); BAR;
;     }
;     float eC = 0.f, eB = 0.f;
;     float2 eS = make_float2(0.f, 0.f);
;     if (EPI == EPI_IN || EPI == EPI_SWIGLU_LN) {
;       if (wr == 0) {
;         eC = ea.c1[bcol + tid];
;         eS = *(const float2*)(ea.st_in + (size_t)(brow + tid) * 2);
;       } else {
;         eC = ea.c2[bcol + tid - 256];
;         if (EPI == EPI_IN) eB = ea.bias[bcol + tid - 256];
;       }
;     }
	s_waitcnt lgkmcnt(0)
	v_mfma_f32_16x16x32_bf16 v[92:95], v[196:199], v[144:147], v[92:95]
	v_mfma_f32_16x16x32_bf16 v[88:91], v[204:207], v[144:147], v[88:91]
	v_mfma_f32_16x16x32_bf16 v[84:87], v[196:199], v[152:155], v[84:87]
	v_mfma_f32_16x16x32_bf16 v[80:83], v[204:207], v[152:155], v[80:83]
	v_mfma_f32_16x16x32_bf16 v[76:79], v[196:199], v[160:163], v[76:79]
	v_mfma_f32_16x16x32_bf16 v[72:75], v[204:207], v[160:163], v[72:75]
	v_mfma_f32_16x16x32_bf16 v[68:71], v[196:199], v[168:171], v[68:71]
	v_mfma_f32_16x16x32_bf16 v[64:67], v[204:207], v[168:171], v[64:67]
	v_mfma_f32_16x16x32_bf16 v[92:95], v[200:203], v[148:151], v[92:95]
	v_mfma_f32_16x16x32_bf16 v[88:91], v[208:211], v[148:151], v[88:91]
	v_mfma_f32_16x16x32_bf16 v[84:87], v[200:203], v[156:159], v[84:87]
	v_mfma_f32_16x16x32_bf16 v[80:83], v[208:211], v[156:159], v[80:83]
	v_mfma_f32_16x16x32_bf16 v[76:79], v[200:203], v[164:167], v[76:79]
	v_mfma_f32_16x16x32_bf16 v[72:75], v[208:211], v[164:167], v[72:75]
	v_mfma_f32_16x16x32_bf16 v[68:71], v[200:203], v[192:195], v[68:71]
	v_mfma_f32_16x16x32_bf16 v[64:67], v[208:211], v[192:195], v[64:67]
	s_mov_b32 m0, s41
	s_add_i32 s64, s66, 0xc000
	s_barrier
	ds_read_b128 v[144:147], v184 offset:49152
	ds_read_b128 v[148:151], v184 offset:50176
	ds_read_b128 v[152:155], v185 offset:49152
	ds_read_b128 v[156:159], v185 offset:50176
	ds_read_b128 v[160:163], v186 offset:49152
	ds_read_b128 v[164:167], v186 offset:50176
	ds_read_b128 v[168:171], v187 offset:49152
	ds_read_b128 v[192:195], v187 offset:50176
	buffer_load_dwordx4 v175, s[0:3], s64 offen lds
	s_mov_b32 m0, s42
	s_add_i32 s66, s66, 0xe000
	buffer_load_dwordx4 v175, s[0:3], s66 offen lds
	s_barrier
	s_waitcnt lgkmcnt(0)
	v_mfma_f32_16x16x32_bf16 v[60:63], v[128:131], v[144:147], v[60:63]
	v_mfma_f32_16x16x32_bf16 v[56:59], v[136:139], v[144:147], v[56:59]
	v_mfma_f32_16x16x32_bf16 v[52:55], v[128:131], v[152:155], v[52:55]
	v_mfma_f32_16x16x32_bf16 v[48:51], v[136:139], v[152:155], v[48:51]
	v_mfma_f32_16x16x32_bf16 v[44:47], v[128:131], v[160:163], v[44:47]
	v_mfma_f32_16x16x32_bf16 v[40:43], v[136:139], v[160:163], v[40:43]
	v_mfma_f32_16x16x32_bf16 v[36:39], v[128:131], v[168:171], v[36:39]
	v_mfma_f32_16x16x32_bf16 v[32:35], v[136:139], v[168:171], v[32:35]
	v_mfma_f32_16x16x32_bf16 v[60:63], v[132:135], v[148:151], v[60:63]
	v_mfma_f32_16x16x32_bf16 v[56:59], v[140:143], v[148:151], v[56:59]
	v_mfma_f32_16x16x32_bf16 v[52:55], v[132:135], v[156:159], v[52:55]
	v_mfma_f32_16x16x32_bf16 v[48:51], v[140:143], v[156:159], v[48:51]
	v_mfma_f32_16x16x32_bf16 v[44:47], v[132:135], v[164:167], v[44:47]
	v_mfma_f32_16x16x32_bf16 v[40:43], v[140:143], v[164:167], v[40:43]
	v_mfma_f32_16x16x32_bf16 v[36:39], v[132:135], v[192:195], v[36:39]
	v_mfma_f32_16x16x32_bf16 v[32:35], v[140:143], v[192:195], v[32:35]
	s_barrier
	s_mov_b32 m0, s43
	s_add_i32 s64, s67, 0xc000
	buffer_load_dwordx4 v175, s[4:7], s64 offen lds
	s_mov_b32 m0, s44
	s_add_i32 s67, s67, 0xe000
	buffer_load_dwordx4 v175, s[4:7], s67 offen lds
	s_waitcnt vmcnt(10)
	s_barrier
	v_mfma_f32_16x16x32_bf16 v[28:31], v[196:199], v[144:147], v[28:31]
	v_mfma_f32_16x16x32_bf16 v[24:27], v[204:207], v[144:147], v[24:27]
	v_mfma_f32_16x16x32_bf16 v[20:23], v[196:199], v[152:155], v[20:23]
	v_mfma_f32_16x16x32_bf16 v[16:19], v[204:207], v[152:155], v[16:19]
	v_mfma_f32_16x16x32_bf16 v[12:15], v[196:199], v[160:163], v[12:15]
	v_mfma_f32_16x16x32_bf16 v[8:11], v[204:207], v[160:163], v[8:11]
	v_mfma_f32_16x16x32_bf16 v[4:7], v[196:199], v[168:171], v[4:7]
	v_mfma_f32_16x16x32_bf16 v[0:3], v[204:207], v[168:171], v[0:3]
	v_mfma_f32_16x16x32_bf16 v[28:31], v[200:203], v[148:151], v[28:31]
	v_mfma_f32_16x16x32_bf16 v[24:27], v[208:211], v[148:151], v[24:27]
	v_mfma_f32_16x16x32_bf16 v[20:23], v[200:203], v[156:159], v[20:23]
	v_mfma_f32_16x16x32_bf16 v[16:19], v[208:211], v[156:159], v[16:19]
	v_mfma_f32_16x16x32_bf16 v[12:15], v[200:203], v[164:167], v[12:15]
	v_mfma_f32_16x16x32_bf16 v[8:11], v[208:211], v[164:167], v[8:11]
	v_mfma_f32_16x16x32_bf16 v[4:7], v[200:203], v[192:195], v[4:7]
	v_mfma_f32_16x16x32_bf16 v[0:3], v[208:211], v[192:195], v[0:3]
	s_add_i32 s62, s62, 2
	s_add_i32 s63, s63, 0x8000
	s_cmp_lt_u32 s62, 28
	s_barrier
	s_cbranch_scc1 .LBB0_565
	v_add_u32_e32 v128, s57, v174
	v_ashrrev_i32_e32 v129, 31, v128
	s_mov_b64 s[6:7], -1
	s_and_b64 vcc, exec, s[18:19]
	s_cbranch_vccz .LBB0_568
	v_lshl_add_u64 v[130:131], v[128:129], 2, s[90:91]
	v_lshl_add_u64 v[130:131], v[130:131], 0, s[20:21]
	s_mov_b64 s[6:7], 0

; #define LDA(dst, b, h)                                                                                               \
;   _Pragma("unroll") for (int m = 0; m < 4; ++m) _Pragma("unroll") for (int k = 0; k < 2; ++k) dst[m][k] =            \
;       *reinterpret_cast<const bf16x8*>(SA(b, h) + lds_byte(wr * 64 + m * 16 + fr, k * 32 + fq * 8))
; #define LDB(dst, b, h)                                                                                               \
;   _Pragma("unroll") for (int n = 0; n < 2; ++n) _Pragma("unroll") for (int k = 0; k < 2; ++k) dst[n][k] =            \
;       *reinterpret_cast<const bf16x8*>(SB(b, h) + lds_byte(wc * 32 + n * 16 + fr, k * 32 + fq * 8))
; #define WAIT_V(n) asm volatile("s_waitcnt vmcnt(" #n ")" ::: "memory")
; #define WAIT_L(n) asm volatile("s_waitcnt lgkmcnt(" #n ")" ::: "memory")
; #define BAR __builtin_amdgcn_s_barrier()
; template <int EPI>
; __device__ __forceinline__ void gemm_phase(const u16* __restrict__ A, const u16* __restrict__ Bt, const int K,
;                                            const int nN, char* shm, const EpiArgs& ea) {
;     ...
;         eC = ea.c1[bcol + tid];
;         eS = *(const float2*)(ea.st_in + (size_t)(brow + tid) * 2);
;       } else {
;         eC = ea.c2[bcol + tid - 256];
;         if (EPI == EPI_IN) eB = ea.bias[bcol + tid - 256];
;       }
;     }
;     {
;       LDB(B0, 0, 0); LDA(At, 0, 0); STAGE(SA(1, 1), rA, brow + HALF, nt - 1);
;       WAIT_V(10); BAR; WAIT_L(0); MMA(0, 0, At, B0); BAR;
;       LDB(B1, 0, 1); WAIT_V(8); BAR; WAIT_L(0); MMA(0, 1, At, B1); BAR;
;       LDA(At, 0, 1); WAIT_V(4); BAR; WAIT_L(0); MMA(1, 0, At, B0); MMA(1, 1, At, B1); BAR;
;     }
;     {
;       LDB(B0, 1, 0); LDA(At, 1, 0); WAIT_V(2); BAR; WAIT_L(0); MMA(0, 0, At, B0); BAR;
;       LDB(B1, 1, 1); WAIT_V(0); BAR; WAIT_L(0); MMA(0, 1, At, B1); BAR;
;       LDA(At, 1, 1); BAR; WAIT_L(0); MMA(1, 0, At, B0); MMA(1, 1, At, B1); BAR;
.LBB0_570:
	s_mov_b32 m0, s46
	s_add_i32 s6, s58, 0x7c000
	global_load_dword v154, v[130:131], off
	ds_read_b128 v[128:131], v183
	ds_read_b128 v[132:135], v183 offset:1024
	ds_read_b128 v[136:139], v183 offset:2048
	ds_read_b128 v[140:143], v183 offset:3072
	ds_read_b128 v[144:147], v184
	ds_read_b128 v[148:151], v184 offset:1024
	ds_read_b128 v[156:159], v185
	ds_read_b128 v[160:163], v185 offset:1024
	ds_read_b128 v[164:167], v186
	ds_read_b128 v[168:171], v186 offset:1024
	ds_read_b128 v[192:195], v187
	ds_read_b128 v[196:199], v187 offset:1024
	buffer_load_dwordx4 v175, s[0:3], s6 offen lds
	s_mov_b32 m0, s47
	s_add_i32 s58, s58, 0x7e000
	buffer_load_dwordx4 v175, s[0:3], s58 offen lds
	s_waitcnt vmcnt(10)
	s_barrier
	s_waitcnt lgkmcnt(0)
	v_mfma_f32_16x16x32_bf16 v[124:127], v[128:131], v[144:147], v[124:127]
	v_mfma_f32_16x16x32_bf16 v[120:123], v[136:139], v[144:147], v[120:123]
	v_mfma_f32_16x16x32_bf16 v[116:119], v[128:131], v[156:159], v[116:119]
	v_mfma_f32_16x16x32_bf16 v[112:115], v[136:139], v[156:159], v[112:115]
	v_mfma_f32_16x16x32_bf16 v[108:111], v[128:131], v[164:167], v[108:111]
	v_mfma_f32_16x16x32_bf16 v[104:107], v[136:139], v[164:167], v[104:107]
	v_mfma_f32_16x16x32_bf16 v[100:103], v[128:131], v[192:195], v[100:103]
	v_mfma_f32_16x16x32_bf16 v[96:99], v[136:139], v[192:195], v[96:99]
	v_mfma_f32_16x16x32_bf16 v[124:127], v[132:135], v[148:151], v[124:127]
	v_mfma_f32_16x16x32_bf16 v[120:123], v[140:143], v[148:151], v[120:123]
	v_mfma_f32_16x16x32_bf16 v[116:119], v[132:135], v[160:163], v[116:119]
	v_mfma_f32_16x16x32_bf16 v[112:115], v[140:143], v[160:163], v[112:115]
	v_mfma_f32_16x16x32_bf16 v[108:111], v[132:135], v[168:171], v[108:111]
	v_mfma_f32_16x16x32_bf16 v[104:107], v[140:143], v[168:171], v[104:107]
	v_mfma_f32_16x16x32_bf16 v[100:103], v[132:135], v[196:199], v[100:103]
	v_mfma_f32_16x16x32_bf16 v[96:99], v[140:143], v[196:199], v[96:99]
	s_barrier
	ds_read_b128 v[200:203], v188
	ds_read_b128 v[204:207], v188 offset:1024
	ds_read_b128 v[208:211], v188 offset:2048
	ds_read_b128 v[212:215], v188 offset:3072
	s_waitcnt vmcnt(8)
	s_barrier
	s_waitcnt lgkmcnt(0)
	v_mfma_f32_16x16x32_bf16 v[92:95], v[200:203], v[144:147], v[92:95]
	v_mfma_f32_16x16x32_bf16 v[88:91], v[208:211], v[144:147], v[88:91]
	v_mfma_f32_16x16x32_bf16 v[84:87], v[200:203], v[156:159], v[84:87]
	v_mfma_f32_16x16x32_bf16 v[80:83], v[208:211], v[156:159], v[80:83]
	v_mfma_f32_16x16x32_bf16 v[76:79], v[200:203], v[164:167], v[76:79]
	v_mfma_f32_16x16x32_bf16 v[72:75], v[208:211], v[164:167], v[72:75]
	v_mfma_f32_16x16x32_bf16 v[68:71], v[200:203], v[192:195], v[68:71]
	v_mfma_f32_16x16x32_bf16 v[92:95], v[204:207], v[148:151], v[92:95]
	v_mfma_f32_16x16x32_bf16 v[88:91], v[212:215], v[148:151], v[88:91]
	v_mfma_f32_16x16x32_bf16 v[84:87], v[204:207], v[160:163], v[84:87]
	v_mfma_f32_16x16x32_bf16 v[80:83], v[212:215], v[160:163], v[80:83]
	v_mfma_f32_16x16x32_bf16 v[76:79], v[204:207], v[168:171], v[76:79]
	v_mfma_f32_16x16x32_bf16 v[72:75], v[212:215], v[168:171], v[72:75]
	v_mfma_f32_16x16x32_bf16 v[68:71], v[204:207], v[196:199], v[68:71]
	v_mfma_f32_16x16x32_bf16 v[64:67], v[208:211], v[192:195], v[64:67]
	v_mfma_f32_16x16x32_bf16 v[64:67], v[212:215], v[196:199], v[64:67]
	s_barrier
	ds_read_b128 v[144:147], v184 offset:16384
	ds_read_b128 v[148:151], v184 offset:17408
	ds_read_b128 v[156:159], v185 offset:16384
	ds_read_b128 v[160:163], v185 offset:17408
	ds_read_b128 v[164:167], v186 offset:16384
	ds_read_b128 v[168:171], v186 offset:17408
	ds_read_b128 v[192:195], v187 offset:16384
	ds_read_b128 v[196:199], v187 offset:17408
	s_waitcnt vmcnt(4)
	s_barrier
	s_waitcnt lgkmcnt(0)
	v_mfma_f32_16x16x32_bf16 v[40:43], v[136:139], v[164:167], v[40:43]
	v_mfma_f32_16x16x32_bf16 v[36:39], v[128:131], v[192:195], v[36:39]
	v_mfma_f32_16x16x32_bf16 v[60:63], v[128:131], v[144:147], v[60:63]
	v_mfma_f32_16x16x32_bf16 v[56:59], v[136:139], v[144:147], v[56:59]
	v_mfma_f32_16x16x32_bf16 v[52:55], v[128:131], v[156:159], v[52:55]
	v_mfma_f32_16x16x32_bf16 v[48:51], v[136:139], v[156:159], v[48:51]
	v_mfma_f32_16x16x32_bf16 v[44:47], v[128:131], v[164:167], v[44:47]
	v_mfma_f32_16x16x32_bf16 v[40:43], v[140:143], v[168:171], v[40:43]
	v_mfma_f32_16x16x32_bf16 v[36:39], v[132:135], v[196:199], v[36:39]
	v_mfma_f32_16x16x32_bf16 v[32:35], v[136:139], v[192:195], v[32:35]
	v_mfma_f32_16x16x32_bf16 v[60:63], v[132:135], v[148:151], v[60:63]
	v_mfma_f32_16x16x32_bf16 v[56:59], v[140:143], v[148:151], v[56:59]
	v_mfma_f32_16x16x32_bf16 v[52:55], v[132:135], v[160:163], v[52:55]
	v_mfma_f32_16x16x32_bf16 v[48:51], v[140:143], v[160:163], v[48:51]
	v_mfma_f32_16x16x32_bf16 v[44:47], v[132:135], v[168:171], v[44:47]
	v_mfma_f32_16x16x32_bf16 v[32:35], v[140:143], v[196:199], v[32:35]
	v_mfma_f32_16x16x32_bf16 v[12:15], v[200:203], v[164:167], v[12:15]
	v_mfma_f32_16x16x32_bf16 v[8:11], v[208:211], v[164:167], v[8:11]
	v_mfma_f32_16x16x32_bf16 v[4:7], v[200:203], v[192:195], v[4:7]
	v_mfma_f32_16x16x32_bf16 v[0:3], v[208:211], v[192:195], v[0:3]
	v_mfma_f32_16x16x32_bf16 v[28:31], v[200:203], v[144:147], v[28:31]
	v_mfma_f32_16x16x32_bf16 v[24:27], v[208:211], v[144:147], v[24:27]
	v_mfma_f32_16x16x32_bf16 v[20:23], v[200:203], v[156:159], v[20:23]
	v_mfma_f32_16x16x32_bf16 v[16:19], v[208:211], v[156:159], v[16:19]
	v_mfma_f32_16x16x32_bf16 v[12:15], v[204:207], v[168:171], v[12:15]
	v_mfma_f32_16x16x32_bf16 v[8:11], v[212:215], v[168:171], v[8:11]
	v_mfma_f32_16x16x32_bf16 v[4:7], v[204:207], v[196:199], v[4:7]
	v_mfma_f32_16x16x32_bf16 v[0:3], v[212:215], v[196:199], v[0:3]
	v_mfma_f32_16x16x32_bf16 v[216:219], v[204:207], v[148:151], v[28:31]
	v_mfma_f32_16x16x32_bf16 v[220:223], v[212:215], v[148:151], v[24:27]
	v_mfma_f32_16x16x32_bf16 v[224:227], v[204:207], v[160:163], v[20:23]
	v_mfma_f32_16x16x32_bf16 v[160:163], v[212:215], v[160:163], v[16:19]
	s_barrier
; #define LDA(dst, b, h)                                                                                               \
;   _Pragma("unroll") for (int m = 0; m < 4; ++m) _Pragma("unroll") for (int k = 0; k < 2; ++k) dst[m][k] =            \
;       *reinterpret_cast<const bf16x8*>(SA(b, h) + lds_byte(wr * 64 + m * 16 + fr, k * 32 + fq * 8))
; #define LDB(dst, b, h)                                                                                               \
;   _Pragma("unroll") for (int n = 0; n < 2; ++n) _Pragma("unroll") for (int k = 0; k < 2; ++k) dst[n][k] =            \
;       *reinterpret_cast<const bf16x8*>(SB(b, h) + lds_byte(wc * 32 + n * 16 + fr, k * 32 + fq * 8))
; #define WAIT_V(n) asm volatile("s_waitcnt vmcnt(" #n ")" ::: "memory")
; #define WAIT_L(n) asm volatile("s_waitcnt lgkmcnt(" #n ")" ::: "memory")
; #define BAR __builtin_amdgcn_s_barrier()
; template <int EPI>
; __device__ __forceinline__ void gemm_phase(const u16* __restrict__ A, const u16* __restrict__ Bt, const int K,
;                                            const int nN, char* shm, const EpiArgs& ea) {
;     ...
;     {
;       LDB(B0, 1, 0); LDA(At, 1, 0); WAIT_V(2); BAR; WAIT_L(0); MMA(0, 0, At, B0); BAR;
;       LDB(B1, 1, 1); WAIT_V(0); BAR; WAIT_L(0); MMA(0, 1, At, B1); BAR;
;       LDA(At, 1, 1); BAR; WAIT_L(0); MMA(1, 0, At, B0); MMA(1, 1, At, B1); BAR;
;     }
;     if (wr == 0) BAR;
;     if (has_next) STAGE7(brow2, bcol2);
	s_nop 0
	ds_read_b128 v[16:19], v189
	ds_read_b128 v[20:23], v189 offset:1024
	ds_read_b128 v[164:167], v189 offset:2048
	ds_read_b128 v[168:171], v189 offset:3072
	ds_read_b128 v[24:27], v184 offset:32768
	ds_read_b128 v[28:31], v184 offset:33792
	ds_read_b128 v[192:195], v185 offset:32768
	ds_read_b128 v[196:199], v185 offset:33792
	ds_read_b128 v[200:203], v186 offset:32768
	ds_read_b128 v[204:207], v186 offset:33792
	ds_read_b128 v[208:211], v187 offset:32768
	ds_read_b128 v[212:215], v187 offset:33792
	s_waitcnt vmcnt(2)
	s_barrier
	s_waitcnt lgkmcnt(0)
	v_mfma_f32_16x16x32_bf16 v[124:127], v[16:19], v[24:27], v[124:127]
	v_mfma_f32_16x16x32_bf16 v[120:123], v[164:167], v[24:27], v[120:123]
	v_mfma_f32_16x16x32_bf16 v[116:119], v[16:19], v[192:195], v[116:119]
	v_mfma_f32_16x16x32_bf16 v[112:115], v[164:167], v[192:195], v[112:115]
	v_mfma_f32_16x16x32_bf16 v[108:111], v[16:19], v[200:203], v[108:111]
	v_mfma_f32_16x16x32_bf16 v[104:107], v[164:167], v[200:203], v[104:107]
	v_mfma_f32_16x16x32_bf16 v[100:103], v[16:19], v[208:211], v[100:103]
	v_mfma_f32_16x16x32_bf16 v[96:99], v[164:167], v[208:211], v[96:99]
	v_mfma_f32_16x16x32_bf16 v[156:159], v[20:23], v[28:31], v[124:127]
	v_mfma_f32_16x16x32_bf16 v[148:151], v[168:171], v[28:31], v[120:123]
	v_mfma_f32_16x16x32_bf16 v[144:147], v[20:23], v[196:199], v[116:119]
	v_mfma_f32_16x16x32_bf16 v[140:143], v[168:171], v[196:199], v[112:115]
	v_mfma_f32_16x16x32_bf16 v[120:123], v[20:23], v[204:207], v[108:111]
	v_mfma_f32_16x16x32_bf16 v[116:119], v[168:171], v[204:207], v[104:107]
	v_mfma_f32_16x16x32_bf16 v[112:115], v[20:23], v[212:215], v[100:103]
	v_mfma_f32_16x16x32_bf16 v[108:111], v[168:171], v[212:215], v[96:99]
	s_barrier
	ds_read_b128 v[228:231], v190
	ds_read_b128 v[232:235], v190 offset:1024
	ds_read_b128 v[236:239], v190 offset:2048
	ds_read_b128 v[240:243], v190 offset:3072
	s_waitcnt vmcnt(0)
	s_barrier
	s_waitcnt lgkmcnt(0)
	v_mfma_f32_16x16x32_bf16 v[92:95], v[228:231], v[24:27], v[92:95]
	v_mfma_f32_16x16x32_bf16 v[24:27], v[236:239], v[24:27], v[88:91]
	v_mfma_f32_16x16x32_bf16 v[132:135], v[240:243], v[28:31], v[24:27]
	v_mfma_f32_16x16x32_bf16 v[24:27], v[228:231], v[192:195], v[84:87]
	v_mfma_f32_16x16x32_bf16 v[128:131], v[232:235], v[196:199], v[24:27]
	v_mfma_f32_16x16x32_bf16 v[24:27], v[236:239], v[192:195], v[80:83]
	v_mfma_f32_16x16x32_bf16 v[124:127], v[240:243], v[196:199], v[24:27]
	v_mfma_f32_16x16x32_bf16 v[24:27], v[228:231], v[200:203], v[76:79]
	v_mfma_f32_16x16x32_bf16 v[104:107], v[232:235], v[204:207], v[24:27]
	v_mfma_f32_16x16x32_bf16 v[24:27], v[236:239], v[200:203], v[72:75]
	v_mfma_f32_16x16x32_bf16 v[100:103], v[240:243], v[204:207], v[24:27]
	v_mfma_f32_16x16x32_bf16 v[24:27], v[228:231], v[208:211], v[68:71]
	v_mfma_f32_16x16x32_bf16 v[96:99], v[232:235], v[212:215], v[24:27]
	v_mfma_f32_16x16x32_bf16 v[24:27], v[236:239], v[208:211], v[64:67]
	v_mfma_f32_16x16x32_bf16 v[136:139], v[232:235], v[28:31], v[92:95]
	v_mfma_f32_16x16x32_bf16 v[92:95], v[240:243], v[212:215], v[24:27]
	s_barrier
	ds_read_b128 v[64:67], v184 offset:49152
	ds_read_b128 v[68:71], v184 offset:50176
	ds_read_b128 v[192:195], v185 offset:49152
	ds_read_b128 v[196:199], v185 offset:50176
	ds_read_b128 v[200:203], v186 offset:49152
	ds_read_b128 v[204:207], v186 offset:50176
	ds_read_b128 v[208:211], v187 offset:49152
	ds_read_b128 v[212:215], v187 offset:50176
	s_barrier
	s_waitcnt lgkmcnt(0)
	v_mfma_f32_16x16x32_bf16 v[24:27], v[16:19], v[64:67], v[60:63]
	v_mfma_f32_16x16x32_bf16 v[88:91], v[20:23], v[68:71], v[24:27]
	v_mfma_f32_16x16x32_bf16 v[24:27], v[164:167], v[64:67], v[56:59]
	v_mfma_f32_16x16x32_bf16 v[84:87], v[168:171], v[68:71], v[24:27]
	v_mfma_f32_16x16x32_bf16 v[24:27], v[16:19], v[192:195], v[52:55]
	v_mfma_f32_16x16x32_bf16 v[80:83], v[20:23], v[196:199], v[24:27]
	v_mfma_f32_16x16x32_bf16 v[24:27], v[164:167], v[192:195], v[48:51]
	v_mfma_f32_16x16x32_bf16 v[76:79], v[168:171], v[196:199], v[24:27]
	v_mfma_f32_16x16x32_bf16 v[24:27], v[16:19], v[200:203], v[44:47]
	v_mfma_f32_16x16x32_bf16 v[16:19], v[16:19], v[208:211], v[36:39]
	v_mfma_f32_16x16x32_bf16 v[28:31], v[20:23], v[204:207], v[24:27]
	v_mfma_f32_16x16x32_bf16 v[24:27], v[164:167], v[200:203], v[40:43]
	v_mfma_f32_16x16x32_bf16 v[20:23], v[20:23], v[212:215], v[16:19]
	v_mfma_f32_16x16x32_bf16 v[16:19], v[164:167], v[208:211], v[32:35]
	v_mfma_f32_16x16x32_bf16 v[24:27], v[168:171], v[204:207], v[24:27]
	v_mfma_f32_16x16x32_bf16 v[16:19], v[168:171], v[212:215], v[16:19]
	v_mfma_f32_16x16x32_bf16 v[32:35], v[228:231], v[64:67], v[216:219]
	v_mfma_f32_16x16x32_bf16 v[72:75], v[232:235], v[68:71], v[32:35]
	v_mfma_f32_16x16x32_bf16 v[32:35], v[236:239], v[64:67], v[220:223]
	v_mfma_f32_16x16x32_bf16 v[68:71], v[240:243], v[68:71], v[32:35]
	v_mfma_f32_16x16x32_bf16 v[32:35], v[228:231], v[192:195], v[224:227]
	v_mfma_f32_16x16x32_bf16 v[40:43], v[232:235], v[196:199], v[32:35]
	v_mfma_f32_16x16x32_bf16 v[32:35], v[236:239], v[192:195], v[160:163]
	v_mfma_f32_16x16x32_bf16 v[12:15], v[228:231], v[200:203], v[12:15]
	v_mfma_f32_16x16x32_bf16 v[8:11], v[236:239], v[200:203], v[8:11]
	v_mfma_f32_16x16x32_bf16 v[4:7], v[228:231], v[208:211], v[4:7]
	v_mfma_f32_16x16x32_bf16 v[0:3], v[236:239], v[208:211], v[0:3]
	v_mfma_f32_16x16x32_bf16 v[36:39], v[240:243], v[196:199], v[32:35]
	v_mfma_f32_16x16x32_bf16 v[12:15], v[232:235], v[204:207], v[12:15]
	v_mfma_f32_16x16x32_bf16 v[8:11], v[240:243], v[204:207], v[8:11]
	v_mfma_f32_16x16x32_bf16 v[4:7], v[232:235], v[212:215], v[4:7]
	v_mfma_f32_16x16x32_bf16 v[0:3], v[240:243], v[212:215], v[0:3]
	s_andn2_b64 vcc, exec, s[16:17]
	s_barrier
	s_cbranch_vccz .LBB0_574
	s_andn2_b64 vcc, exec, s[28:29]
	s_cbranch_vccz .LBB0_575

; template <int EPI>
; __device__ __forceinline__ void gemm_phase(const u16* __restrict__ A, const u16* __restrict__ Bt, const int K,
;                                            const int nN, char* shm, const EpiArgs& ea) {
;     ...
;     if (has_next) STAGE7(brow2, bcol2);
.LBB0_575:
	s_lshr_b32 s6, s53, 7
	s_mov_b32 m0, s30
	s_mul_i32 s28, s6, 0x84000
	s_mov_b32 s6, s2
	s_mov_b32 s7, s3
	buffer_load_dwordx4 v175, s[4:7], s28 offen lds
	s_mov_b32 m0, s31
	s_or_b32 s29, s28, 0x2000
	buffer_load_dwordx4 v175, s[4:7], s29 offen lds
	s_lshr_b32 s29, s54, 7
	s_mul_i32 s29, s29, 0x84000
	s_mov_b32 m0, s33
	s_or_b32 s57, s29, 0x2000
	buffer_load_dwordx4 v175, s[0:3], s29 offen lds
	s_mov_b32 m0, s34
	s_nop 0
	buffer_load_dwordx4 v175, s[0:3], s57 offen lds
	s_mov_b32 m0, s35
	s_add_i32 s57, s28, 0x84000
	buffer_load_dwordx4 v175, s[4:7], s57 offen lds
	s_mov_b32 m0, s36
	s_add_i32 s57, s28, 0x86000
	buffer_load_dwordx4 v175, s[4:7], s57 offen lds
	s_mov_b32 m0, s37
	s_add_i32 s57, s29, 0x84000
	buffer_load_dwordx4 v175, s[0:3], s57 offen lds
	s_mov_b32 m0, s38
	s_add_i32 s57, s29, 0x86000
	buffer_load_dwordx4 v175, s[0:3], s57 offen lds
	s_mov_b32 m0, s39
	s_or_b32 s57, s28, 0x4000
	buffer_load_dwordx4 v175, s[4:7], s57 offen lds
	s_mov_b32 m0, s40
	s_or_b32 s57, s28, 0x6000
	buffer_load_dwordx4 v175, s[4:7], s57 offen lds
	s_or_b32 s57, s29, 0x4000
	s_mov_b32 m0, s41
	s_or_b32 s29, s29, 0x6000
	buffer_load_dwordx4 v175, s[0:3], s57 offen lds
	s_mov_b32 m0, s42
	s_nop 0
	buffer_load_dwordx4 v175, s[0:3], s29 offen lds
	s_add_i32 s29, s28, 0x88000
	s_mov_b32 m0, s43
	s_add_i32 s28, s28, 0x8a000
	buffer_load_dwordx4 v175, s[4:7], s29 offen lds
	s_mov_b32 m0, s44
	s_nop 0
	buffer_load_dwordx4 v175, s[4:7], s28 offen lds
	s_mov_b64 s[6:7], -1
	s_and_b64 vcc, exec, s[18:19]
	s_cbranch_vccz .LBB0_573

; #define LDA(dst, b, h)                                                                                               \
;   _Pragma("unroll") for (int m = 0; m < 4; ++m) _Pragma("unroll") for (int k = 0; k < 2; ++k) dst[m][k] =            \
;       *reinterpret_cast<const bf16x8*>(SA(b, h) + lds_byte(wr * 64 + m * 16 + fr, k * 32 + fq * 8))
; #define LDB(dst, b, h)                                                                                               \
;   _Pragma("unroll") for (int n = 0; n < 2; ++n) _Pragma("unroll") for (int k = 0; k < 2; ++k) dst[n][k] =            \
;       *reinterpret_cast<const bf16x8*>(SB(b, h) + lds_byte(wc * 32 + n * 16 + fr, k * 32 + fq * 8))
; #define WAIT_V(n) asm volatile("s_waitcnt vmcnt(" #n ")" ::: "memory")
; #define WAIT_L(n) asm volatile("s_waitcnt lgkmcnt(" #n ")" ::: "memory")
; #define BAR __builtin_amdgcn_s_barrier()
; #define SCHED __builtin_amdgcn_sched_barrier(0)
; template <int EPI>
; __device__ __forceinline__ void gemm_phase(const u16* __restrict__ A, const u16* __restrict__ Bt, const int K,
;                                            const int nN, char* shm, const EpiArgs& ea) {
;     ...
;     for (int t = 0; t < nt - 2; t += 2) {
;       LDB(B0, 0, 0); SCHED; LDA(At, 0, 0); STAGE(SA(1, 1), rA, brow + HALF, t + 1);
;       WAIT_V(10); WAIT_L(8); BAR; WAIT_L(0); MMA(0, 0, At, B0); BAR; SCHED;
;       LDB(B1, 0, 1); STAGE(SB(0, 0), rB, bcol, t + 2);
;       WAIT_V(10); BAR; WAIT_L(0); MMA(0, 1, At, B1); BAR;
;       LDA(At, 0, 1); STAGE(SA(0, 0), rA, brow, t + 2);
;       BAR; WAIT_L(0); MMA(1, 0, At, B0); BAR; SCHED;
;       STAGE(SB(0, 1), rB, bcol + HALF, t + 2);
;       WAIT_V(10); BAR; MMA(1, 1, At, B1); BAR;
.LBB0_631:
	ds_read_b128 v[130:133], v141
	ds_read_b128 v[134:137], v141 offset:1024
	ds_read_b128 v[150:153], v141 offset:2048
	ds_read_b128 v[154:157], v141 offset:3072
	s_add_i32 s54, s48, s53
	s_mov_b32 m0, s41
	s_add_i32 s6, s54, 0x4000
	ds_read_b128 v[158:161], v142
	ds_read_b128 v[162:165], v142 offset:1024
	ds_read_b128 v[166:169], v143
	ds_read_b128 v[170:173], v143 offset:1024
	ds_read_b128 v[176:179], v144
	ds_read_b128 v[180:183], v144 offset:1024
	ds_read_b128 v[184:187], v145
	ds_read_b128 v[188:191], v145 offset:1024
	buffer_load_dwordx4 v138, s[0:3], s6 offen lds
	s_mov_b32 m0, s42
	s_add_i32 s6, s54, 0x6000
	buffer_load_dwordx4 v138, s[0:3], s6 offen lds
	s_waitcnt vmcnt(10)
	s_waitcnt lgkmcnt(8)
	s_barrier
	s_waitcnt lgkmcnt(0)
	v_mfma_f32_16x16x32_bf16 v[124:127], v[130:133], v[158:161], v[124:127]
	v_mfma_f32_16x16x32_bf16 v[120:123], v[150:153], v[158:161], v[120:123]
	v_mfma_f32_16x16x32_bf16 v[116:119], v[130:133], v[166:169], v[116:119]
	v_mfma_f32_16x16x32_bf16 v[112:115], v[150:153], v[166:169], v[112:115]
	v_mfma_f32_16x16x32_bf16 v[108:111], v[130:133], v[176:179], v[108:111]
	v_mfma_f32_16x16x32_bf16 v[104:107], v[150:153], v[176:179], v[104:107]
	v_mfma_f32_16x16x32_bf16 v[100:103], v[130:133], v[184:187], v[100:103]
	v_mfma_f32_16x16x32_bf16 v[96:99], v[150:153], v[184:187], v[96:99]
	v_mfma_f32_16x16x32_bf16 v[124:127], v[134:137], v[162:165], v[124:127]
	v_mfma_f32_16x16x32_bf16 v[120:123], v[154:157], v[162:165], v[120:123]
	v_mfma_f32_16x16x32_bf16 v[116:119], v[134:137], v[170:173], v[116:119]
	v_mfma_f32_16x16x32_bf16 v[112:115], v[154:157], v[170:173], v[112:115]
	v_mfma_f32_16x16x32_bf16 v[108:111], v[134:137], v[180:183], v[108:111]
	v_mfma_f32_16x16x32_bf16 v[104:107], v[154:157], v[180:183], v[104:107]
	v_mfma_f32_16x16x32_bf16 v[100:103], v[134:137], v[188:191], v[100:103]
	v_mfma_f32_16x16x32_bf16 v[96:99], v[154:157], v[188:191], v[96:99]
	s_barrier
	s_add_i32 s55, s51, s53
	s_mov_b32 m0, s19
	s_add_i32 s56, s55, 0x8000
	s_mov_b32 s6, s2
	s_mov_b32 s7, s3
	ds_read_b128 v[192:195], v146
	ds_read_b128 v[196:199], v146 offset:1024
	ds_read_b128 v[200:203], v146 offset:2048
	ds_read_b128 v[204:207], v146 offset:3072
	buffer_load_dwordx4 v138, s[4:7], s56 offen lds
	s_mov_b32 m0, s26
	s_add_i32 s56, s55, 0xa000
	buffer_load_dwordx4 v138, s[4:7], s56 offen lds
	s_waitcnt vmcnt(10)
	s_barrier
	s_waitcnt lgkmcnt(0)
	v_mfma_f32_16x16x32_bf16 v[92:95], v[192:195], v[158:161], v[92:95]
	v_mfma_f32_16x16x32_bf16 v[88:91], v[200:203], v[158:161], v[88:91]
	v_mfma_f32_16x16x32_bf16 v[84:87], v[192:195], v[166:169], v[84:87]
	v_mfma_f32_16x16x32_bf16 v[80:83], v[200:203], v[166:169], v[80:83]
	v_mfma_f32_16x16x32_bf16 v[76:79], v[192:195], v[176:179], v[76:79]
	v_mfma_f32_16x16x32_bf16 v[72:75], v[200:203], v[176:179], v[72:75]
	v_mfma_f32_16x16x32_bf16 v[68:71], v[192:195], v[184:187], v[68:71]
	v_mfma_f32_16x16x32_bf16 v[64:67], v[200:203], v[184:187], v[64:67]
	v_mfma_f32_16x16x32_bf16 v[92:95], v[196:199], v[162:165], v[92:95]
	v_mfma_f32_16x16x32_bf16 v[88:91], v[204:207], v[162:165], v[88:91]
	v_mfma_f32_16x16x32_bf16 v[84:87], v[196:199], v[170:173], v[84:87]
	v_mfma_f32_16x16x32_bf16 v[80:83], v[204:207], v[170:173], v[80:83]
	v_mfma_f32_16x16x32_bf16 v[76:79], v[196:199], v[180:183], v[76:79]
	v_mfma_f32_16x16x32_bf16 v[72:75], v[204:207], v[180:183], v[72:75]
	v_mfma_f32_16x16x32_bf16 v[68:71], v[196:199], v[188:191], v[68:71]
	v_mfma_f32_16x16x32_bf16 v[64:67], v[204:207], v[188:191], v[64:67]
	s_add_i32 s56, s50, s53
	s_mov_b32 m0, s27
	s_add_i32 s57, s56, 0x8000
	s_barrier
	ds_read_b128 v[158:161], v142 offset:16384
	ds_read_b128 v[162:165], v142 offset:17408
	ds_read_b128 v[166:169], v143 offset:16384
	ds_read_b128 v[170:173], v143 offset:17408
	ds_read_b128 v[176:179], v144 offset:16384
	ds_read_b128 v[180:183], v144 offset:17408
	ds_read_b128 v[184:187], v145 offset:16384
	ds_read_b128 v[188:191], v145 offset:17408
	buffer_load_dwordx4 v138, s[0:3], s57 offen lds
	s_mov_b32 m0, s28
	s_add_i32 s57, s56, 0xa000
	buffer_load_dwordx4 v138, s[0:3], s57 offen lds
	s_barrier
	s_waitcnt lgkmcnt(0)
	v_mfma_f32_16x16x32_bf16 v[60:63], v[130:133], v[158:161], v[60:63]
	v_mfma_f32_16x16x32_bf16 v[56:59], v[150:153], v[158:161], v[56:59]
	v_mfma_f32_16x16x32_bf16 v[52:55], v[130:133], v[166:169], v[52:55]
	v_mfma_f32_16x16x32_bf16 v[48:51], v[150:153], v[166:169], v[48:51]
	v_mfma_f32_16x16x32_bf16 v[44:47], v[130:133], v[176:179], v[44:47]
	v_mfma_f32_16x16x32_bf16 v[40:43], v[150:153], v[176:179], v[40:43]
	v_mfma_f32_16x16x32_bf16 v[36:39], v[130:133], v[184:187], v[36:39]
	v_mfma_f32_16x16x32_bf16 v[32:35], v[150:153], v[184:187], v[32:35]
	v_mfma_f32_16x16x32_bf16 v[60:63], v[134:137], v[162:165], v[60:63]
	v_mfma_f32_16x16x32_bf16 v[56:59], v[154:157], v[162:165], v[56:59]
	v_mfma_f32_16x16x32_bf16 v[52:55], v[134:137], v[170:173], v[52:55]
	v_mfma_f32_16x16x32_bf16 v[48:51], v[154:157], v[170:173], v[48:51]
	v_mfma_f32_16x16x32_bf16 v[44:47], v[134:137], v[180:183], v[44:47]
	v_mfma_f32_16x16x32_bf16 v[40:43], v[154:157], v[180:183], v[40:43]
	v_mfma_f32_16x16x32_bf16 v[36:39], v[134:137], v[188:191], v[36:39]
	v_mfma_f32_16x16x32_bf16 v[32:35], v[154:157], v[188:191], v[32:35]
	s_barrier
	s_add_i32 s57, s49, s53
	s_mov_b32 m0, s29
	s_add_i32 s58, s57, 0x8000
	buffer_load_dwordx4 v138, s[4:7], s58 offen lds
	s_mov_b32 m0, s30
	s_add_i32 s58, s57, 0xa000
	buffer_load_dwordx4 v138, s[4:7], s58 offen lds
	s_waitcnt vmcnt(10)
	s_barrier
; #define LDA(dst, b, h)                                                                                               \
;   _Pragma("unroll") for (int m = 0; m < 4; ++m) _Pragma("unroll") for (int k = 0; k < 2; ++k) dst[m][k] =            \
;       *reinterpret_cast<const bf16x8*>(SA(b, h) + lds_byte(wr * 64 + m * 16 + fr, k * 32 + fq * 8))
; #define LDB(dst, b, h)                                                                                               \
;   _Pragma("unroll") for (int n = 0; n < 2; ++n) _Pragma("unroll") for (int k = 0; k < 2; ++k) dst[n][k] =            \
;       *reinterpret_cast<const bf16x8*>(SB(b, h) + lds_byte(wc * 32 + n * 16 + fr, k * 32 + fq * 8))
; #define WAIT_V(n) asm volatile("s_waitcnt vmcnt(" #n ")" ::: "memory")
; #define WAIT_L(n) asm volatile("s_waitcnt lgkmcnt(" #n ")" ::: "memory")
; #define BAR __builtin_amdgcn_s_barrier()
; #define SCHED __builtin_amdgcn_sched_barrier(0)
; template <int EPI>
; __device__ __forceinline__ void gemm_phase(const u16* __restrict__ A, const u16* __restrict__ Bt, const int K,
;                                            const int nN, char* shm, const EpiArgs& ea) {
;     ...
;       WAIT_V(10); BAR; WAIT_L(0); MMA(0, 1, At, B1); BAR;
;       LDA(At, 0, 1); STAGE(SA(0, 0), rA, brow, t + 2);
;       BAR; WAIT_L(0); MMA(1, 0, At, B0); BAR; SCHED;
;       STAGE(SB(0, 1), rB, bcol + HALF, t + 2);
;       WAIT_V(10); BAR; MMA(1, 1, At, B1); BAR;
;       LDB(B0, 1, 0); SCHED; LDA(At, 1, 0); STAGE(SA(0, 1), rA, brow + HALF, t + 2);
;       WAIT_V(10); WAIT_L(8); BAR; WAIT_L(0); MMA(0, 0, At, B0); BAR; SCHED;
;       LDB(B1, 1, 1); STAGE(SB(1, 0), rB, bcol, t + 3);
;       WAIT_V(10); BAR; WAIT_L(0); MMA(0, 1, At, B1); BAR;
;       LDA(At, 1, 1); STAGE(SA(1, 0), rA, brow, t + 3);
;       BAR; WAIT_L(0); MMA(1, 0, At, B0); BAR; SCHED;
	v_mfma_f32_16x16x32_bf16 v[28:31], v[192:195], v[158:161], v[28:31]
	v_mfma_f32_16x16x32_bf16 v[24:27], v[200:203], v[158:161], v[24:27]
	v_mfma_f32_16x16x32_bf16 v[20:23], v[192:195], v[166:169], v[20:23]
	v_mfma_f32_16x16x32_bf16 v[16:19], v[200:203], v[166:169], v[16:19]
	v_mfma_f32_16x16x32_bf16 v[12:15], v[192:195], v[176:179], v[12:15]
	v_mfma_f32_16x16x32_bf16 v[8:11], v[200:203], v[176:179], v[8:11]
	v_mfma_f32_16x16x32_bf16 v[4:7], v[192:195], v[184:187], v[4:7]
	v_mfma_f32_16x16x32_bf16 v[0:3], v[200:203], v[184:187], v[0:3]
	v_mfma_f32_16x16x32_bf16 v[28:31], v[196:199], v[162:165], v[28:31]
	v_mfma_f32_16x16x32_bf16 v[24:27], v[204:207], v[162:165], v[24:27]
	v_mfma_f32_16x16x32_bf16 v[20:23], v[196:199], v[170:173], v[20:23]
	v_mfma_f32_16x16x32_bf16 v[16:19], v[204:207], v[170:173], v[16:19]
	v_mfma_f32_16x16x32_bf16 v[12:15], v[196:199], v[180:183], v[12:15]
	v_mfma_f32_16x16x32_bf16 v[8:11], v[204:207], v[180:183], v[8:11]
	v_mfma_f32_16x16x32_bf16 v[4:7], v[196:199], v[188:191], v[4:7]
	v_mfma_f32_16x16x32_bf16 v[0:3], v[204:207], v[188:191], v[0:3]
	s_barrier
	ds_read_b128 v[130:133], v147
	ds_read_b128 v[134:137], v147 offset:1024
	ds_read_b128 v[150:153], v147 offset:2048
	ds_read_b128 v[154:157], v147 offset:3072
	s_mov_b32 m0, s31
	s_add_i32 s58, s54, 0x8000
	ds_read_b128 v[158:161], v142 offset:32768
	ds_read_b128 v[162:165], v142 offset:33792
	ds_read_b128 v[166:169], v143 offset:32768
	ds_read_b128 v[170:173], v143 offset:33792
	ds_read_b128 v[176:179], v144 offset:32768
	ds_read_b128 v[180:183], v144 offset:33792
	ds_read_b128 v[184:187], v145 offset:32768
	ds_read_b128 v[188:191], v145 offset:33792
	buffer_load_dwordx4 v138, s[0:3], s58 offen lds
	s_mov_b32 m0, s34
	s_add_i32 s54, s54, 0xa000
	buffer_load_dwordx4 v138, s[0:3], s54 offen lds
	s_waitcnt vmcnt(10)
	s_waitcnt lgkmcnt(8)
	s_barrier
	s_waitcnt lgkmcnt(0)
	v_mfma_f32_16x16x32_bf16 v[124:127], v[130:133], v[158:161], v[124:127]
	v_mfma_f32_16x16x32_bf16 v[120:123], v[150:153], v[158:161], v[120:123]
	v_mfma_f32_16x16x32_bf16 v[116:119], v[130:133], v[166:169], v[116:119]
	v_mfma_f32_16x16x32_bf16 v[112:115], v[150:153], v[166:169], v[112:115]
	v_mfma_f32_16x16x32_bf16 v[108:111], v[130:133], v[176:179], v[108:111]
	v_mfma_f32_16x16x32_bf16 v[104:107], v[150:153], v[176:179], v[104:107]
	v_mfma_f32_16x16x32_bf16 v[100:103], v[130:133], v[184:187], v[100:103]
	v_mfma_f32_16x16x32_bf16 v[96:99], v[150:153], v[184:187], v[96:99]
	v_mfma_f32_16x16x32_bf16 v[124:127], v[134:137], v[162:165], v[124:127]
	v_mfma_f32_16x16x32_bf16 v[120:123], v[154:157], v[162:165], v[120:123]
	v_mfma_f32_16x16x32_bf16 v[116:119], v[134:137], v[170:173], v[116:119]
	v_mfma_f32_16x16x32_bf16 v[112:115], v[154:157], v[170:173], v[112:115]
	v_mfma_f32_16x16x32_bf16 v[108:111], v[134:137], v[180:183], v[108:111]
	v_mfma_f32_16x16x32_bf16 v[104:107], v[154:157], v[180:183], v[104:107]
	v_mfma_f32_16x16x32_bf16 v[100:103], v[134:137], v[188:191], v[100:103]
	v_mfma_f32_16x16x32_bf16 v[96:99], v[154:157], v[188:191], v[96:99]
	s_barrier
	s_mov_b32 m0, s35
	s_add_i32 s54, s55, 0xc000
	ds_read_b128 v[192:195], v148
	ds_read_b128 v[196:199], v148 offset:1024
	ds_read_b128 v[200:203], v148 offset:2048
	ds_read_b128 v[204:207], v148 offset:3072
	buffer_load_dwordx4 v138, s[4:7], s54 offen lds
	s_mov_b32 m0, s36
	s_add_i32 s55, s55, 0xe000
	buffer_load_dwordx4 v138, s[4:7], s55 offen lds
	s_waitcnt vmcnt(10)
	s_barrier
	s_waitcnt lgkmcnt(0)
	v_mfma_f32_16x16x32_bf16 v[92:95], v[192:195], v[158:161], v[92:95]
	v_mfma_f32_16x16x32_bf16 v[88:91], v[200:203], v[158:161], v[88:91]
	v_mfma_f32_16x16x32_bf16 v[84:87], v[192:195], v[166:169], v[84:87]
	v_mfma_f32_16x16x32_bf16 v[80:83], v[200:203], v[166:169], v[80:83]
	v_mfma_f32_16x16x32_bf16 v[76:79], v[192:195], v[176:179], v[76:79]
	v_mfma_f32_16x16x32_bf16 v[72:75], v[200:203], v[176:179], v[72:75]
	v_mfma_f32_16x16x32_bf16 v[68:71], v[192:195], v[184:187], v[68:71]
	v_mfma_f32_16x16x32_bf16 v[64:67], v[200:203], v[184:187], v[64:67]
	v_mfma_f32_16x16x32_bf16 v[92:95], v[196:199], v[162:165], v[92:95]
	v_mfma_f32_16x16x32_bf16 v[88:91], v[204:207], v[162:165], v[88:91]
	v_mfma_f32_16x16x32_bf16 v[84:87], v[196:199], v[170:173], v[84:87]
	v_mfma_f32_16x16x32_bf16 v[80:83], v[204:207], v[170:173], v[80:83]
	v_mfma_f32_16x16x32_bf16 v[76:79], v[196:199], v[180:183], v[76:79]
	v_mfma_f32_16x16x32_bf16 v[72:75], v[204:207], v[180:183], v[72:75]
	v_mfma_f32_16x16x32_bf16 v[68:71], v[196:199], v[188:191], v[68:71]
	v_mfma_f32_16x16x32_bf16 v[64:67], v[204:207], v[188:191], v[64:67]
	s_mov_b32 m0, s37
	s_add_i32 s54, s56, 0xc000
	s_barrier
	ds_read_b128 v[158:161], v142 offset:49152
	ds_read_b128 v[162:165], v142 offset:50176
	ds_read_b128 v[166:169], v143 offset:49152
	ds_read_b128 v[170:173], v143 offset:50176
	ds_read_b128 v[176:179], v144 offset:49152
	ds_read_b128 v[180:183], v144 offset:50176
	ds_read_b128 v[184:187], v145 offset:49152
	ds_read_b128 v[188:191], v145 offset:50176
	buffer_load_dwordx4 v138, s[0:3], s54 offen lds
	s_mov_b32 m0, s38
	s_add_i32 s56, s56, 0xe000
	buffer_load_dwordx4 v138, s[0:3], s56 offen lds
	s_barrier
; #define LDA(dst, b, h)                                                                                               \
;   _Pragma("unroll") for (int m = 0; m < 4; ++m) _Pragma("unroll") for (int k = 0; k < 2; ++k) dst[m][k] =            \
;       *reinterpret_cast<const bf16x8*>(SA(b, h) + lds_byte(wr * 64 + m * 16 + fr, k * 32 + fq * 8))
; #define LDB(dst, b, h)                                                                                               \
;   _Pragma("unroll") for (int n = 0; n < 2; ++n) _Pragma("unroll") for (int k = 0; k < 2; ++k) dst[n][k] =            \
;       *reinterpret_cast<const bf16x8*>(SB(b, h) + lds_byte(wc * 32 + n * 16 + fr, k * 32 + fq * 8))
; #define WAIT_V(n) asm volatile("s_waitcnt vmcnt(" #n ")" ::: "memory")
; #define WAIT_L(n) asm volatile("s_waitcnt lgkmcnt(" #n ")" ::: "memory")
; #define BAR __builtin_amdgcn_s_barrier()
; #define SCHED __builtin_amdgcn_sched_barrier(0)
; template <int EPI>
; __device__ __forceinline__ void gemm_phase(const u16* __restrict__ A, const u16* __restrict__ Bt, const int K,
;                                            const int nN, char* shm, const EpiArgs& ea) {
;     ...
;       WAIT_V(10); BAR; WAIT_L(0); MMA(0, 1, At, B1); BAR;
;       LDA(At, 1, 1); STAGE(SA(1, 0), rA, brow, t + 3);
;       BAR; WAIT_L(0); MMA(1, 0, At, B0); BAR; SCHED;
;       STAGE(SB(1, 1), rB, bcol + HALF, t + 3);
;       WAIT_V(10); BAR; MMA(1, 1, At, B1); BAR;
;     }
;     float eC = 0.f, eB = 0.f;
;     float2 eS = make_float2(0.f, 0.f);
;     if (EPI == EPI_IN || EPI == EPI_SWIGLU_LN) {
;       if (wr == 0) {
;         eC = ea.c1[bcol + tid];
;         eS = *(const float2*)(ea.st_in + (size_t)(brow + tid) * 2);
;       } else {
;         eC = ea.c2[bcol + tid - 256];
;         if (EPI == EPI_IN) eB = ea.bias[bcol + tid - 256];
;       }
;     }
;     {
;       LDB(B0, 0, 0); LDA(At, 0, 0); STAGE(SA(1, 1), rA, brow + HALF, nt - 1);
;       WAIT_V(10); BAR; WAIT_L(0); MMA(0, 0, At, B0); BAR;
;       LDB(B1, 0, 1); WAIT_V(8); BAR; WAIT_L(0); MMA(0, 1, At, B1); BAR;
;       LDA(At, 0, 1); WAIT_V(4); BAR; WAIT_L(0); MMA(1, 0, At, B0); MMA(1, 1, At, B1); BAR;
	s_waitcnt lgkmcnt(0)
	v_mfma_f32_16x16x32_bf16 v[60:63], v[130:133], v[158:161], v[60:63]
	v_mfma_f32_16x16x32_bf16 v[56:59], v[150:153], v[158:161], v[56:59]
	v_mfma_f32_16x16x32_bf16 v[52:55], v[130:133], v[166:169], v[52:55]
	v_mfma_f32_16x16x32_bf16 v[48:51], v[150:153], v[166:169], v[48:51]
	v_mfma_f32_16x16x32_bf16 v[44:47], v[130:133], v[176:179], v[44:47]
	v_mfma_f32_16x16x32_bf16 v[40:43], v[150:153], v[176:179], v[40:43]
	v_mfma_f32_16x16x32_bf16 v[36:39], v[130:133], v[184:187], v[36:39]
	v_mfma_f32_16x16x32_bf16 v[32:35], v[150:153], v[184:187], v[32:35]
	v_mfma_f32_16x16x32_bf16 v[60:63], v[134:137], v[162:165], v[60:63]
	v_mfma_f32_16x16x32_bf16 v[56:59], v[154:157], v[162:165], v[56:59]
	v_mfma_f32_16x16x32_bf16 v[52:55], v[134:137], v[170:173], v[52:55]
	v_mfma_f32_16x16x32_bf16 v[48:51], v[154:157], v[170:173], v[48:51]
	v_mfma_f32_16x16x32_bf16 v[44:47], v[134:137], v[180:183], v[44:47]
	v_mfma_f32_16x16x32_bf16 v[40:43], v[154:157], v[180:183], v[40:43]
	v_mfma_f32_16x16x32_bf16 v[36:39], v[134:137], v[188:191], v[36:39]
	v_mfma_f32_16x16x32_bf16 v[32:35], v[154:157], v[188:191], v[32:35]
	s_barrier
	s_mov_b32 m0, s39
	s_add_i32 s54, s57, 0xc000
	buffer_load_dwordx4 v138, s[4:7], s54 offen lds
	s_mov_b32 m0, s40
	s_add_i32 s57, s57, 0xe000
	buffer_load_dwordx4 v138, s[4:7], s57 offen lds
	s_waitcnt vmcnt(10)
	s_barrier
	v_mfma_f32_16x16x32_bf16 v[28:31], v[192:195], v[158:161], v[28:31]
	v_mfma_f32_16x16x32_bf16 v[24:27], v[200:203], v[158:161], v[24:27]
	v_mfma_f32_16x16x32_bf16 v[20:23], v[192:195], v[166:169], v[20:23]
	v_mfma_f32_16x16x32_bf16 v[16:19], v[200:203], v[166:169], v[16:19]
	v_mfma_f32_16x16x32_bf16 v[12:15], v[192:195], v[176:179], v[12:15]
	v_mfma_f32_16x16x32_bf16 v[8:11], v[200:203], v[176:179], v[8:11]
	v_mfma_f32_16x16x32_bf16 v[4:7], v[192:195], v[184:187], v[4:7]
	v_mfma_f32_16x16x32_bf16 v[0:3], v[200:203], v[184:187], v[0:3]
	v_mfma_f32_16x16x32_bf16 v[28:31], v[196:199], v[162:165], v[28:31]
	v_mfma_f32_16x16x32_bf16 v[24:27], v[204:207], v[162:165], v[24:27]
	v_mfma_f32_16x16x32_bf16 v[20:23], v[196:199], v[170:173], v[20:23]
	v_mfma_f32_16x16x32_bf16 v[16:19], v[204:207], v[170:173], v[16:19]
	v_mfma_f32_16x16x32_bf16 v[12:15], v[196:199], v[180:183], v[12:15]
	v_mfma_f32_16x16x32_bf16 v[8:11], v[204:207], v[180:183], v[8:11]
	v_mfma_f32_16x16x32_bf16 v[4:7], v[196:199], v[188:191], v[4:7]
	v_mfma_f32_16x16x32_bf16 v[0:3], v[204:207], v[188:191], v[0:3]
	s_add_i32 s52, s52, 2
	s_add_i32 s53, s53, 0x8000
	s_cmpk_lt_u32 s52, 0x54
	s_barrier
	s_cbranch_scc1 .LBB0_631
	s_mov_b32 m0, s41
	s_add_i32 s6, s48, 0x15c000
	ds_read_b128 v[130:133], v141
	ds_read_b128 v[134:137], v141 offset:1024
	ds_read_b128 v[150:153], v141 offset:2048
	ds_read_b128 v[154:157], v141 offset:3072
	ds_read_b128 v[158:161], v142
	ds_read_b128 v[162:165], v142 offset:1024
	ds_read_b128 v[166:169], v143
	ds_read_b128 v[170:173], v143 offset:1024
	ds_read_b128 v[176:179], v144
	ds_read_b128 v[180:183], v144 offset:1024
	ds_read_b128 v[184:187], v145
	ds_read_b128 v[188:191], v145 offset:1024
	buffer_load_dwordx4 v138, s[0:3], s6 offen lds
	s_mov_b32 m0, s42
	s_add_i32 s48, s48, 0x15e000
	buffer_load_dwordx4 v138, s[0:3], s48 offen lds
	s_waitcnt vmcnt(10)
	s_barrier
	s_waitcnt lgkmcnt(0)
	v_mfma_f32_16x16x32_bf16 v[124:127], v[130:133], v[158:161], v[124:127]
	v_mfma_f32_16x16x32_bf16 v[120:123], v[150:153], v[158:161], v[120:123]
	v_mfma_f32_16x16x32_bf16 v[116:119], v[130:133], v[166:169], v[116:119]
	v_mfma_f32_16x16x32_bf16 v[112:115], v[150:153], v[166:169], v[112:115]
	v_mfma_f32_16x16x32_bf16 v[100:103], v[130:133], v[184:187], v[100:103]
	v_mfma_f32_16x16x32_bf16 v[96:99], v[150:153], v[184:187], v[96:99]
	v_mfma_f32_16x16x32_bf16 v[124:127], v[134:137], v[162:165], v[124:127]
	v_mfma_f32_16x16x32_bf16 v[120:123], v[154:157], v[162:165], v[120:123]
	v_mfma_f32_16x16x32_bf16 v[116:119], v[134:137], v[170:173], v[116:119]
	v_mfma_f32_16x16x32_bf16 v[112:115], v[154:157], v[170:173], v[112:115]
	v_mfma_f32_16x16x32_bf16 v[108:111], v[130:133], v[176:179], v[108:111]
	v_mfma_f32_16x16x32_bf16 v[104:107], v[150:153], v[176:179], v[104:107]
	v_mfma_f32_16x16x32_bf16 v[100:103], v[134:137], v[188:191], v[100:103]
	v_mfma_f32_16x16x32_bf16 v[96:99], v[154:157], v[188:191], v[96:99]
	v_mfma_f32_16x16x32_bf16 v[192:195], v[134:137], v[180:183], v[108:111]
	v_mfma_f32_16x16x32_bf16 v[196:199], v[154:157], v[180:183], v[104:107]
	s_barrier
	s_nop 0
	ds_read_b128 v[104:107], v146
	ds_read_b128 v[108:111], v146 offset:1024
	ds_read_b128 v[200:203], v146 offset:2048
	ds_read_b128 v[204:207], v146 offset:3072
	s_waitcnt vmcnt(8)
	s_barrier
	s_waitcnt lgkmcnt(0)
	v_mfma_f32_16x16x32_bf16 v[84:87], v[104:107], v[166:169], v[84:87]
	v_mfma_f32_16x16x32_bf16 v[80:83], v[200:203], v[166:169], v[80:83]
	v_mfma_f32_16x16x32_bf16 v[68:71], v[104:107], v[184:187], v[68:71]
	v_mfma_f32_16x16x32_bf16 v[64:67], v[200:203], v[184:187], v[64:67]
	v_mfma_f32_16x16x32_bf16 v[92:95], v[104:107], v[158:161], v[92:95]
	v_mfma_f32_16x16x32_bf16 v[88:91], v[200:203], v[158:161], v[88:91]
	v_mfma_f32_16x16x32_bf16 v[84:87], v[108:111], v[170:173], v[84:87]
	v_mfma_f32_16x16x32_bf16 v[80:83], v[204:207], v[170:173], v[80:83]
	v_mfma_f32_16x16x32_bf16 v[76:79], v[104:107], v[176:179], v[76:79]
	v_mfma_f32_16x16x32_bf16 v[72:75], v[200:203], v[176:179], v[72:75]
	v_mfma_f32_16x16x32_bf16 v[68:71], v[108:111], v[188:191], v[68:71]
	v_mfma_f32_16x16x32_bf16 v[64:67], v[204:207], v[188:191], v[64:67]
	v_mfma_f32_16x16x32_bf16 v[208:211], v[108:111], v[162:165], v[92:95]
	v_mfma_f32_16x16x32_bf16 v[158:161], v[204:207], v[162:165], v[88:91]
	v_mfma_f32_16x16x32_bf16 v[162:165], v[108:111], v[180:183], v[76:79]
	v_mfma_f32_16x16x32_bf16 v[166:169], v[204:207], v[180:183], v[72:75]
	s_barrier
; #define LDA(dst, b, h)                                                                                               \
;   _Pragma("unroll") for (int m = 0; m < 4; ++m) _Pragma("unroll") for (int k = 0; k < 2; ++k) dst[m][k] =            \
;       *reinterpret_cast<const bf16x8*>(SA(b, h) + lds_byte(wr * 64 + m * 16 + fr, k * 32 + fq * 8))
; #define LDB(dst, b, h)                                                                                               \
;   _Pragma("unroll") for (int n = 0; n < 2; ++n) _Pragma("unroll") for (int k = 0; k < 2; ++k) dst[n][k] =            \
;       *reinterpret_cast<const bf16x8*>(SB(b, h) + lds_byte(wc * 32 + n * 16 + fr, k * 32 + fq * 8))
; #define WAIT_V(n) asm volatile("s_waitcnt vmcnt(" #n ")" ::: "memory")
; #define WAIT_L(n) asm volatile("s_waitcnt lgkmcnt(" #n ")" ::: "memory")
; #define BAR __builtin_amdgcn_s_barrier()
; template <int EPI>
; __device__ __forceinline__ void gemm_phase(const u16* __restrict__ A, const u16* __restrict__ Bt, const int K,
;                                            const int nN, char* shm, const EpiArgs& ea) {
;     ...
;       LDB(B0, 0, 0); LDA(At, 0, 0); STAGE(SA(1, 1), rA, brow + HALF, nt - 1);
;       WAIT_V(10); BAR; WAIT_L(0); MMA(0, 0, At, B0); BAR;
;       LDB(B1, 0, 1); WAIT_V(8); BAR; WAIT_L(0); MMA(0, 1, At, B1); BAR;
;       LDA(At, 0, 1); WAIT_V(4); BAR; WAIT_L(0); MMA(1, 0, At, B0); MMA(1, 1, At, B1); BAR;
;     }
;     {
;       LDB(B0, 1, 0); LDA(At, 1, 0); WAIT_V(2); BAR; WAIT_L(0); MMA(0, 0, At, B0); BAR;
;       LDB(B1, 1, 1); WAIT_V(0); BAR; WAIT_L(0); MMA(0, 1, At, B1); BAR;
;       LDA(At, 1, 1); BAR; WAIT_L(0); MMA(1, 0, At, B0); MMA(1, 1, At, B1); BAR;
	s_nop 0
	ds_read_b128 v[72:75], v142 offset:16384
	ds_read_b128 v[76:79], v142 offset:17408
	ds_read_b128 v[88:91], v143 offset:16384
	ds_read_b128 v[92:95], v143 offset:17408
	ds_read_b128 v[170:173], v144 offset:16384
	ds_read_b128 v[176:179], v144 offset:17408
	ds_read_b128 v[180:183], v145 offset:16384
	ds_read_b128 v[184:187], v145 offset:17408
	s_waitcnt vmcnt(4)
	s_barrier
	s_waitcnt lgkmcnt(0)
	v_mfma_f32_16x16x32_bf16 v[60:63], v[130:133], v[72:75], v[60:63]
	v_mfma_f32_16x16x32_bf16 v[56:59], v[150:153], v[72:75], v[56:59]
	v_mfma_f32_16x16x32_bf16 v[52:55], v[130:133], v[88:91], v[52:55]
	v_mfma_f32_16x16x32_bf16 v[48:51], v[150:153], v[88:91], v[48:51]
	v_mfma_f32_16x16x32_bf16 v[36:39], v[130:133], v[180:183], v[36:39]
	v_mfma_f32_16x16x32_bf16 v[32:35], v[150:153], v[180:183], v[32:35]
	v_mfma_f32_16x16x32_bf16 v[60:63], v[134:137], v[76:79], v[60:63]
	v_mfma_f32_16x16x32_bf16 v[56:59], v[154:157], v[76:79], v[56:59]
	v_mfma_f32_16x16x32_bf16 v[52:55], v[134:137], v[92:95], v[52:55]
	v_mfma_f32_16x16x32_bf16 v[48:51], v[154:157], v[92:95], v[48:51]
	v_mfma_f32_16x16x32_bf16 v[44:47], v[130:133], v[170:173], v[44:47]
	v_mfma_f32_16x16x32_bf16 v[40:43], v[150:153], v[170:173], v[40:43]
	v_mfma_f32_16x16x32_bf16 v[36:39], v[134:137], v[184:187], v[36:39]
	v_mfma_f32_16x16x32_bf16 v[32:35], v[154:157], v[184:187], v[32:35]
	v_mfma_f32_16x16x32_bf16 v[188:191], v[134:137], v[176:179], v[44:47]
	v_mfma_f32_16x16x32_bf16 v[212:215], v[154:157], v[176:179], v[40:43]
	v_mfma_f32_16x16x32_bf16 v[20:23], v[104:107], v[88:91], v[20:23]
	v_mfma_f32_16x16x32_bf16 v[16:19], v[200:203], v[88:91], v[16:19]
	v_mfma_f32_16x16x32_bf16 v[4:7], v[104:107], v[180:183], v[4:7]
	v_mfma_f32_16x16x32_bf16 v[0:3], v[200:203], v[180:183], v[0:3]
	v_mfma_f32_16x16x32_bf16 v[28:31], v[104:107], v[72:75], v[28:31]
	v_mfma_f32_16x16x32_bf16 v[24:27], v[200:203], v[72:75], v[24:27]
	v_mfma_f32_16x16x32_bf16 v[20:23], v[108:111], v[92:95], v[20:23]
	v_mfma_f32_16x16x32_bf16 v[16:19], v[204:207], v[92:95], v[16:19]
	v_mfma_f32_16x16x32_bf16 v[12:15], v[104:107], v[170:173], v[12:15]
	v_mfma_f32_16x16x32_bf16 v[8:11], v[200:203], v[170:173], v[8:11]
	v_mfma_f32_16x16x32_bf16 v[4:7], v[108:111], v[184:187], v[4:7]
	v_mfma_f32_16x16x32_bf16 v[0:3], v[204:207], v[184:187], v[0:3]
	v_mfma_f32_16x16x32_bf16 v[130:133], v[108:111], v[76:79], v[28:31]
	v_mfma_f32_16x16x32_bf16 v[134:137], v[204:207], v[76:79], v[24:27]
	v_mfma_f32_16x16x32_bf16 v[150:153], v[108:111], v[176:179], v[12:15]
	v_mfma_f32_16x16x32_bf16 v[154:157], v[204:207], v[176:179], v[8:11]
	s_barrier
	s_nop 0
	ds_read_b128 v[8:11], v147
	ds_read_b128 v[12:15], v147 offset:1024
	ds_read_b128 v[170:173], v147 offset:2048
	ds_read_b128 v[176:179], v147 offset:3072
	ds_read_b128 v[24:27], v142 offset:32768
	ds_read_b128 v[28:31], v142 offset:33792
	ds_read_b128 v[40:43], v143 offset:32768
	ds_read_b128 v[44:47], v143 offset:33792
	ds_read_b128 v[180:183], v144 offset:32768
	ds_read_b128 v[184:187], v144 offset:33792
	ds_read_b128 v[200:203], v145 offset:32768
	ds_read_b128 v[204:207], v145 offset:33792
	s_waitcnt vmcnt(2)
	s_barrier
	s_waitcnt lgkmcnt(0)
	v_mfma_f32_16x16x32_bf16 v[72:75], v[8:11], v[24:27], v[124:127]
	v_mfma_f32_16x16x32_bf16 v[124:127], v[12:15], v[28:31], v[72:75]
	v_mfma_f32_16x16x32_bf16 v[72:75], v[170:173], v[24:27], v[120:123]
	v_mfma_f32_16x16x32_bf16 v[120:123], v[176:179], v[28:31], v[72:75]
	v_mfma_f32_16x16x32_bf16 v[72:75], v[8:11], v[40:43], v[116:119]
	v_mfma_f32_16x16x32_bf16 v[108:111], v[12:15], v[44:47], v[72:75]
	v_mfma_f32_16x16x32_bf16 v[72:75], v[170:173], v[40:43], v[112:115]
	v_mfma_f32_16x16x32_bf16 v[104:107], v[176:179], v[44:47], v[72:75]
	v_mfma_f32_16x16x32_bf16 v[72:75], v[8:11], v[180:183], v[192:195]
	v_mfma_f32_16x16x32_bf16 v[92:95], v[12:15], v[184:187], v[72:75]
	v_mfma_f32_16x16x32_bf16 v[72:75], v[170:173], v[180:183], v[196:199]
	v_mfma_f32_16x16x32_bf16 v[88:91], v[176:179], v[184:187], v[72:75]
	v_mfma_f32_16x16x32_bf16 v[72:75], v[8:11], v[200:203], v[100:103]
	v_mfma_f32_16x16x32_bf16 v[76:79], v[12:15], v[204:207], v[72:75]
	v_mfma_f32_16x16x32_bf16 v[72:75], v[170:173], v[200:203], v[96:99]
	v_mfma_f32_16x16x32_bf16 v[72:75], v[176:179], v[204:207], v[72:75]
	s_barrier
	ds_read_b128 v[192:195], v148
	ds_read_b128 v[196:199], v148 offset:1024
	ds_read_b128 v[216:219], v148 offset:2048
	ds_read_b128 v[220:223], v148 offset:3072
	s_waitcnt vmcnt(0)
	s_barrier
; #define LDA(dst, b, h)                                                                                               \
;   _Pragma("unroll") for (int m = 0; m < 4; ++m) _Pragma("unroll") for (int k = 0; k < 2; ++k) dst[m][k] =            \
;       *reinterpret_cast<const bf16x8*>(SA(b, h) + lds_byte(wr * 64 + m * 16 + fr, k * 32 + fq * 8))
; #define LDB(dst, b, h)                                                                                               \
;   _Pragma("unroll") for (int n = 0; n < 2; ++n) _Pragma("unroll") for (int k = 0; k < 2; ++k) dst[n][k] =            \
;       *reinterpret_cast<const bf16x8*>(SB(b, h) + lds_byte(wc * 32 + n * 16 + fr, k * 32 + fq * 8))
; #define WAIT_V(n) asm volatile("s_waitcnt vmcnt(" #n ")" ::: "memory")
; #define WAIT_L(n) asm volatile("s_waitcnt lgkmcnt(" #n ")" ::: "memory")
; #define BAR __builtin_amdgcn_s_barrier()
; template <int EPI>
; __device__ __forceinline__ void gemm_phase(const u16* __restrict__ A, const u16* __restrict__ Bt, const int K,
;                                            const int nN, char* shm, const EpiArgs& ea) {
;     ...
;       LDB(B0, 1, 0); LDA(At, 1, 0); WAIT_V(2); BAR; WAIT_L(0); MMA(0, 0, At, B0); BAR;
;       LDB(B1, 1, 1); WAIT_V(0); BAR; WAIT_L(0); MMA(0, 1, At, B1); BAR;
;       LDA(At, 1, 1); BAR; WAIT_L(0); MMA(1, 0, At, B0); MMA(1, 1, At, B1); BAR;
;     }
;     if (wr == 0) BAR;
;     if (has_next) STAGE7(brow2, bcol2);
	s_waitcnt lgkmcnt(0)
	v_mfma_f32_16x16x32_bf16 v[96:99], v[192:195], v[24:27], v[208:211]
	v_mfma_f32_16x16x32_bf16 v[24:27], v[216:219], v[24:27], v[158:161]
	v_mfma_f32_16x16x32_bf16 v[112:115], v[220:223], v[28:31], v[24:27]
	v_mfma_f32_16x16x32_bf16 v[24:27], v[192:195], v[40:43], v[84:87]
	v_mfma_f32_16x16x32_bf16 v[100:103], v[196:199], v[44:47], v[24:27]
	v_mfma_f32_16x16x32_bf16 v[24:27], v[216:219], v[40:43], v[80:83]
	v_mfma_f32_16x16x32_bf16 v[116:119], v[196:199], v[28:31], v[96:99]
	v_mfma_f32_16x16x32_bf16 v[96:99], v[220:223], v[44:47], v[24:27]
	v_mfma_f32_16x16x32_bf16 v[24:27], v[192:195], v[180:183], v[162:165]
	v_mfma_f32_16x16x32_bf16 v[84:87], v[196:199], v[184:187], v[24:27]
	v_mfma_f32_16x16x32_bf16 v[24:27], v[216:219], v[180:183], v[166:169]
	v_mfma_f32_16x16x32_bf16 v[80:83], v[220:223], v[184:187], v[24:27]
	v_mfma_f32_16x16x32_bf16 v[24:27], v[192:195], v[200:203], v[68:71]
	v_mfma_f32_16x16x32_bf16 v[68:71], v[196:199], v[204:207], v[24:27]
	v_mfma_f32_16x16x32_bf16 v[24:27], v[216:219], v[200:203], v[64:67]
	v_mfma_f32_16x16x32_bf16 v[64:67], v[220:223], v[204:207], v[24:27]
	s_barrier
	ds_read_b128 v[158:161], v142 offset:49152
	ds_read_b128 v[162:165], v142 offset:50176
	ds_read_b128 v[166:169], v143 offset:49152
	ds_read_b128 v[180:183], v143 offset:50176
	ds_read_b128 v[184:187], v144 offset:49152
	ds_read_b128 v[200:203], v144 offset:50176
	ds_read_b128 v[204:207], v145 offset:49152
	ds_read_b128 v[208:211], v145 offset:50176
	s_barrier
	s_waitcnt lgkmcnt(0)
	v_mfma_f32_16x16x32_bf16 v[24:27], v[8:11], v[158:161], v[60:63]
	v_mfma_f32_16x16x32_bf16 v[60:63], v[12:15], v[162:165], v[24:27]
	v_mfma_f32_16x16x32_bf16 v[24:27], v[170:173], v[158:161], v[56:59]
	v_mfma_f32_16x16x32_bf16 v[56:59], v[176:179], v[162:165], v[24:27]
	v_mfma_f32_16x16x32_bf16 v[24:27], v[8:11], v[166:169], v[52:55]
	v_mfma_f32_16x16x32_bf16 v[44:47], v[12:15], v[180:183], v[24:27]
	v_mfma_f32_16x16x32_bf16 v[24:27], v[170:173], v[166:169], v[48:51]
	v_mfma_f32_16x16x32_bf16 v[40:43], v[176:179], v[180:183], v[24:27]
	v_mfma_f32_16x16x32_bf16 v[24:27], v[8:11], v[184:187], v[188:191]
	v_mfma_f32_16x16x32_bf16 v[8:11], v[8:11], v[204:207], v[36:39]
	v_mfma_f32_16x16x32_bf16 v[28:31], v[12:15], v[200:203], v[24:27]
	v_mfma_f32_16x16x32_bf16 v[24:27], v[170:173], v[184:187], v[212:215]
	v_mfma_f32_16x16x32_bf16 v[12:15], v[12:15], v[208:211], v[8:11]
	v_mfma_f32_16x16x32_bf16 v[8:11], v[170:173], v[204:207], v[32:35]
	v_mfma_f32_16x16x32_bf16 v[24:27], v[176:179], v[200:203], v[24:27]
	v_mfma_f32_16x16x32_bf16 v[8:11], v[176:179], v[208:211], v[8:11]
	v_mfma_f32_16x16x32_bf16 v[32:35], v[192:195], v[158:161], v[130:133]
	v_mfma_f32_16x16x32_bf16 v[52:55], v[196:199], v[162:165], v[32:35]
	v_mfma_f32_16x16x32_bf16 v[32:35], v[216:219], v[158:161], v[134:137]
	v_mfma_f32_16x16x32_bf16 v[16:19], v[216:219], v[166:169], v[16:19]
	v_mfma_f32_16x16x32_bf16 v[48:51], v[220:223], v[162:165], v[32:35]
	v_mfma_f32_16x16x32_bf16 v[20:23], v[192:195], v[166:169], v[20:23]
	v_mfma_f32_16x16x32_bf16 v[32:35], v[220:223], v[180:183], v[16:19]
	v_mfma_f32_16x16x32_bf16 v[16:19], v[192:195], v[184:187], v[150:153]
	v_mfma_f32_16x16x32_bf16 v[36:39], v[196:199], v[180:183], v[20:23]
	v_mfma_f32_16x16x32_bf16 v[20:23], v[196:199], v[200:203], v[16:19]
	v_mfma_f32_16x16x32_bf16 v[16:19], v[216:219], v[184:187], v[154:157]
	v_mfma_f32_16x16x32_bf16 v[4:7], v[192:195], v[204:207], v[4:7]
	v_mfma_f32_16x16x32_bf16 v[0:3], v[216:219], v[204:207], v[0:3]
	v_mfma_f32_16x16x32_bf16 v[16:19], v[220:223], v[200:203], v[16:19]
	v_mfma_f32_16x16x32_bf16 v[4:7], v[196:199], v[208:211], v[4:7]
	v_mfma_f32_16x16x32_bf16 v[0:3], v[220:223], v[208:211], v[0:3]
	s_andn2_b64 vcc, exec, s[14:15]
	s_barrier
	s_cbranch_vccnz .LBB0_634
	s_barrier
.LBB0_634:
	s_andn2_b64 vcc, exec, s[24:25]
	s_cbranch_vccnz .LBB0_625
	s_lshr_b32 s6, s45, 7
	s_mov_b32 m0, s19
	s_mul_i32 s24, s6, 0x164000
	s_mov_b32 s6, s2
	s_mov_b32 s7, s3
	buffer_load_dwordx4 v138, s[4:7], s24 offen lds
	s_mov_b32 m0, s26
	s_or_b32 s25, s24, 0x2000
	buffer_load_dwordx4 v138, s[4:7], s25 offen lds
	s_lshr_b32 s25, s46, 7
	s_mul_i32 s25, s25, 0x164000
	s_mov_b32 m0, s27
	s_or_b32 s48, s25, 0x2000
	buffer_load_dwordx4 v138, s[0:3], s25 offen lds
	s_mov_b32 m0, s28
	s_nop 0
	buffer_load_dwordx4 v138, s[0:3], s48 offen lds
	s_mov_b32 m0, s29
	s_add_i32 s48, s24, 0x164000
	buffer_load_dwordx4 v138, s[4:7], s48 offen lds
	s_mov_b32 m0, s30
	s_add_i32 s48, s24, 0x166000
	buffer_load_dwordx4 v138, s[4:7], s48 offen lds
	s_mov_b32 m0, s31
	s_add_i32 s48, s25, 0x164000
	buffer_load_dwordx4 v138, s[0:3], s48 offen lds
	s_mov_b32 m0, s34
	s_add_i32 s48, s25, 0x166000
	buffer_load_dwordx4 v138, s[0:3], s48 offen lds
	s_mov_b32 m0, s35
	s_or_b32 s48, s24, 0x4000
	buffer_load_dwordx4 v138, s[4:7], s48 offen lds
	s_mov_b32 m0, s36
	s_or_b32 s48, s24, 0x6000
	buffer_load_dwordx4 v138, s[4:7], s48 offen lds
	s_or_b32 s48, s25, 0x4000
	s_mov_b32 m0, s37
	s_or_b32 s25, s25, 0x6000
	buffer_load_dwordx4 v138, s[0:3], s48 offen lds
	s_mov_b32 m0, s38
	s_nop 0
	buffer_load_dwordx4 v138, s[0:3], s25 offen lds
	s_add_i32 s25, s24, 0x168000
	s_mov_b32 m0, s39
	s_add_i32 s24, s24, 0x16a000
	buffer_load_dwordx4 v138, s[4:7], s25 offen lds
	s_mov_b32 m0, s40
	s_nop 0
	buffer_load_dwordx4 v138, s[4:7], s24 offen lds
	s_branch .LBB0_625
